# K-loop 6-piece load segments: LDS-DMA pieces use scalar-base or immediate-offset addressing (64-bit address VALU removed), ds_reads interleaved as m0 separators
# baseline (speedup 1.0000x reference)
.LBB0_322:
	s_ashr_i32 s43, s42, 31
	s_lshl_b64 s[46:47], s[42:43], 19
	s_add_u32 s46, s12, s46
	s_addc_u32 s47, s13, s47
	s_and_b64 s[48:49], s[4:5], exec
	s_cselect_b32 s18, s47, s7
	s_cselect_b32 s43, s46, s6
	s_ashr_i32 s45, s44, 31
	s_lshl_b64 s[48:49], s[44:45], 19
	s_add_u32 s48, s59, s48
	s_addc_u32 s49, s60, s49
	s_and_b64 s[50:51], s[4:5], exec
	s_cselect_b32 s45, s49, s9
	s_cselect_b32 s55, s48, s8
	s_add_u32 s6, s6, 0x40080
	s_addc_u32 s7, s7, 0
	s_add_u32 s56, s8, 0x100
	s_addc_u32 s57, s9, 0
	s_mov_b32 s78, -2
	ds_read_b128 v[96:99], v209
	ds_read_b128 v[100:103], v209 offset:1024
	ds_read_b128 v[120:123], v209 offset:2048
	ds_read_b128 v[124:127], v209 offset:3072
	ds_read_b128 v[144:147], v210
	ds_read_b128 v[148:151], v210 offset:1024
	ds_read_b128 v[152:155], v210 offset:2048
	ds_read_b128 v[156:159], v210 offset:3072
	s_add_u32 s8, s6, 0xfffc0080
	s_addc_u32 s9, s7, -1
	s_cmp_eq_u32 s78, 12
	s_cselect_b32 s51, s18, s9
	s_cselect_b32 s50, s43, s8
	s_cselect_b32 s9, s45, s57
	s_cselect_b32 s8, s55, s56
	v_lshl_add_u64 v[206:207], s[6:7], 0, v[170:171]
	s_add_i32 m0, s17, 0xc000
	ds_read_b128 v[178:181], v211
	ds_read_b128 v[182:185], v211 offset:1024
	ds_read_b128 v[186:189], v211 offset:2048
	ds_read_b128 v[190:193], v211 offset:3072
	ds_read_b128 v[194:197], v211 offset:4096
	ds_read_b128 v[198:201], v211 offset:5120
	ds_read_b128 v[202:205], v211 offset:6144
	ds_read_b128 v[218:221], v211 offset:7168
	global_load_lds_dwordx4 v[206:207], off
	s_add_i32 m0, s17, 0xe000
	v_lshl_add_u64 v[206:207], s[6:7], 0, v[172:173]
	global_load_lds_dwordx4 v[206:207], off
	s_waitcnt vmcnt(8)
	s_waitcnt lgkmcnt(0)
	s_barrier
	s_setprio 1
	s_waitcnt lgkmcnt(0)
	v_mfma_f32_16x16x32_bf16 v[140:143], v[96:99], v[178:181], 0
	v_mfma_f32_16x16x32_bf16 v[136:139], v[120:123], v[178:181], 0
	v_mfma_f32_16x16x32_bf16 v[116:119], v[96:99], v[186:189], 0
	v_mfma_f32_16x16x32_bf16 v[112:115], v[120:123], v[186:189], 0
	v_mfma_f32_16x16x32_bf16 v[92:95], v[96:99], v[194:197], 0
	v_mfma_f32_16x16x32_bf16 v[88:91], v[120:123], v[194:197], 0
	v_mfma_f32_16x16x32_bf16 v[76:79], v[96:99], v[202:205], 0
	v_mfma_f32_16x16x32_bf16 v[72:75], v[120:123], v[202:205], 0
	v_mfma_f32_16x16x32_bf16 v[140:143], v[100:103], v[182:185], v[140:143]
	v_mfma_f32_16x16x32_bf16 v[136:139], v[124:127], v[182:185], v[136:139]
	v_mfma_f32_16x16x32_bf16 v[116:119], v[100:103], v[190:193], v[116:119]
	v_mfma_f32_16x16x32_bf16 v[112:115], v[124:127], v[190:193], v[112:115]
	v_mfma_f32_16x16x32_bf16 v[92:95], v[100:103], v[198:201], v[92:95]
	v_mfma_f32_16x16x32_bf16 v[88:91], v[124:127], v[198:201], v[88:91]
	v_mfma_f32_16x16x32_bf16 v[76:79], v[100:103], v[218:221], v[76:79]
	v_mfma_f32_16x16x32_bf16 v[72:75], v[124:127], v[218:221], v[72:75]
	s_setprio 0
	s_setprio 1
	v_mfma_f32_16x16x32_bf16 v[132:135], v[144:147], v[178:181], 0
	v_mfma_f32_16x16x32_bf16 v[128:131], v[152:155], v[178:181], 0
	v_mfma_f32_16x16x32_bf16 v[108:111], v[144:147], v[186:189], 0
	v_mfma_f32_16x16x32_bf16 v[104:107], v[152:155], v[186:189], 0
	v_mfma_f32_16x16x32_bf16 v[84:87], v[144:147], v[194:197], 0
	v_mfma_f32_16x16x32_bf16 v[80:83], v[152:155], v[194:197], 0
	v_mfma_f32_16x16x32_bf16 v[68:71], v[144:147], v[202:205], 0
	v_mfma_f32_16x16x32_bf16 v[64:67], v[152:155], v[202:205], 0
	v_mfma_f32_16x16x32_bf16 v[132:135], v[148:151], v[182:185], v[132:135]
	v_mfma_f32_16x16x32_bf16 v[128:131], v[156:159], v[182:185], v[128:131]
	v_mfma_f32_16x16x32_bf16 v[108:111], v[148:151], v[190:193], v[108:111]
	v_mfma_f32_16x16x32_bf16 v[104:107], v[156:159], v[190:193], v[104:107]
	s_setprio 2
	s_barrier
	v_mfma_f32_16x16x32_bf16 v[84:87], v[148:151], v[198:201], v[84:87]
	v_mfma_f32_16x16x32_bf16 v[80:83], v[156:159], v[198:201], v[80:83]
	v_mfma_f32_16x16x32_bf16 v[68:71], v[148:151], v[218:221], v[68:71]
	v_mfma_f32_16x16x32_bf16 v[64:67], v[156:159], v[218:221], v[64:67]
	s_setprio 0
	s_add_i32 s79, s73, s61
	v_lshl_add_u64 v[206:207], s[8:9], 0, v[162:163]
	s_mov_b32 m0, s79
	ds_read_b128 v[178:181], v211 offset:16384
	ds_read_b128 v[182:185], v211 offset:17408
	ds_read_b128 v[186:189], v211 offset:18432
	ds_read_b128 v[190:193], v211 offset:19456
	ds_read_b128 v[194:197], v211 offset:20480
	ds_read_b128 v[198:201], v211 offset:21504
	global_load_lds_dwordx4 v[206:207], off
	s_add_i32 m0, s79, 0x2000
	s_add_u32 s80, s8, 0x40000
	v_lshl_add_u64 v[222:223], s[8:9], 0, v[166:167]
	s_addc_u32 s81, s9, 0
	s_add_i32 s79, s74, s61
	global_load_lds_dwordx4 v[222:223], off
	s_mov_b32 m0, s79
	v_lshl_add_u64 v[226:227], s[50:51], 0, v[164:165]
	global_load_lds_dwordx4 v162, s[80:81]
	s_add_i32 m0, s79, 0x2000
	ds_read_b128 v[202:205], v211 offset:22528
	global_load_lds_dwordx4 v166, s[80:81]
	s_mov_b32 m0, s17
	v_lshl_add_u64 v[224:225], s[50:51], 0, v[160:161]
	global_load_lds_dwordx4 v[224:225], off
	s_mov_b32 m0, s62
	ds_read_b128 v[218:221], v211 offset:23552
	global_load_lds_dwordx4 v[226:227], off
	s_waitcnt vmcnt(8)
	s_waitcnt lgkmcnt(0)
	s_barrier
	s_setprio 1
	s_waitcnt lgkmcnt(0)
	v_mfma_f32_16x16x32_bf16 v[60:63], v[96:99], v[178:181], 0
	v_mfma_f32_16x16x32_bf16 v[56:59], v[120:123], v[178:181], 0
	v_mfma_f32_16x16x32_bf16 v[44:47], v[96:99], v[186:189], 0
	v_mfma_f32_16x16x32_bf16 v[40:43], v[120:123], v[186:189], 0
	v_mfma_f32_16x16x32_bf16 v[28:31], v[96:99], v[194:197], 0
	v_mfma_f32_16x16x32_bf16 v[24:27], v[120:123], v[194:197], 0
	v_mfma_f32_16x16x32_bf16 v[12:15], v[96:99], v[202:205], 0
	v_mfma_f32_16x16x32_bf16 v[8:11], v[120:123], v[202:205], 0
	v_mfma_f32_16x16x32_bf16 v[60:63], v[100:103], v[182:185], v[60:63]
	v_mfma_f32_16x16x32_bf16 v[56:59], v[124:127], v[182:185], v[56:59]
	v_mfma_f32_16x16x32_bf16 v[44:47], v[100:103], v[190:193], v[44:47]
	v_mfma_f32_16x16x32_bf16 v[40:43], v[124:127], v[190:193], v[40:43]
	v_mfma_f32_16x16x32_bf16 v[28:31], v[100:103], v[198:201], v[28:31]
	v_mfma_f32_16x16x32_bf16 v[24:27], v[124:127], v[198:201], v[24:27]
	v_mfma_f32_16x16x32_bf16 v[12:15], v[100:103], v[218:221], v[12:15]
	v_mfma_f32_16x16x32_bf16 v[8:11], v[124:127], v[218:221], v[8:11]
	s_setprio 0
	s_setprio 1
	v_mfma_f32_16x16x32_bf16 v[52:55], v[144:147], v[178:181], 0
	v_mfma_f32_16x16x32_bf16 v[48:51], v[152:155], v[178:181], 0
	v_mfma_f32_16x16x32_bf16 v[36:39], v[144:147], v[186:189], 0
	v_mfma_f32_16x16x32_bf16 v[32:35], v[152:155], v[186:189], 0
	v_mfma_f32_16x16x32_bf16 v[20:23], v[144:147], v[194:197], 0
	v_mfma_f32_16x16x32_bf16 v[16:19], v[152:155], v[194:197], 0
	v_mfma_f32_16x16x32_bf16 v[4:7], v[144:147], v[202:205], 0
	v_mfma_f32_16x16x32_bf16 v[0:3], v[152:155], v[202:205], 0
	v_mfma_f32_16x16x32_bf16 v[52:55], v[148:151], v[182:185], v[52:55]
	v_mfma_f32_16x16x32_bf16 v[48:51], v[156:159], v[182:185], v[48:51]
	v_mfma_f32_16x16x32_bf16 v[36:39], v[148:151], v[190:193], v[36:39]
	v_mfma_f32_16x16x32_bf16 v[32:35], v[156:159], v[190:193], v[32:35]
	s_setprio 2
	s_barrier
	v_mfma_f32_16x16x32_bf16 v[20:23], v[148:151], v[198:201], v[20:23]
	v_mfma_f32_16x16x32_bf16 v[16:19], v[156:159], v[198:201], v[16:19]
	v_mfma_f32_16x16x32_bf16 v[4:7], v[148:151], v[218:221], v[4:7]
	v_mfma_f32_16x16x32_bf16 v[0:3], v[156:159], v[218:221], v[0:3]
	s_setprio 0
	s_add_i32 s79, 0, 0x18000
	s_add_i32 s80, 0, 0x1c000
	v_add_u32_e32 v124, s79, v208
	v_add_u32_e32 v156, s80, v208
	ds_read_b128 v[96:99], v124
	ds_read_b128 v[100:103], v124 offset:1024
	ds_read_b128 v[120:123], v124 offset:2048
	ds_read_b128 v[124:127], v124 offset:3072
	ds_read_b128 v[144:147], v156
	ds_read_b128 v[148:151], v156 offset:1024
	ds_read_b128 v[152:155], v156 offset:2048
	ds_read_b128 v[156:159], v156 offset:3072
	s_add_u32 s50, s50, 0x40000
	s_addc_u32 s51, s51, 0
	s_mov_b32 m0, s63
	v_lshl_add_u64 v[228:229], s[50:51], 0, v[160:161]
	ds_read_b128 v[178:181], v211 offset:32768
	ds_read_b128 v[182:185], v211 offset:33792
	ds_read_b128 v[186:189], v211 offset:34816
	ds_read_b128 v[190:193], v211 offset:35840
	ds_read_b128 v[194:197], v211 offset:36864
	ds_read_b128 v[198:201], v211 offset:37888
	ds_read_b128 v[202:205], v211 offset:38912
	ds_read_b128 v[218:221], v211 offset:39936
	global_load_lds_dwordx4 v[228:229], off
	s_mov_b32 m0, s64
	v_lshl_add_u64 v[228:229], s[50:51], 0, v[164:165]
	global_load_lds_dwordx4 v[228:229], off
	s_waitcnt vmcnt(8)
	s_waitcnt lgkmcnt(0)
	s_barrier
	s_setprio 1
	s_waitcnt lgkmcnt(0)
	v_mfma_f32_16x16x32_bf16 v[140:143], v[96:99], v[178:181], v[140:143]
	v_mfma_f32_16x16x32_bf16 v[136:139], v[120:123], v[178:181], v[136:139]
	v_mfma_f32_16x16x32_bf16 v[116:119], v[96:99], v[186:189], v[116:119]
	v_mfma_f32_16x16x32_bf16 v[112:115], v[120:123], v[186:189], v[112:115]
	v_mfma_f32_16x16x32_bf16 v[92:95], v[96:99], v[194:197], v[92:95]
	v_mfma_f32_16x16x32_bf16 v[88:91], v[120:123], v[194:197], v[88:91]
	v_mfma_f32_16x16x32_bf16 v[76:79], v[96:99], v[202:205], v[76:79]
	v_mfma_f32_16x16x32_bf16 v[72:75], v[120:123], v[202:205], v[72:75]
	v_mfma_f32_16x16x32_bf16 v[140:143], v[100:103], v[182:185], v[140:143]
	v_mfma_f32_16x16x32_bf16 v[136:139], v[124:127], v[182:185], v[136:139]
	v_mfma_f32_16x16x32_bf16 v[116:119], v[100:103], v[190:193], v[116:119]
	v_mfma_f32_16x16x32_bf16 v[112:115], v[124:127], v[190:193], v[112:115]
	v_mfma_f32_16x16x32_bf16 v[92:95], v[100:103], v[198:201], v[92:95]
	v_mfma_f32_16x16x32_bf16 v[88:91], v[124:127], v[198:201], v[88:91]
	v_mfma_f32_16x16x32_bf16 v[76:79], v[100:103], v[218:221], v[76:79]
	v_mfma_f32_16x16x32_bf16 v[72:75], v[124:127], v[218:221], v[72:75]
	s_setprio 0
	s_setprio 1
	v_mfma_f32_16x16x32_bf16 v[132:135], v[144:147], v[178:181], v[132:135]
	v_mfma_f32_16x16x32_bf16 v[128:131], v[152:155], v[178:181], v[128:131]
	v_mfma_f32_16x16x32_bf16 v[108:111], v[144:147], v[186:189], v[108:111]
	v_mfma_f32_16x16x32_bf16 v[104:107], v[152:155], v[186:189], v[104:107]
	v_mfma_f32_16x16x32_bf16 v[84:87], v[144:147], v[194:197], v[84:87]
	v_mfma_f32_16x16x32_bf16 v[80:83], v[152:155], v[194:197], v[80:83]
	v_mfma_f32_16x16x32_bf16 v[68:71], v[144:147], v[202:205], v[68:71]
	v_mfma_f32_16x16x32_bf16 v[64:67], v[152:155], v[202:205], v[64:67]
	v_mfma_f32_16x16x32_bf16 v[132:135], v[148:151], v[182:185], v[132:135]
	v_mfma_f32_16x16x32_bf16 v[128:131], v[156:159], v[182:185], v[128:131]
	v_mfma_f32_16x16x32_bf16 v[108:111], v[148:151], v[190:193], v[108:111]
	v_mfma_f32_16x16x32_bf16 v[104:107], v[156:159], v[190:193], v[104:107]
	s_setprio 2
	s_barrier
	v_mfma_f32_16x16x32_bf16 v[84:87], v[148:151], v[198:201], v[84:87]
	v_mfma_f32_16x16x32_bf16 v[80:83], v[156:159], v[198:201], v[80:83]
	v_mfma_f32_16x16x32_bf16 v[68:71], v[148:151], v[218:221], v[68:71]
	v_mfma_f32_16x16x32_bf16 v[64:67], v[156:159], v[218:221], v[64:67]
	s_setprio 0
	s_add_i32 s50, s79, s61
	s_add_i32 m0, s50, 0xffffff80
	ds_read_b128 v[178:181], v211 offset:49152
	ds_read_b128 v[182:185], v211 offset:50176
	ds_read_b128 v[186:189], v211 offset:51200
	ds_read_b128 v[190:193], v211 offset:52224
	global_load_lds_dwordx4 v[206:207], off offset:128
	s_add_i32 m0, s50, 0x1f80
	s_add_u32 s8, s8, 0x40080
	s_addc_u32 s9, s9, 0
	s_add_i32 s50, s80, s61
	global_load_lds_dwordx4 v[222:223], off offset:128
	s_mov_b32 m0, s50
	ds_read_b128 v[194:197], v211 offset:53248
	global_load_lds_dwordx4 v162, s[8:9]
	s_add_i32 m0, s50, 0x2000
	ds_read_b128 v[198:201], v211 offset:54272
	global_load_lds_dwordx4 v166, s[8:9]
	s_add_i32 m0, s68, 0xffffff80
	ds_read_b128 v[202:205], v211 offset:55296
	global_load_lds_dwordx4 v[224:225], off offset:128
	s_add_i32 m0, s69, 0xffffff80
	ds_read_b128 v[218:221], v211 offset:56320
	global_load_lds_dwordx4 v[226:227], off offset:128
	s_waitcnt vmcnt(8)
	s_waitcnt lgkmcnt(0)
	s_barrier
	s_setprio 1
	s_waitcnt lgkmcnt(0)
	v_mfma_f32_16x16x32_bf16 v[60:63], v[96:99], v[178:181], v[60:63]
	v_mfma_f32_16x16x32_bf16 v[56:59], v[120:123], v[178:181], v[56:59]
	v_mfma_f32_16x16x32_bf16 v[44:47], v[96:99], v[186:189], v[44:47]
	v_mfma_f32_16x16x32_bf16 v[40:43], v[120:123], v[186:189], v[40:43]
	v_mfma_f32_16x16x32_bf16 v[28:31], v[96:99], v[194:197], v[28:31]
	v_mfma_f32_16x16x32_bf16 v[24:27], v[120:123], v[194:197], v[24:27]
	v_mfma_f32_16x16x32_bf16 v[12:15], v[96:99], v[202:205], v[12:15]
	v_mfma_f32_16x16x32_bf16 v[8:11], v[120:123], v[202:205], v[8:11]
	v_mfma_f32_16x16x32_bf16 v[60:63], v[100:103], v[182:185], v[60:63]
	v_mfma_f32_16x16x32_bf16 v[56:59], v[124:127], v[182:185], v[56:59]
	v_mfma_f32_16x16x32_bf16 v[44:47], v[100:103], v[190:193], v[44:47]
	v_mfma_f32_16x16x32_bf16 v[40:43], v[124:127], v[190:193], v[40:43]
	v_mfma_f32_16x16x32_bf16 v[28:31], v[100:103], v[198:201], v[28:31]
	v_mfma_f32_16x16x32_bf16 v[24:27], v[124:127], v[198:201], v[24:27]
	v_mfma_f32_16x16x32_bf16 v[12:15], v[100:103], v[218:221], v[12:15]
	v_mfma_f32_16x16x32_bf16 v[8:11], v[124:127], v[218:221], v[8:11]
	s_setprio 0
	s_setprio 1
	v_mfma_f32_16x16x32_bf16 v[52:55], v[144:147], v[178:181], v[52:55]
	v_mfma_f32_16x16x32_bf16 v[48:51], v[152:155], v[178:181], v[48:51]
	v_mfma_f32_16x16x32_bf16 v[36:39], v[144:147], v[186:189], v[36:39]
	v_mfma_f32_16x16x32_bf16 v[32:35], v[152:155], v[186:189], v[32:35]
	v_mfma_f32_16x16x32_bf16 v[20:23], v[144:147], v[194:197], v[20:23]
	v_mfma_f32_16x16x32_bf16 v[16:19], v[152:155], v[194:197], v[16:19]
	v_mfma_f32_16x16x32_bf16 v[4:7], v[144:147], v[202:205], v[4:7]
	v_mfma_f32_16x16x32_bf16 v[0:3], v[152:155], v[202:205], v[0:3]
	v_mfma_f32_16x16x32_bf16 v[52:55], v[148:151], v[182:185], v[52:55]
	v_mfma_f32_16x16x32_bf16 v[48:51], v[156:159], v[182:185], v[48:51]
	v_mfma_f32_16x16x32_bf16 v[36:39], v[148:151], v[190:193], v[36:39]
	v_mfma_f32_16x16x32_bf16 v[32:35], v[156:159], v[190:193], v[32:35]
	s_setprio 2
	s_barrier
	v_mfma_f32_16x16x32_bf16 v[20:23], v[148:151], v[198:201], v[20:23]
	v_mfma_f32_16x16x32_bf16 v[16:19], v[156:159], v[198:201], v[16:19]
	v_mfma_f32_16x16x32_bf16 v[4:7], v[148:151], v[218:221], v[4:7]
	v_mfma_f32_16x16x32_bf16 v[0:3], v[156:159], v[218:221], v[0:3]
	s_setprio 0
	s_add_i32 s78, s78, 2
	s_add_u32 s6, s6, 0x100
	s_addc_u32 s7, s7, 0
	s_add_u32 s56, s56, 0x100
	s_addc_u32 s57, s57, 0
	s_cmp_gt_u32 s78, 13
.LBB0_323:
	ds_read_b128 v[96:99], v209
	ds_read_b128 v[100:103], v209 offset:1024
	ds_read_b128 v[120:123], v209 offset:2048
	ds_read_b128 v[124:127], v209 offset:3072
	ds_read_b128 v[144:147], v210
	ds_read_b128 v[148:151], v210 offset:1024
	ds_read_b128 v[152:155], v210 offset:2048
	ds_read_b128 v[156:159], v210 offset:3072
	s_add_u32 s8, s6, 0xfffc0080
	s_addc_u32 s9, s7, -1
	s_cmp_eq_u32 s78, 12
	s_cselect_b32 s51, s18, s9
	s_cselect_b32 s50, s43, s8
	s_cselect_b32 s9, s45, s57
	s_cselect_b32 s8, s55, s56
	v_lshl_add_u64 v[206:207], s[6:7], 0, v[170:171]
	s_add_i32 m0, s17, 0xc000
	ds_read_b128 v[178:181], v211
	ds_read_b128 v[182:185], v211 offset:1024
	ds_read_b128 v[186:189], v211 offset:2048
	ds_read_b128 v[190:193], v211 offset:3072
	ds_read_b128 v[194:197], v211 offset:4096
	ds_read_b128 v[198:201], v211 offset:5120
	ds_read_b128 v[202:205], v211 offset:6144
	ds_read_b128 v[218:221], v211 offset:7168
	global_load_lds_dwordx4 v[206:207], off
	s_add_i32 m0, s17, 0xe000
	v_lshl_add_u64 v[206:207], s[6:7], 0, v[172:173]
	global_load_lds_dwordx4 v[206:207], off
	s_waitcnt vmcnt(8)
	s_waitcnt lgkmcnt(0)
	s_barrier
	s_setprio 1
	s_waitcnt lgkmcnt(0)
	v_mfma_f32_16x16x32_bf16 v[140:143], v[96:99], v[178:181], v[140:143]
	v_mfma_f32_16x16x32_bf16 v[136:139], v[120:123], v[178:181], v[136:139]
	v_mfma_f32_16x16x32_bf16 v[116:119], v[96:99], v[186:189], v[116:119]
	v_mfma_f32_16x16x32_bf16 v[112:115], v[120:123], v[186:189], v[112:115]
	v_mfma_f32_16x16x32_bf16 v[92:95], v[96:99], v[194:197], v[92:95]
	v_mfma_f32_16x16x32_bf16 v[88:91], v[120:123], v[194:197], v[88:91]
	v_mfma_f32_16x16x32_bf16 v[76:79], v[96:99], v[202:205], v[76:79]
	v_mfma_f32_16x16x32_bf16 v[72:75], v[120:123], v[202:205], v[72:75]
	v_mfma_f32_16x16x32_bf16 v[140:143], v[100:103], v[182:185], v[140:143]
	v_mfma_f32_16x16x32_bf16 v[136:139], v[124:127], v[182:185], v[136:139]
	v_mfma_f32_16x16x32_bf16 v[116:119], v[100:103], v[190:193], v[116:119]
	v_mfma_f32_16x16x32_bf16 v[112:115], v[124:127], v[190:193], v[112:115]
	v_mfma_f32_16x16x32_bf16 v[92:95], v[100:103], v[198:201], v[92:95]
	v_mfma_f32_16x16x32_bf16 v[88:91], v[124:127], v[198:201], v[88:91]
	v_mfma_f32_16x16x32_bf16 v[76:79], v[100:103], v[218:221], v[76:79]
	v_mfma_f32_16x16x32_bf16 v[72:75], v[124:127], v[218:221], v[72:75]
	s_setprio 0
	s_setprio 1
	v_mfma_f32_16x16x32_bf16 v[132:135], v[144:147], v[178:181], v[132:135]
	v_mfma_f32_16x16x32_bf16 v[128:131], v[152:155], v[178:181], v[128:131]
	v_mfma_f32_16x16x32_bf16 v[108:111], v[144:147], v[186:189], v[108:111]
	v_mfma_f32_16x16x32_bf16 v[104:107], v[152:155], v[186:189], v[104:107]
	v_mfma_f32_16x16x32_bf16 v[84:87], v[144:147], v[194:197], v[84:87]
	v_mfma_f32_16x16x32_bf16 v[80:83], v[152:155], v[194:197], v[80:83]
	v_mfma_f32_16x16x32_bf16 v[68:71], v[144:147], v[202:205], v[68:71]
	v_mfma_f32_16x16x32_bf16 v[64:67], v[152:155], v[202:205], v[64:67]
	v_mfma_f32_16x16x32_bf16 v[132:135], v[148:151], v[182:185], v[132:135]
	v_mfma_f32_16x16x32_bf16 v[128:131], v[156:159], v[182:185], v[128:131]
	v_mfma_f32_16x16x32_bf16 v[108:111], v[148:151], v[190:193], v[108:111]
	v_mfma_f32_16x16x32_bf16 v[104:107], v[156:159], v[190:193], v[104:107]
	s_setprio 2
	s_barrier
	v_mfma_f32_16x16x32_bf16 v[84:87], v[148:151], v[198:201], v[84:87]
	v_mfma_f32_16x16x32_bf16 v[80:83], v[156:159], v[198:201], v[80:83]
	v_mfma_f32_16x16x32_bf16 v[68:71], v[148:151], v[218:221], v[68:71]
	v_mfma_f32_16x16x32_bf16 v[64:67], v[156:159], v[218:221], v[64:67]
	s_setprio 0
	s_add_i32 s79, s73, s61
	v_lshl_add_u64 v[206:207], s[8:9], 0, v[162:163]
	s_mov_b32 m0, s79
	ds_read_b128 v[178:181], v211 offset:16384
	ds_read_b128 v[182:185], v211 offset:17408
	ds_read_b128 v[186:189], v211 offset:18432
	ds_read_b128 v[190:193], v211 offset:19456
	ds_read_b128 v[194:197], v211 offset:20480
	ds_read_b128 v[198:201], v211 offset:21504
	global_load_lds_dwordx4 v[206:207], off
	s_add_i32 m0, s79, 0x2000
	s_add_u32 s80, s8, 0x40000
	v_lshl_add_u64 v[222:223], s[8:9], 0, v[166:167]
	s_addc_u32 s81, s9, 0
	s_add_i32 s79, s74, s61
	global_load_lds_dwordx4 v[222:223], off
	s_mov_b32 m0, s79
	v_lshl_add_u64 v[226:227], s[50:51], 0, v[164:165]
	global_load_lds_dwordx4 v162, s[80:81]
	s_add_i32 m0, s79, 0x2000
	ds_read_b128 v[202:205], v211 offset:22528
	global_load_lds_dwordx4 v166, s[80:81]
	s_mov_b32 m0, s17
	v_lshl_add_u64 v[224:225], s[50:51], 0, v[160:161]
	global_load_lds_dwordx4 v[224:225], off
	s_mov_b32 m0, s62
	ds_read_b128 v[218:221], v211 offset:23552
	global_load_lds_dwordx4 v[226:227], off
	s_waitcnt vmcnt(8)
	s_waitcnt lgkmcnt(0)
	s_barrier
	s_setprio 1
	s_waitcnt lgkmcnt(0)
	v_mfma_f32_16x16x32_bf16 v[60:63], v[96:99], v[178:181], v[60:63]
	v_mfma_f32_16x16x32_bf16 v[56:59], v[120:123], v[178:181], v[56:59]
	v_mfma_f32_16x16x32_bf16 v[44:47], v[96:99], v[186:189], v[44:47]
	v_mfma_f32_16x16x32_bf16 v[40:43], v[120:123], v[186:189], v[40:43]
	v_mfma_f32_16x16x32_bf16 v[28:31], v[96:99], v[194:197], v[28:31]
	v_mfma_f32_16x16x32_bf16 v[24:27], v[120:123], v[194:197], v[24:27]
	v_mfma_f32_16x16x32_bf16 v[12:15], v[96:99], v[202:205], v[12:15]
	v_mfma_f32_16x16x32_bf16 v[8:11], v[120:123], v[202:205], v[8:11]
	v_mfma_f32_16x16x32_bf16 v[60:63], v[100:103], v[182:185], v[60:63]
	v_mfma_f32_16x16x32_bf16 v[56:59], v[124:127], v[182:185], v[56:59]
	v_mfma_f32_16x16x32_bf16 v[44:47], v[100:103], v[190:193], v[44:47]
	v_mfma_f32_16x16x32_bf16 v[40:43], v[124:127], v[190:193], v[40:43]
	v_mfma_f32_16x16x32_bf16 v[28:31], v[100:103], v[198:201], v[28:31]
	v_mfma_f32_16x16x32_bf16 v[24:27], v[124:127], v[198:201], v[24:27]
	v_mfma_f32_16x16x32_bf16 v[12:15], v[100:103], v[218:221], v[12:15]
	v_mfma_f32_16x16x32_bf16 v[8:11], v[124:127], v[218:221], v[8:11]
	s_setprio 0
	s_setprio 1
	v_mfma_f32_16x16x32_bf16 v[52:55], v[144:147], v[178:181], v[52:55]
	v_mfma_f32_16x16x32_bf16 v[48:51], v[152:155], v[178:181], v[48:51]
	v_mfma_f32_16x16x32_bf16 v[36:39], v[144:147], v[186:189], v[36:39]
	v_mfma_f32_16x16x32_bf16 v[32:35], v[152:155], v[186:189], v[32:35]
	v_mfma_f32_16x16x32_bf16 v[20:23], v[144:147], v[194:197], v[20:23]
	v_mfma_f32_16x16x32_bf16 v[16:19], v[152:155], v[194:197], v[16:19]
	v_mfma_f32_16x16x32_bf16 v[4:7], v[144:147], v[202:205], v[4:7]
	v_mfma_f32_16x16x32_bf16 v[0:3], v[152:155], v[202:205], v[0:3]
	v_mfma_f32_16x16x32_bf16 v[52:55], v[148:151], v[182:185], v[52:55]
	v_mfma_f32_16x16x32_bf16 v[48:51], v[156:159], v[182:185], v[48:51]
	v_mfma_f32_16x16x32_bf16 v[36:39], v[148:151], v[190:193], v[36:39]
	v_mfma_f32_16x16x32_bf16 v[32:35], v[156:159], v[190:193], v[32:35]
	s_setprio 2
	s_barrier
	v_mfma_f32_16x16x32_bf16 v[20:23], v[148:151], v[198:201], v[20:23]
	v_mfma_f32_16x16x32_bf16 v[16:19], v[156:159], v[198:201], v[16:19]
	v_mfma_f32_16x16x32_bf16 v[4:7], v[148:151], v[218:221], v[4:7]
	v_mfma_f32_16x16x32_bf16 v[0:3], v[156:159], v[218:221], v[0:3]
	s_setprio 0
	s_add_i32 s79, 0, 0x18000
	s_add_i32 s80, 0, 0x1c000
	v_add_u32_e32 v124, s79, v208
	v_add_u32_e32 v156, s80, v208
	ds_read_b128 v[96:99], v124
	ds_read_b128 v[100:103], v124 offset:1024
	ds_read_b128 v[120:123], v124 offset:2048
	ds_read_b128 v[124:127], v124 offset:3072
	ds_read_b128 v[144:147], v156
	ds_read_b128 v[148:151], v156 offset:1024
	ds_read_b128 v[152:155], v156 offset:2048
	ds_read_b128 v[156:159], v156 offset:3072
	s_add_u32 s50, s50, 0x40000
	s_addc_u32 s51, s51, 0
	s_mov_b32 m0, s63
	v_lshl_add_u64 v[228:229], s[50:51], 0, v[160:161]
	ds_read_b128 v[178:181], v211 offset:32768
	ds_read_b128 v[182:185], v211 offset:33792
	ds_read_b128 v[186:189], v211 offset:34816
	ds_read_b128 v[190:193], v211 offset:35840
	ds_read_b128 v[194:197], v211 offset:36864
	ds_read_b128 v[198:201], v211 offset:37888
	ds_read_b128 v[202:205], v211 offset:38912
	ds_read_b128 v[218:221], v211 offset:39936
	global_load_lds_dwordx4 v[228:229], off
	s_mov_b32 m0, s64
	v_lshl_add_u64 v[228:229], s[50:51], 0, v[164:165]
	global_load_lds_dwordx4 v[228:229], off
	s_waitcnt vmcnt(8)
	s_waitcnt lgkmcnt(0)
	s_barrier
	s_setprio 1
	s_waitcnt lgkmcnt(0)
	v_mfma_f32_16x16x32_bf16 v[140:143], v[96:99], v[178:181], v[140:143]
	v_mfma_f32_16x16x32_bf16 v[136:139], v[120:123], v[178:181], v[136:139]
	v_mfma_f32_16x16x32_bf16 v[116:119], v[96:99], v[186:189], v[116:119]
	v_mfma_f32_16x16x32_bf16 v[112:115], v[120:123], v[186:189], v[112:115]
	v_mfma_f32_16x16x32_bf16 v[92:95], v[96:99], v[194:197], v[92:95]
	v_mfma_f32_16x16x32_bf16 v[88:91], v[120:123], v[194:197], v[88:91]
	v_mfma_f32_16x16x32_bf16 v[76:79], v[96:99], v[202:205], v[76:79]
	v_mfma_f32_16x16x32_bf16 v[72:75], v[120:123], v[202:205], v[72:75]
	v_mfma_f32_16x16x32_bf16 v[140:143], v[100:103], v[182:185], v[140:143]
	v_mfma_f32_16x16x32_bf16 v[136:139], v[124:127], v[182:185], v[136:139]
	v_mfma_f32_16x16x32_bf16 v[116:119], v[100:103], v[190:193], v[116:119]
	v_mfma_f32_16x16x32_bf16 v[112:115], v[124:127], v[190:193], v[112:115]
	v_mfma_f32_16x16x32_bf16 v[92:95], v[100:103], v[198:201], v[92:95]
	v_mfma_f32_16x16x32_bf16 v[88:91], v[124:127], v[198:201], v[88:91]
	v_mfma_f32_16x16x32_bf16 v[76:79], v[100:103], v[218:221], v[76:79]
	v_mfma_f32_16x16x32_bf16 v[72:75], v[124:127], v[218:221], v[72:75]
	s_setprio 0
	s_setprio 1
	v_mfma_f32_16x16x32_bf16 v[132:135], v[144:147], v[178:181], v[132:135]
	v_mfma_f32_16x16x32_bf16 v[128:131], v[152:155], v[178:181], v[128:131]
	v_mfma_f32_16x16x32_bf16 v[108:111], v[144:147], v[186:189], v[108:111]
	v_mfma_f32_16x16x32_bf16 v[104:107], v[152:155], v[186:189], v[104:107]
	v_mfma_f32_16x16x32_bf16 v[84:87], v[144:147], v[194:197], v[84:87]
	v_mfma_f32_16x16x32_bf16 v[80:83], v[152:155], v[194:197], v[80:83]
	v_mfma_f32_16x16x32_bf16 v[68:71], v[144:147], v[202:205], v[68:71]
	v_mfma_f32_16x16x32_bf16 v[64:67], v[152:155], v[202:205], v[64:67]
	v_mfma_f32_16x16x32_bf16 v[132:135], v[148:151], v[182:185], v[132:135]
	v_mfma_f32_16x16x32_bf16 v[128:131], v[156:159], v[182:185], v[128:131]
	v_mfma_f32_16x16x32_bf16 v[108:111], v[148:151], v[190:193], v[108:111]
	v_mfma_f32_16x16x32_bf16 v[104:107], v[156:159], v[190:193], v[104:107]
	s_setprio 2
	s_barrier
	v_mfma_f32_16x16x32_bf16 v[84:87], v[148:151], v[198:201], v[84:87]
	v_mfma_f32_16x16x32_bf16 v[80:83], v[156:159], v[198:201], v[80:83]
	v_mfma_f32_16x16x32_bf16 v[68:71], v[148:151], v[218:221], v[68:71]
	v_mfma_f32_16x16x32_bf16 v[64:67], v[156:159], v[218:221], v[64:67]
	s_setprio 0
	s_add_i32 s50, s79, s61
	s_add_i32 m0, s50, 0xffffff80
	ds_read_b128 v[178:181], v211 offset:49152
	ds_read_b128 v[182:185], v211 offset:50176
	ds_read_b128 v[186:189], v211 offset:51200
	ds_read_b128 v[190:193], v211 offset:52224
	ds_read_b128 v[194:197], v211 offset:53248
	global_load_lds_dwordx4 v[206:207], off offset:128
	s_add_i32 m0, s50, 0x1f80
	s_add_u32 s8, s8, 0x40080
	s_addc_u32 s9, s9, 0
	s_add_i32 s50, s80, s61
	global_load_lds_dwordx4 v[222:223], off offset:128
	s_mov_b32 m0, s50
	ds_read_b128 v[198:201], v211 offset:54272
	global_load_lds_dwordx4 v162, s[8:9]
	s_add_i32 m0, s50, 0x2000
	ds_read_b128 v[202:205], v211 offset:55296
	global_load_lds_dwordx4 v166, s[8:9]
	s_add_i32 m0, s68, 0xffffff80
	ds_read_b128 v[218:221], v211 offset:56320
	global_load_lds_dwordx4 v[224:225], off offset:128
	s_mov_b32 m0, s69
	v_lshl_add_u64 v[206:207], v[226:227], 0, s[36:37]
	global_load_lds_dwordx4 v[206:207], off
	s_waitcnt vmcnt(8)
	s_waitcnt lgkmcnt(0)
	s_barrier
	s_setprio 1
	s_waitcnt lgkmcnt(0)
	v_mfma_f32_16x16x32_bf16 v[60:63], v[96:99], v[178:181], v[60:63]
	v_mfma_f32_16x16x32_bf16 v[56:59], v[120:123], v[178:181], v[56:59]
	v_mfma_f32_16x16x32_bf16 v[44:47], v[96:99], v[186:189], v[44:47]
	v_mfma_f32_16x16x32_bf16 v[40:43], v[120:123], v[186:189], v[40:43]
	v_mfma_f32_16x16x32_bf16 v[28:31], v[96:99], v[194:197], v[28:31]
	v_mfma_f32_16x16x32_bf16 v[24:27], v[120:123], v[194:197], v[24:27]
	v_mfma_f32_16x16x32_bf16 v[12:15], v[96:99], v[202:205], v[12:15]
	v_mfma_f32_16x16x32_bf16 v[8:11], v[120:123], v[202:205], v[8:11]
	v_mfma_f32_16x16x32_bf16 v[60:63], v[100:103], v[182:185], v[60:63]
	v_mfma_f32_16x16x32_bf16 v[56:59], v[124:127], v[182:185], v[56:59]
	v_mfma_f32_16x16x32_bf16 v[44:47], v[100:103], v[190:193], v[44:47]
	v_mfma_f32_16x16x32_bf16 v[40:43], v[124:127], v[190:193], v[40:43]
	v_mfma_f32_16x16x32_bf16 v[28:31], v[100:103], v[198:201], v[28:31]
	v_mfma_f32_16x16x32_bf16 v[24:27], v[124:127], v[198:201], v[24:27]
	v_mfma_f32_16x16x32_bf16 v[12:15], v[100:103], v[218:221], v[12:15]
	v_mfma_f32_16x16x32_bf16 v[8:11], v[124:127], v[218:221], v[8:11]
	s_setprio 0
	s_setprio 1
	v_mfma_f32_16x16x32_bf16 v[52:55], v[144:147], v[178:181], v[52:55]
	v_mfma_f32_16x16x32_bf16 v[48:51], v[152:155], v[178:181], v[48:51]
	v_mfma_f32_16x16x32_bf16 v[36:39], v[144:147], v[186:189], v[36:39]
	v_mfma_f32_16x16x32_bf16 v[32:35], v[152:155], v[186:189], v[32:35]
	v_mfma_f32_16x16x32_bf16 v[20:23], v[144:147], v[194:197], v[20:23]
	v_mfma_f32_16x16x32_bf16 v[16:19], v[152:155], v[194:197], v[16:19]
	v_mfma_f32_16x16x32_bf16 v[4:7], v[144:147], v[202:205], v[4:7]
	v_mfma_f32_16x16x32_bf16 v[0:3], v[152:155], v[202:205], v[0:3]
	v_mfma_f32_16x16x32_bf16 v[52:55], v[148:151], v[182:185], v[52:55]
	v_mfma_f32_16x16x32_bf16 v[48:51], v[156:159], v[182:185], v[48:51]
	v_mfma_f32_16x16x32_bf16 v[36:39], v[148:151], v[190:193], v[36:39]
	v_mfma_f32_16x16x32_bf16 v[32:35], v[156:159], v[190:193], v[32:35]
	s_setprio 2
	s_barrier
	v_mfma_f32_16x16x32_bf16 v[20:23], v[148:151], v[198:201], v[20:23]
	v_mfma_f32_16x16x32_bf16 v[16:19], v[156:159], v[198:201], v[16:19]
	v_mfma_f32_16x16x32_bf16 v[4:7], v[148:151], v[218:221], v[4:7]
	v_mfma_f32_16x16x32_bf16 v[0:3], v[156:159], v[218:221], v[0:3]
	s_setprio 0
	s_add_i32 s78, s78, 2
	s_add_u32 s6, s6, 0x100
	s_addc_u32 s7, s7, 0
	s_add_u32 s56, s56, 0x100
	s_addc_u32 s57, s57, 0
	s_cmp_gt_u32 s78, 13
	s_cbranch_scc0 .LBB0_323

.LBB0_700:
	ds_read_b128 v[130:133], v203
	ds_read_b128 v[134:137], v203 offset:1024
	ds_read_b128 v[138:141], v203 offset:2048
	ds_read_b128 v[142:145], v203 offset:3072
	ds_read_b128 v[146:149], v195
	ds_read_b128 v[150:153], v195 offset:1024
	ds_read_b128 v[154:157], v195 offset:2048
	ds_read_b128 v[158:161], v195 offset:3072
	s_add_u32 s47, s44, 0xfff80080
	s_addc_u32 s48, s45, -1
	s_cmp_eq_u32 s46, 28
	s_cselect_b32 s49, s29, s48
	s_cselect_b32 s48, s71, s47
	s_cselect_b32 s47, s31, s84
	s_cselect_b32 s46, s72, s83
	s_mov_b32 m0, s73
	v_lshl_add_u64 v[174:175], s[44:45], 0, v[180:181]
	ds_read_b128 v[162:165], v211
	ds_read_b128 v[166:169], v211 offset:1024
	ds_read_b128 v[170:173], v211 offset:2048
	ds_read_b128 v[184:187], v211 offset:3072
	ds_read_b128 v[190:193], v211 offset:4096
	ds_read_b128 v[196:199], v211 offset:5120
	ds_read_b128 v[204:207], v211 offset:6144
	ds_read_b128 v[212:215], v211 offset:7168
	global_load_lds_dwordx4 v[174:175], off
	s_mov_b32 m0, s74
	v_lshl_add_u64 v[174:175], s[44:45], 0, v[182:183]
	global_load_lds_dwordx4 v[174:175], off
	s_waitcnt vmcnt(8)
	s_waitcnt lgkmcnt(0)
	s_barrier
	s_setprio 1
	s_waitcnt lgkmcnt(0)
	v_mfma_f32_16x16x32_bf16 v[124:127], v[130:133], v[162:165], v[124:127]
	v_mfma_f32_16x16x32_bf16 v[120:123], v[138:141], v[162:165], v[120:123]
	v_mfma_f32_16x16x32_bf16 v[108:111], v[130:133], v[170:173], v[108:111]
	v_mfma_f32_16x16x32_bf16 v[104:107], v[138:141], v[170:173], v[104:107]
	v_mfma_f32_16x16x32_bf16 v[92:95], v[130:133], v[190:193], v[92:95]
	v_mfma_f32_16x16x32_bf16 v[88:91], v[138:141], v[190:193], v[88:91]
	v_mfma_f32_16x16x32_bf16 v[76:79], v[130:133], v[204:207], v[76:79]
	v_mfma_f32_16x16x32_bf16 v[72:75], v[138:141], v[204:207], v[72:75]
	v_mfma_f32_16x16x32_bf16 v[124:127], v[134:137], v[166:169], v[124:127]
	v_mfma_f32_16x16x32_bf16 v[120:123], v[142:145], v[166:169], v[120:123]
	v_mfma_f32_16x16x32_bf16 v[108:111], v[134:137], v[184:187], v[108:111]
	v_mfma_f32_16x16x32_bf16 v[104:107], v[142:145], v[184:187], v[104:107]
	v_mfma_f32_16x16x32_bf16 v[92:95], v[134:137], v[196:199], v[92:95]
	v_mfma_f32_16x16x32_bf16 v[88:91], v[142:145], v[196:199], v[88:91]
	v_mfma_f32_16x16x32_bf16 v[76:79], v[134:137], v[212:215], v[76:79]
	v_mfma_f32_16x16x32_bf16 v[72:75], v[142:145], v[212:215], v[72:75]
	s_setprio 0
	s_setprio 1
	v_mfma_f32_16x16x32_bf16 v[116:119], v[146:149], v[162:165], v[116:119]
	v_mfma_f32_16x16x32_bf16 v[112:115], v[154:157], v[162:165], v[112:115]
	v_mfma_f32_16x16x32_bf16 v[100:103], v[146:149], v[170:173], v[100:103]
	v_mfma_f32_16x16x32_bf16 v[96:99], v[154:157], v[170:173], v[96:99]
	v_mfma_f32_16x16x32_bf16 v[84:87], v[146:149], v[190:193], v[84:87]
	v_mfma_f32_16x16x32_bf16 v[80:83], v[154:157], v[190:193], v[80:83]
	v_mfma_f32_16x16x32_bf16 v[68:71], v[146:149], v[204:207], v[68:71]
	v_mfma_f32_16x16x32_bf16 v[64:67], v[154:157], v[204:207], v[64:67]
	v_mfma_f32_16x16x32_bf16 v[116:119], v[150:153], v[166:169], v[116:119]
	v_mfma_f32_16x16x32_bf16 v[112:115], v[158:161], v[166:169], v[112:115]
	v_mfma_f32_16x16x32_bf16 v[100:103], v[150:153], v[184:187], v[100:103]
	v_mfma_f32_16x16x32_bf16 v[96:99], v[158:161], v[184:187], v[96:99]
	s_setprio 2
	s_barrier
	v_mfma_f32_16x16x32_bf16 v[84:87], v[150:153], v[196:199], v[84:87]
	v_mfma_f32_16x16x32_bf16 v[80:83], v[158:161], v[196:199], v[80:83]
	v_mfma_f32_16x16x32_bf16 v[68:71], v[150:153], v[212:215], v[68:71]
	v_mfma_f32_16x16x32_bf16 v[64:67], v[158:161], v[212:215], v[64:67]
	s_setprio 0
	s_mov_b32 m0, s75
	v_lshl_add_u64 v[174:175], s[46:47], 0, v[176:177]
	s_add_u32 s86, s46, 0x80000
	ds_read_b128 v[162:165], v211 offset:16384
	ds_read_b128 v[166:169], v211 offset:17408
	ds_read_b128 v[170:173], v211 offset:18432
	ds_read_b128 v[184:187], v211 offset:19456
	ds_read_b128 v[190:193], v211 offset:20480
	ds_read_b128 v[196:199], v211 offset:21504
	ds_read_b128 v[204:207], v211 offset:22528
	global_load_lds_dwordx4 v[174:175], off
	v_lshl_add_u64 v[200:201], s[46:47], 0, v[178:179]
	s_mov_b32 m0, s76
	s_addc_u32 s87, s47, 0
	global_load_lds_dwordx4 v[200:201], off
	v_lshl_add_u64 v[208:209], s[86:87], 0, v[176:177]
	s_mov_b32 m0, s77
	v_lshl_add_u64 v[216:217], s[48:49], 0, v[178:179]
	global_load_lds_dwordx4 v[208:209], off
	s_mov_b32 m0, s78
	v_lshl_add_u64 v[208:209], s[86:87], 0, v[178:179]
	global_load_lds_dwordx4 v[208:209], off
	s_mov_b32 m0, s56
	v_lshl_add_u64 v[208:209], s[48:49], 0, v[176:177]
	global_load_lds_dwordx4 v[208:209], off
	s_mov_b32 m0, s57
	ds_read_b128 v[212:215], v211 offset:23552
	global_load_lds_dwordx4 v[216:217], off
	s_waitcnt vmcnt(8)
	s_waitcnt lgkmcnt(0)
	s_barrier
	s_setprio 1
	s_waitcnt lgkmcnt(0)
	v_mfma_f32_16x16x32_bf16 v[60:63], v[130:133], v[162:165], v[60:63]
	v_mfma_f32_16x16x32_bf16 v[56:59], v[138:141], v[162:165], v[56:59]
	v_mfma_f32_16x16x32_bf16 v[44:47], v[130:133], v[170:173], v[44:47]
	v_mfma_f32_16x16x32_bf16 v[40:43], v[138:141], v[170:173], v[40:43]
	v_mfma_f32_16x16x32_bf16 v[28:31], v[130:133], v[190:193], v[28:31]
	v_mfma_f32_16x16x32_bf16 v[24:27], v[138:141], v[190:193], v[24:27]
	v_mfma_f32_16x16x32_bf16 v[12:15], v[130:133], v[204:207], v[12:15]
	v_mfma_f32_16x16x32_bf16 v[8:11], v[138:141], v[204:207], v[8:11]
	v_mfma_f32_16x16x32_bf16 v[60:63], v[134:137], v[166:169], v[60:63]
	v_mfma_f32_16x16x32_bf16 v[56:59], v[142:145], v[166:169], v[56:59]
	v_mfma_f32_16x16x32_bf16 v[44:47], v[134:137], v[184:187], v[44:47]
	v_mfma_f32_16x16x32_bf16 v[40:43], v[142:145], v[184:187], v[40:43]
	v_mfma_f32_16x16x32_bf16 v[28:31], v[134:137], v[196:199], v[28:31]
	v_mfma_f32_16x16x32_bf16 v[24:27], v[142:145], v[196:199], v[24:27]
	v_mfma_f32_16x16x32_bf16 v[12:15], v[134:137], v[212:215], v[12:15]
	v_mfma_f32_16x16x32_bf16 v[8:11], v[142:145], v[212:215], v[8:11]
	s_setprio 0
	s_setprio 1
	v_mfma_f32_16x16x32_bf16 v[52:55], v[146:149], v[162:165], v[52:55]
	v_mfma_f32_16x16x32_bf16 v[48:51], v[154:157], v[162:165], v[48:51]
	v_mfma_f32_16x16x32_bf16 v[36:39], v[146:149], v[170:173], v[36:39]
	v_mfma_f32_16x16x32_bf16 v[32:35], v[154:157], v[170:173], v[32:35]
	v_mfma_f32_16x16x32_bf16 v[20:23], v[146:149], v[190:193], v[20:23]
	v_mfma_f32_16x16x32_bf16 v[16:19], v[154:157], v[190:193], v[16:19]
	v_mfma_f32_16x16x32_bf16 v[4:7], v[146:149], v[204:207], v[4:7]
	v_mfma_f32_16x16x32_bf16 v[0:3], v[154:157], v[204:207], v[0:3]
	v_mfma_f32_16x16x32_bf16 v[52:55], v[150:153], v[166:169], v[52:55]
	v_mfma_f32_16x16x32_bf16 v[48:51], v[158:161], v[166:169], v[48:51]
	v_mfma_f32_16x16x32_bf16 v[36:39], v[150:153], v[184:187], v[36:39]
	v_mfma_f32_16x16x32_bf16 v[32:35], v[158:161], v[184:187], v[32:35]
	s_setprio 2
	s_barrier
	v_mfma_f32_16x16x32_bf16 v[20:23], v[150:153], v[196:199], v[20:23]
	v_mfma_f32_16x16x32_bf16 v[16:19], v[158:161], v[196:199], v[16:19]
	v_mfma_f32_16x16x32_bf16 v[4:7], v[150:153], v[212:215], v[4:7]
	v_mfma_f32_16x16x32_bf16 v[0:3], v[158:161], v[212:215], v[0:3]
	s_setprio 0
	ds_read_b128 v[130:133], v128
	ds_read_b128 v[134:137], v128 offset:1024
	ds_read_b128 v[138:141], v128 offset:2048
	ds_read_b128 v[142:145], v128 offset:3072
	ds_read_b128 v[146:149], v129
	ds_read_b128 v[150:153], v129 offset:1024
	ds_read_b128 v[154:157], v129 offset:2048
	ds_read_b128 v[158:161], v129 offset:3072
	s_add_u32 s48, s48, 0x80000
	s_addc_u32 s49, s49, 0
	s_mov_b32 m0, s58
	v_lshl_add_u64 v[218:219], s[48:49], 0, v[176:177]
	ds_read_b128 v[162:165], v211 offset:32768
	ds_read_b128 v[166:169], v211 offset:33792
	ds_read_b128 v[170:173], v211 offset:34816
	ds_read_b128 v[184:187], v211 offset:35840
	ds_read_b128 v[190:193], v211 offset:36864
	ds_read_b128 v[196:199], v211 offset:37888
	ds_read_b128 v[204:207], v211 offset:38912
	ds_read_b128 v[212:215], v211 offset:39936
	global_load_lds_dwordx4 v[218:219], off
	s_mov_b32 m0, s59
	v_lshl_add_u64 v[218:219], s[48:49], 0, v[178:179]
	global_load_lds_dwordx4 v[218:219], off
	s_waitcnt vmcnt(8)
	s_waitcnt lgkmcnt(0)
	s_barrier
	s_setprio 1
	s_waitcnt lgkmcnt(0)
	v_mfma_f32_16x16x32_bf16 v[124:127], v[130:133], v[162:165], v[124:127]
	v_mfma_f32_16x16x32_bf16 v[120:123], v[138:141], v[162:165], v[120:123]
	v_mfma_f32_16x16x32_bf16 v[108:111], v[130:133], v[170:173], v[108:111]
	v_mfma_f32_16x16x32_bf16 v[104:107], v[138:141], v[170:173], v[104:107]
	v_mfma_f32_16x16x32_bf16 v[92:95], v[130:133], v[190:193], v[92:95]
	v_mfma_f32_16x16x32_bf16 v[88:91], v[138:141], v[190:193], v[88:91]
	v_mfma_f32_16x16x32_bf16 v[76:79], v[130:133], v[204:207], v[76:79]
	v_mfma_f32_16x16x32_bf16 v[72:75], v[138:141], v[204:207], v[72:75]
	v_mfma_f32_16x16x32_bf16 v[124:127], v[134:137], v[166:169], v[124:127]
	v_mfma_f32_16x16x32_bf16 v[120:123], v[142:145], v[166:169], v[120:123]
	v_mfma_f32_16x16x32_bf16 v[108:111], v[134:137], v[184:187], v[108:111]
	v_mfma_f32_16x16x32_bf16 v[104:107], v[142:145], v[184:187], v[104:107]
	v_mfma_f32_16x16x32_bf16 v[92:95], v[134:137], v[196:199], v[92:95]
	v_mfma_f32_16x16x32_bf16 v[88:91], v[142:145], v[196:199], v[88:91]
	v_mfma_f32_16x16x32_bf16 v[76:79], v[134:137], v[212:215], v[76:79]
	v_mfma_f32_16x16x32_bf16 v[72:75], v[142:145], v[212:215], v[72:75]
	s_setprio 0
	s_setprio 1
	v_mfma_f32_16x16x32_bf16 v[116:119], v[146:149], v[162:165], v[116:119]
	v_mfma_f32_16x16x32_bf16 v[112:115], v[154:157], v[162:165], v[112:115]
	v_mfma_f32_16x16x32_bf16 v[100:103], v[146:149], v[170:173], v[100:103]
	v_mfma_f32_16x16x32_bf16 v[96:99], v[154:157], v[170:173], v[96:99]
	v_mfma_f32_16x16x32_bf16 v[84:87], v[146:149], v[190:193], v[84:87]
	v_mfma_f32_16x16x32_bf16 v[80:83], v[154:157], v[190:193], v[80:83]
	v_mfma_f32_16x16x32_bf16 v[68:71], v[146:149], v[204:207], v[68:71]
	v_mfma_f32_16x16x32_bf16 v[64:67], v[154:157], v[204:207], v[64:67]
	v_mfma_f32_16x16x32_bf16 v[116:119], v[150:153], v[166:169], v[116:119]
	v_mfma_f32_16x16x32_bf16 v[112:115], v[158:161], v[166:169], v[112:115]
	v_mfma_f32_16x16x32_bf16 v[100:103], v[150:153], v[184:187], v[100:103]
	v_mfma_f32_16x16x32_bf16 v[96:99], v[158:161], v[184:187], v[96:99]
	s_setprio 2
	s_barrier
	v_mfma_f32_16x16x32_bf16 v[84:87], v[150:153], v[196:199], v[84:87]
	v_mfma_f32_16x16x32_bf16 v[80:83], v[158:161], v[196:199], v[80:83]
	v_mfma_f32_16x16x32_bf16 v[68:71], v[150:153], v[212:215], v[68:71]
	v_mfma_f32_16x16x32_bf16 v[64:67], v[158:161], v[212:215], v[64:67]
	s_setprio 0
	s_mov_b32 m0, s79
	v_lshl_add_u64 v[174:175], v[174:175], 0, s[20:21]
	s_add_u32 s46, s46, 0x80080
	ds_read_b128 v[162:165], v211 offset:49152
	ds_read_b128 v[166:169], v211 offset:50176
	ds_read_b128 v[170:173], v211 offset:51200
	ds_read_b128 v[184:187], v211 offset:52224
	ds_read_b128 v[190:193], v211 offset:53248
	ds_read_b128 v[196:199], v211 offset:54272
	ds_read_b128 v[204:207], v211 offset:55296
	ds_read_b128 v[212:215], v211 offset:56320
	global_load_lds_dwordx4 v[174:175], off
	v_lshl_add_u64 v[174:175], v[200:201], 0, s[20:21]
	s_mov_b32 m0, s80
	s_addc_u32 s47, s47, 0
	global_load_lds_dwordx4 v[174:175], off
	s_mov_b32 m0, s81
	v_lshl_add_u64 v[174:175], s[46:47], 0, v[176:177]
	global_load_lds_dwordx4 v[174:175], off
	s_mov_b32 m0, s82
	v_lshl_add_u64 v[174:175], s[46:47], 0, v[178:179]
	global_load_lds_dwordx4 v[174:175], off
	s_mov_b32 m0, s61
	v_lshl_add_u64 v[174:175], v[208:209], 0, s[20:21]
	global_load_lds_dwordx4 v[174:175], off
	s_mov_b32 m0, s62
	v_lshl_add_u64 v[174:175], v[216:217], 0, s[20:21]
	global_load_lds_dwordx4 v[174:175], off
	s_waitcnt vmcnt(8)
	s_waitcnt lgkmcnt(0)
	s_barrier
	s_setprio 1
	s_waitcnt lgkmcnt(0)
	v_mfma_f32_16x16x32_bf16 v[60:63], v[130:133], v[162:165], v[60:63]
	v_mfma_f32_16x16x32_bf16 v[56:59], v[138:141], v[162:165], v[56:59]
	v_mfma_f32_16x16x32_bf16 v[44:47], v[130:133], v[170:173], v[44:47]
	v_mfma_f32_16x16x32_bf16 v[40:43], v[138:141], v[170:173], v[40:43]
	v_mfma_f32_16x16x32_bf16 v[28:31], v[130:133], v[190:193], v[28:31]
	v_mfma_f32_16x16x32_bf16 v[24:27], v[138:141], v[190:193], v[24:27]
	v_mfma_f32_16x16x32_bf16 v[12:15], v[130:133], v[204:207], v[12:15]
	v_mfma_f32_16x16x32_bf16 v[8:11], v[138:141], v[204:207], v[8:11]
	v_mfma_f32_16x16x32_bf16 v[60:63], v[134:137], v[166:169], v[60:63]
	v_mfma_f32_16x16x32_bf16 v[56:59], v[142:145], v[166:169], v[56:59]
	v_mfma_f32_16x16x32_bf16 v[44:47], v[134:137], v[184:187], v[44:47]
	v_mfma_f32_16x16x32_bf16 v[40:43], v[142:145], v[184:187], v[40:43]
	v_mfma_f32_16x16x32_bf16 v[28:31], v[134:137], v[196:199], v[28:31]
	v_mfma_f32_16x16x32_bf16 v[24:27], v[142:145], v[196:199], v[24:27]
	v_mfma_f32_16x16x32_bf16 v[12:15], v[134:137], v[212:215], v[12:15]
	v_mfma_f32_16x16x32_bf16 v[8:11], v[142:145], v[212:215], v[8:11]
	s_setprio 0
	s_setprio 1
	v_mfma_f32_16x16x32_bf16 v[52:55], v[146:149], v[162:165], v[52:55]
	v_mfma_f32_16x16x32_bf16 v[48:51], v[154:157], v[162:165], v[48:51]
	v_mfma_f32_16x16x32_bf16 v[36:39], v[146:149], v[170:173], v[36:39]
	v_mfma_f32_16x16x32_bf16 v[32:35], v[154:157], v[170:173], v[32:35]
	v_mfma_f32_16x16x32_bf16 v[20:23], v[146:149], v[190:193], v[20:23]
	v_mfma_f32_16x16x32_bf16 v[16:19], v[154:157], v[190:193], v[16:19]
	v_mfma_f32_16x16x32_bf16 v[4:7], v[146:149], v[204:207], v[4:7]
	v_mfma_f32_16x16x32_bf16 v[0:3], v[154:157], v[204:207], v[0:3]
	v_mfma_f32_16x16x32_bf16 v[52:55], v[150:153], v[166:169], v[52:55]
	v_mfma_f32_16x16x32_bf16 v[48:51], v[158:161], v[166:169], v[48:51]
	v_mfma_f32_16x16x32_bf16 v[36:39], v[150:153], v[184:187], v[36:39]
	v_mfma_f32_16x16x32_bf16 v[32:35], v[158:161], v[184:187], v[32:35]
	s_setprio 2
	s_barrier
	v_mfma_f32_16x16x32_bf16 v[20:23], v[150:153], v[196:199], v[20:23]
	v_mfma_f32_16x16x32_bf16 v[16:19], v[158:161], v[196:199], v[16:19]
	v_mfma_f32_16x16x32_bf16 v[4:7], v[150:153], v[212:215], v[4:7]
	v_mfma_f32_16x16x32_bf16 v[0:3], v[158:161], v[212:215], v[0:3]
	s_setprio 0
	s_add_i32 s70, s70, 1
	s_add_u32 s44, s44, 0x100
	s_addc_u32 s45, s45, 0
	s_add_u32 s83, s83, 0x100
	s_addc_u32 s84, s84, 0
	s_cmp_gt_u32 s85, 29
	s_cbranch_scc0 .LBB0_698
	s_lshl_b32 s29, s41, 12
	s_and_b32 s29, s29, 0x1000
	s_add_i32 s29, s29, 0
	v_mbcnt_lo_u32_b32 v128, -1, 0
	v_mbcnt_hi_u32_b32 v128, -1, v128
	s_add_i32 s29, s29, s63
	v_lshlrev_b32_e32 v128, 4, v128
	s_add_i32 s29, s29, 0x20400
	v_and_b32_e32 v128, 0xf0, v128
	v_add_u32_e32 v128, s29, v128
	ds_read2_b32 v[214:215], v128 offset0:3 offset1:67
	ds_read2_b32 v[206:207], v128 offset0:131 offset1:195
	v_add_u32_e32 v128, 12, v128
	ds_read2st64_b32 v[196:197], v128 offset0:8 offset1:9
	ds_read2st64_b32 v[190:191], v128 offset0:10 offset1:11
	s_and_b64 vcc, exec, s[22:23]
	s_waitcnt lgkmcnt(0)
	v_mov_b32_e32 v210, v215
	v_mov_b32_e32 v202, v207
	v_mov_b32_e32 v194, v197
	v_mov_b32_e32 v188, v191
	s_cbranch_vccz .LBB0_703
	s_barrier

.LBB0_783:
	s_ashr_i32 s23, s22, 31
	s_lshl_b64 s[26:27], s[22:23], 19
	s_add_u32 s26, s43, s26
	s_addc_u32 s27, s44, s27
	s_and_b64 s[28:29], s[4:5], exec
	s_cselect_b32 s23, s27, s37
	s_cselect_b32 s31, s26, s36
	s_ashr_i32 s25, s24, 31
	s_lshl_b64 s[28:29], s[24:25], 19
	s_add_u32 s28, s45, s28
	s_addc_u32 s29, s46, s29
	s_and_b64 s[40:41], s[4:5], exec
	s_cselect_b32 s25, s29, s39
	s_cselect_b32 s62, s28, s38
	s_add_u32 s36, s36, 0x40080
	s_addc_u32 s37, s37, 0
	s_add_u32 s63, s38, 0x100
	s_addc_u32 s64, s39, 0
	s_mov_b32 s65, -2
	ds_read_b128 v[144:147], v163
	ds_read_b128 v[148:151], v163 offset:1024
	ds_read_b128 v[152:155], v163 offset:2048
	ds_read_b128 v[156:159], v163 offset:3072
	ds_read_b128 v[168:171], v164
	ds_read_b128 v[172:175], v164 offset:1024
	ds_read_b128 v[176:179], v164 offset:2048
	ds_read_b128 v[180:183], v164 offset:3072
	s_add_u32 s38, s36, 0xfffc0080
	s_addc_u32 s39, s37, -1
	s_cmp_eq_u32 s65, 12
	s_cselect_b32 s41, s23, s39
	s_cselect_b32 s40, s31, s38
	s_cselect_b32 s39, s25, s64
	s_cselect_b32 s38, s62, s63
	v_lshl_add_u64 v[160:161], s[36:37], 0, v[136:137]
	s_add_i32 m0, s50, 0xc000
	ds_read_b128 v[184:187], v165
	ds_read_b128 v[188:191], v165 offset:1024
	ds_read_b128 v[192:195], v165 offset:2048
	ds_read_b128 v[196:199], v165 offset:3072
	ds_read_b128 v[200:203], v165 offset:4096
	ds_read_b128 v[204:207], v165 offset:5120
	ds_read_b128 v[208:211], v165 offset:6144
	ds_read_b128 v[212:215], v165 offset:7168
	global_load_lds_dwordx4 v[160:161], off
	s_add_i32 m0, s50, 0xe000
	v_lshl_add_u64 v[160:161], s[36:37], 0, v[138:139]
	global_load_lds_dwordx4 v[160:161], off
	s_waitcnt vmcnt(8)
	s_waitcnt lgkmcnt(0)
	s_barrier
	s_setprio 1
	s_waitcnt lgkmcnt(0)
	v_mfma_f32_16x16x32_bf16 v[124:127], v[144:147], v[184:187], 0
	v_mfma_f32_16x16x32_bf16 v[120:123], v[152:155], v[184:187], 0
	v_mfma_f32_16x16x32_bf16 v[108:111], v[144:147], v[192:195], 0
	v_mfma_f32_16x16x32_bf16 v[104:107], v[152:155], v[192:195], 0
	v_mfma_f32_16x16x32_bf16 v[92:95], v[144:147], v[200:203], 0
	v_mfma_f32_16x16x32_bf16 v[88:91], v[152:155], v[200:203], 0
	v_mfma_f32_16x16x32_bf16 v[76:79], v[144:147], v[208:211], 0
	v_mfma_f32_16x16x32_bf16 v[72:75], v[152:155], v[208:211], 0
	v_mfma_f32_16x16x32_bf16 v[124:127], v[148:151], v[188:191], v[124:127]
	v_mfma_f32_16x16x32_bf16 v[120:123], v[156:159], v[188:191], v[120:123]
	v_mfma_f32_16x16x32_bf16 v[108:111], v[148:151], v[196:199], v[108:111]
	v_mfma_f32_16x16x32_bf16 v[104:107], v[156:159], v[196:199], v[104:107]
	v_mfma_f32_16x16x32_bf16 v[92:95], v[148:151], v[204:207], v[92:95]
	v_mfma_f32_16x16x32_bf16 v[88:91], v[156:159], v[204:207], v[88:91]
	v_mfma_f32_16x16x32_bf16 v[76:79], v[148:151], v[212:215], v[76:79]
	v_mfma_f32_16x16x32_bf16 v[72:75], v[156:159], v[212:215], v[72:75]
	s_setprio 0
	s_setprio 1
	v_mfma_f32_16x16x32_bf16 v[116:119], v[168:171], v[184:187], 0
	v_mfma_f32_16x16x32_bf16 v[112:115], v[176:179], v[184:187], 0
	v_mfma_f32_16x16x32_bf16 v[100:103], v[168:171], v[192:195], 0
	v_mfma_f32_16x16x32_bf16 v[96:99], v[176:179], v[192:195], 0
	v_mfma_f32_16x16x32_bf16 v[84:87], v[168:171], v[200:203], 0
	v_mfma_f32_16x16x32_bf16 v[80:83], v[176:179], v[200:203], 0
	v_mfma_f32_16x16x32_bf16 v[68:71], v[168:171], v[208:211], 0
	v_mfma_f32_16x16x32_bf16 v[64:67], v[176:179], v[208:211], 0
	v_mfma_f32_16x16x32_bf16 v[116:119], v[172:175], v[188:191], v[116:119]
	v_mfma_f32_16x16x32_bf16 v[112:115], v[180:183], v[188:191], v[112:115]
	v_mfma_f32_16x16x32_bf16 v[100:103], v[172:175], v[196:199], v[100:103]
	v_mfma_f32_16x16x32_bf16 v[96:99], v[180:183], v[196:199], v[96:99]
	s_setprio 2
	s_barrier
	v_mfma_f32_16x16x32_bf16 v[84:87], v[172:175], v[204:207], v[84:87]
	v_mfma_f32_16x16x32_bf16 v[80:83], v[180:183], v[204:207], v[80:83]
	v_mfma_f32_16x16x32_bf16 v[68:71], v[172:175], v[212:215], v[68:71]
	v_mfma_f32_16x16x32_bf16 v[64:67], v[180:183], v[212:215], v[64:67]
	s_setprio 0
	s_add_i32 s66, s59, s47
	v_lshl_add_u64 v[160:161], s[38:39], 0, v[132:133]
	s_mov_b32 m0, s66
	ds_read_b128 v[184:187], v165 offset:16384
	ds_read_b128 v[188:191], v165 offset:17408
	ds_read_b128 v[192:195], v165 offset:18432
	ds_read_b128 v[196:199], v165 offset:19456
	ds_read_b128 v[200:203], v165 offset:20480
	ds_read_b128 v[204:207], v165 offset:21504
	global_load_lds_dwordx4 v[160:161], off
	s_add_i32 m0, s66, 0x2000
	s_add_u32 s66, s38, 0x40000
	v_lshl_add_u64 v[216:217], s[38:39], 0, v[128:129]
	s_addc_u32 s67, s39, 0
	s_add_i32 s68, s60, s47
	global_load_lds_dwordx4 v[216:217], off
	s_mov_b32 m0, s68
	v_lshl_add_u64 v[220:221], s[40:41], 0, v[130:131]
	global_load_lds_dwordx4 v132, s[66:67]
	s_add_i32 m0, s68, 0x2000
	ds_read_b128 v[208:211], v165 offset:22528
	global_load_lds_dwordx4 v128, s[66:67]
	s_mov_b32 m0, s50
	v_lshl_add_u64 v[218:219], s[40:41], 0, v[134:135]
	global_load_lds_dwordx4 v[218:219], off
	s_mov_b32 m0, s51
	ds_read_b128 v[212:215], v165 offset:23552
	global_load_lds_dwordx4 v[220:221], off
	s_waitcnt vmcnt(8)
	s_waitcnt lgkmcnt(0)
	s_barrier
	s_setprio 1
	s_waitcnt lgkmcnt(0)
	v_mfma_f32_16x16x32_bf16 v[60:63], v[144:147], v[184:187], 0
	v_mfma_f32_16x16x32_bf16 v[56:59], v[152:155], v[184:187], 0
	v_mfma_f32_16x16x32_bf16 v[44:47], v[144:147], v[192:195], 0
	v_mfma_f32_16x16x32_bf16 v[40:43], v[152:155], v[192:195], 0
	v_mfma_f32_16x16x32_bf16 v[28:31], v[144:147], v[200:203], 0
	v_mfma_f32_16x16x32_bf16 v[24:27], v[152:155], v[200:203], 0
	v_mfma_f32_16x16x32_bf16 v[12:15], v[144:147], v[208:211], 0
	v_mfma_f32_16x16x32_bf16 v[8:11], v[152:155], v[208:211], 0
	v_mfma_f32_16x16x32_bf16 v[60:63], v[148:151], v[188:191], v[60:63]
	v_mfma_f32_16x16x32_bf16 v[56:59], v[156:159], v[188:191], v[56:59]
	v_mfma_f32_16x16x32_bf16 v[44:47], v[148:151], v[196:199], v[44:47]
	v_mfma_f32_16x16x32_bf16 v[40:43], v[156:159], v[196:199], v[40:43]
	v_mfma_f32_16x16x32_bf16 v[28:31], v[148:151], v[204:207], v[28:31]
	v_mfma_f32_16x16x32_bf16 v[24:27], v[156:159], v[204:207], v[24:27]
	v_mfma_f32_16x16x32_bf16 v[12:15], v[148:151], v[212:215], v[12:15]
	v_mfma_f32_16x16x32_bf16 v[8:11], v[156:159], v[212:215], v[8:11]
	s_setprio 0
	s_setprio 1
	v_mfma_f32_16x16x32_bf16 v[52:55], v[168:171], v[184:187], 0
	v_mfma_f32_16x16x32_bf16 v[48:51], v[176:179], v[184:187], 0
	v_mfma_f32_16x16x32_bf16 v[36:39], v[168:171], v[192:195], 0
	v_mfma_f32_16x16x32_bf16 v[32:35], v[176:179], v[192:195], 0
	v_mfma_f32_16x16x32_bf16 v[20:23], v[168:171], v[200:203], 0
	v_mfma_f32_16x16x32_bf16 v[16:19], v[176:179], v[200:203], 0
	v_mfma_f32_16x16x32_bf16 v[4:7], v[168:171], v[208:211], 0
	v_mfma_f32_16x16x32_bf16 v[0:3], v[176:179], v[208:211], 0
	v_mfma_f32_16x16x32_bf16 v[52:55], v[172:175], v[188:191], v[52:55]
	v_mfma_f32_16x16x32_bf16 v[48:51], v[180:183], v[188:191], v[48:51]
	v_mfma_f32_16x16x32_bf16 v[36:39], v[172:175], v[196:199], v[36:39]
	v_mfma_f32_16x16x32_bf16 v[32:35], v[180:183], v[196:199], v[32:35]
	s_setprio 2
	s_barrier
	v_mfma_f32_16x16x32_bf16 v[20:23], v[172:175], v[204:207], v[20:23]
	v_mfma_f32_16x16x32_bf16 v[16:19], v[180:183], v[204:207], v[16:19]
	v_mfma_f32_16x16x32_bf16 v[4:7], v[172:175], v[212:215], v[4:7]
	v_mfma_f32_16x16x32_bf16 v[0:3], v[180:183], v[212:215], v[0:3]
	s_setprio 0
	s_add_i32 s66, 0, 0x18000
	s_add_i32 s67, 0, 0x1c000
	v_add_u32_e32 v156, s66, v162
	v_add_u32_e32 v167, s67, v162
	ds_read_b128 v[144:147], v156
	ds_read_b128 v[148:151], v156 offset:1024
	ds_read_b128 v[152:155], v156 offset:2048
	ds_read_b128 v[156:159], v156 offset:3072
	ds_read_b128 v[168:171], v167
	ds_read_b128 v[172:175], v167 offset:1024
	ds_read_b128 v[176:179], v167 offset:2048
	ds_read_b128 v[180:183], v167 offset:3072
	s_add_u32 s40, s40, 0x40000
	s_addc_u32 s41, s41, 0
	s_mov_b32 m0, s54
	v_lshl_add_u64 v[222:223], s[40:41], 0, v[134:135]
	ds_read_b128 v[184:187], v165 offset:32768
	ds_read_b128 v[188:191], v165 offset:33792
	ds_read_b128 v[192:195], v165 offset:34816
	ds_read_b128 v[196:199], v165 offset:35840
	ds_read_b128 v[200:203], v165 offset:36864
	ds_read_b128 v[204:207], v165 offset:37888
	ds_read_b128 v[208:211], v165 offset:38912
	ds_read_b128 v[212:215], v165 offset:39936
	global_load_lds_dwordx4 v[222:223], off
	s_mov_b32 m0, s55
	v_lshl_add_u64 v[222:223], s[40:41], 0, v[130:131]
	global_load_lds_dwordx4 v[222:223], off
	s_waitcnt vmcnt(8)
	s_waitcnt lgkmcnt(0)
	s_barrier
	s_setprio 1
	s_waitcnt lgkmcnt(0)
	v_mfma_f32_16x16x32_bf16 v[124:127], v[144:147], v[184:187], v[124:127]
	v_mfma_f32_16x16x32_bf16 v[120:123], v[152:155], v[184:187], v[120:123]
	v_mfma_f32_16x16x32_bf16 v[108:111], v[144:147], v[192:195], v[108:111]
	v_mfma_f32_16x16x32_bf16 v[104:107], v[152:155], v[192:195], v[104:107]
	v_mfma_f32_16x16x32_bf16 v[92:95], v[144:147], v[200:203], v[92:95]
	v_mfma_f32_16x16x32_bf16 v[88:91], v[152:155], v[200:203], v[88:91]
	v_mfma_f32_16x16x32_bf16 v[76:79], v[144:147], v[208:211], v[76:79]
	v_mfma_f32_16x16x32_bf16 v[72:75], v[152:155], v[208:211], v[72:75]
	v_mfma_f32_16x16x32_bf16 v[124:127], v[148:151], v[188:191], v[124:127]
	v_mfma_f32_16x16x32_bf16 v[120:123], v[156:159], v[188:191], v[120:123]
	v_mfma_f32_16x16x32_bf16 v[108:111], v[148:151], v[196:199], v[108:111]
	v_mfma_f32_16x16x32_bf16 v[104:107], v[156:159], v[196:199], v[104:107]
	v_mfma_f32_16x16x32_bf16 v[92:95], v[148:151], v[204:207], v[92:95]
	v_mfma_f32_16x16x32_bf16 v[88:91], v[156:159], v[204:207], v[88:91]
	v_mfma_f32_16x16x32_bf16 v[76:79], v[148:151], v[212:215], v[76:79]
	v_mfma_f32_16x16x32_bf16 v[72:75], v[156:159], v[212:215], v[72:75]
	s_setprio 0
	s_setprio 1
	v_mfma_f32_16x16x32_bf16 v[116:119], v[168:171], v[184:187], v[116:119]
	v_mfma_f32_16x16x32_bf16 v[112:115], v[176:179], v[184:187], v[112:115]
	v_mfma_f32_16x16x32_bf16 v[100:103], v[168:171], v[192:195], v[100:103]
	v_mfma_f32_16x16x32_bf16 v[96:99], v[176:179], v[192:195], v[96:99]
	v_mfma_f32_16x16x32_bf16 v[84:87], v[168:171], v[200:203], v[84:87]
	v_mfma_f32_16x16x32_bf16 v[80:83], v[176:179], v[200:203], v[80:83]
	v_mfma_f32_16x16x32_bf16 v[68:71], v[168:171], v[208:211], v[68:71]
	v_mfma_f32_16x16x32_bf16 v[64:67], v[176:179], v[208:211], v[64:67]
	v_mfma_f32_16x16x32_bf16 v[116:119], v[172:175], v[188:191], v[116:119]
	v_mfma_f32_16x16x32_bf16 v[112:115], v[180:183], v[188:191], v[112:115]
	v_mfma_f32_16x16x32_bf16 v[100:103], v[172:175], v[196:199], v[100:103]
	v_mfma_f32_16x16x32_bf16 v[96:99], v[180:183], v[196:199], v[96:99]
	s_setprio 2
	s_barrier
	v_mfma_f32_16x16x32_bf16 v[84:87], v[172:175], v[204:207], v[84:87]
	v_mfma_f32_16x16x32_bf16 v[80:83], v[180:183], v[204:207], v[80:83]
	v_mfma_f32_16x16x32_bf16 v[68:71], v[172:175], v[212:215], v[68:71]
	v_mfma_f32_16x16x32_bf16 v[64:67], v[180:183], v[212:215], v[64:67]
	s_setprio 0
	s_add_i32 s40, s66, s47
	s_add_i32 m0, s40, 0xffffff80
	ds_read_b128 v[184:187], v165 offset:49152
	ds_read_b128 v[188:191], v165 offset:50176
	ds_read_b128 v[192:195], v165 offset:51200
	ds_read_b128 v[196:199], v165 offset:52224
	global_load_lds_dwordx4 v[160:161], off offset:128
	s_add_i32 m0, s40, 0x1f80
	s_add_u32 s38, s38, 0x40080
	s_addc_u32 s39, s39, 0
	s_add_i32 s40, s67, s47
	global_load_lds_dwordx4 v[216:217], off offset:128
	s_mov_b32 m0, s40
	ds_read_b128 v[200:203], v165 offset:53248
	global_load_lds_dwordx4 v132, s[38:39]
	s_add_i32 m0, s40, 0x2000
	ds_read_b128 v[204:207], v165 offset:54272
	global_load_lds_dwordx4 v128, s[38:39]
	s_add_i32 m0, s57, 0xffffff80
	ds_read_b128 v[208:211], v165 offset:55296
	global_load_lds_dwordx4 v[218:219], off offset:128
	s_add_i32 m0, s58, 0xffffff80
	ds_read_b128 v[212:215], v165 offset:56320
	global_load_lds_dwordx4 v[220:221], off offset:128
	s_waitcnt vmcnt(8)
	s_waitcnt lgkmcnt(0)
	s_barrier
	s_setprio 1
	s_waitcnt lgkmcnt(0)
	v_mfma_f32_16x16x32_bf16 v[60:63], v[144:147], v[184:187], v[60:63]
	v_mfma_f32_16x16x32_bf16 v[56:59], v[152:155], v[184:187], v[56:59]
	v_mfma_f32_16x16x32_bf16 v[44:47], v[144:147], v[192:195], v[44:47]
	v_mfma_f32_16x16x32_bf16 v[40:43], v[152:155], v[192:195], v[40:43]
	v_mfma_f32_16x16x32_bf16 v[28:31], v[144:147], v[200:203], v[28:31]
	v_mfma_f32_16x16x32_bf16 v[24:27], v[152:155], v[200:203], v[24:27]
	v_mfma_f32_16x16x32_bf16 v[12:15], v[144:147], v[208:211], v[12:15]
	v_mfma_f32_16x16x32_bf16 v[8:11], v[152:155], v[208:211], v[8:11]
	v_mfma_f32_16x16x32_bf16 v[60:63], v[148:151], v[188:191], v[60:63]
	v_mfma_f32_16x16x32_bf16 v[56:59], v[156:159], v[188:191], v[56:59]
	v_mfma_f32_16x16x32_bf16 v[44:47], v[148:151], v[196:199], v[44:47]
	v_mfma_f32_16x16x32_bf16 v[40:43], v[156:159], v[196:199], v[40:43]
	v_mfma_f32_16x16x32_bf16 v[28:31], v[148:151], v[204:207], v[28:31]
	v_mfma_f32_16x16x32_bf16 v[24:27], v[156:159], v[204:207], v[24:27]
	v_mfma_f32_16x16x32_bf16 v[12:15], v[148:151], v[212:215], v[12:15]
	v_mfma_f32_16x16x32_bf16 v[8:11], v[156:159], v[212:215], v[8:11]
	s_setprio 0
	s_setprio 1
	v_mfma_f32_16x16x32_bf16 v[52:55], v[168:171], v[184:187], v[52:55]
	v_mfma_f32_16x16x32_bf16 v[48:51], v[176:179], v[184:187], v[48:51]
	v_mfma_f32_16x16x32_bf16 v[36:39], v[168:171], v[192:195], v[36:39]
	v_mfma_f32_16x16x32_bf16 v[32:35], v[176:179], v[192:195], v[32:35]
	v_mfma_f32_16x16x32_bf16 v[20:23], v[168:171], v[200:203], v[20:23]
	v_mfma_f32_16x16x32_bf16 v[16:19], v[176:179], v[200:203], v[16:19]
	v_mfma_f32_16x16x32_bf16 v[4:7], v[168:171], v[208:211], v[4:7]
	v_mfma_f32_16x16x32_bf16 v[0:3], v[176:179], v[208:211], v[0:3]
	v_mfma_f32_16x16x32_bf16 v[52:55], v[172:175], v[188:191], v[52:55]
	v_mfma_f32_16x16x32_bf16 v[48:51], v[180:183], v[188:191], v[48:51]
	v_mfma_f32_16x16x32_bf16 v[36:39], v[172:175], v[196:199], v[36:39]
	v_mfma_f32_16x16x32_bf16 v[32:35], v[180:183], v[196:199], v[32:35]
	s_setprio 2
	s_barrier
	v_mfma_f32_16x16x32_bf16 v[20:23], v[172:175], v[204:207], v[20:23]
	v_mfma_f32_16x16x32_bf16 v[16:19], v[180:183], v[204:207], v[16:19]
	v_mfma_f32_16x16x32_bf16 v[4:7], v[172:175], v[212:215], v[4:7]
	v_mfma_f32_16x16x32_bf16 v[0:3], v[180:183], v[212:215], v[0:3]
	s_setprio 0
	s_add_i32 s65, s65, 2
	s_add_u32 s36, s36, 0x100
	s_addc_u32 s37, s37, 0
	s_add_u32 s63, s63, 0x100
	s_addc_u32 s64, s64, 0
	s_cmp_gt_u32 s65, 13
.LBB0_784:
	ds_read_b128 v[144:147], v163
	ds_read_b128 v[148:151], v163 offset:1024
	ds_read_b128 v[152:155], v163 offset:2048
	ds_read_b128 v[156:159], v163 offset:3072
	ds_read_b128 v[168:171], v164
	ds_read_b128 v[172:175], v164 offset:1024
	ds_read_b128 v[176:179], v164 offset:2048
	ds_read_b128 v[180:183], v164 offset:3072
	s_add_u32 s38, s36, 0xfffc0080
	s_addc_u32 s39, s37, -1
	s_cmp_eq_u32 s65, 12
	s_cselect_b32 s41, s23, s39
	s_cselect_b32 s40, s31, s38
	s_cselect_b32 s39, s25, s64
	s_cselect_b32 s38, s62, s63
	v_lshl_add_u64 v[160:161], s[36:37], 0, v[136:137]
	s_add_i32 m0, s50, 0xc000
	ds_read_b128 v[184:187], v165
	ds_read_b128 v[188:191], v165 offset:1024
	ds_read_b128 v[192:195], v165 offset:2048
	ds_read_b128 v[196:199], v165 offset:3072
	ds_read_b128 v[200:203], v165 offset:4096
	ds_read_b128 v[204:207], v165 offset:5120
	ds_read_b128 v[208:211], v165 offset:6144
	ds_read_b128 v[212:215], v165 offset:7168
	global_load_lds_dwordx4 v[160:161], off
	s_add_i32 m0, s50, 0xe000
	v_lshl_add_u64 v[160:161], s[36:37], 0, v[138:139]
	global_load_lds_dwordx4 v[160:161], off
	s_waitcnt vmcnt(8)
	s_waitcnt lgkmcnt(0)
	s_barrier
	s_setprio 1
	s_waitcnt lgkmcnt(0)
	v_mfma_f32_16x16x32_bf16 v[124:127], v[144:147], v[184:187], v[124:127]
	v_mfma_f32_16x16x32_bf16 v[120:123], v[152:155], v[184:187], v[120:123]
	v_mfma_f32_16x16x32_bf16 v[108:111], v[144:147], v[192:195], v[108:111]
	v_mfma_f32_16x16x32_bf16 v[104:107], v[152:155], v[192:195], v[104:107]
	v_mfma_f32_16x16x32_bf16 v[92:95], v[144:147], v[200:203], v[92:95]
	v_mfma_f32_16x16x32_bf16 v[88:91], v[152:155], v[200:203], v[88:91]
	v_mfma_f32_16x16x32_bf16 v[76:79], v[144:147], v[208:211], v[76:79]
	v_mfma_f32_16x16x32_bf16 v[72:75], v[152:155], v[208:211], v[72:75]
	v_mfma_f32_16x16x32_bf16 v[124:127], v[148:151], v[188:191], v[124:127]
	v_mfma_f32_16x16x32_bf16 v[120:123], v[156:159], v[188:191], v[120:123]
	v_mfma_f32_16x16x32_bf16 v[108:111], v[148:151], v[196:199], v[108:111]
	v_mfma_f32_16x16x32_bf16 v[104:107], v[156:159], v[196:199], v[104:107]
	v_mfma_f32_16x16x32_bf16 v[92:95], v[148:151], v[204:207], v[92:95]
	v_mfma_f32_16x16x32_bf16 v[88:91], v[156:159], v[204:207], v[88:91]
	v_mfma_f32_16x16x32_bf16 v[76:79], v[148:151], v[212:215], v[76:79]
	v_mfma_f32_16x16x32_bf16 v[72:75], v[156:159], v[212:215], v[72:75]
	s_setprio 0
	s_setprio 1
	v_mfma_f32_16x16x32_bf16 v[116:119], v[168:171], v[184:187], v[116:119]
	v_mfma_f32_16x16x32_bf16 v[112:115], v[176:179], v[184:187], v[112:115]
	v_mfma_f32_16x16x32_bf16 v[100:103], v[168:171], v[192:195], v[100:103]
	v_mfma_f32_16x16x32_bf16 v[96:99], v[176:179], v[192:195], v[96:99]
	v_mfma_f32_16x16x32_bf16 v[84:87], v[168:171], v[200:203], v[84:87]
	v_mfma_f32_16x16x32_bf16 v[80:83], v[176:179], v[200:203], v[80:83]
	v_mfma_f32_16x16x32_bf16 v[68:71], v[168:171], v[208:211], v[68:71]
	v_mfma_f32_16x16x32_bf16 v[64:67], v[176:179], v[208:211], v[64:67]
	v_mfma_f32_16x16x32_bf16 v[116:119], v[172:175], v[188:191], v[116:119]
	v_mfma_f32_16x16x32_bf16 v[112:115], v[180:183], v[188:191], v[112:115]
	v_mfma_f32_16x16x32_bf16 v[100:103], v[172:175], v[196:199], v[100:103]
	v_mfma_f32_16x16x32_bf16 v[96:99], v[180:183], v[196:199], v[96:99]
	s_setprio 2
	s_barrier
	v_mfma_f32_16x16x32_bf16 v[84:87], v[172:175], v[204:207], v[84:87]
	v_mfma_f32_16x16x32_bf16 v[80:83], v[180:183], v[204:207], v[80:83]
	v_mfma_f32_16x16x32_bf16 v[68:71], v[172:175], v[212:215], v[68:71]
	v_mfma_f32_16x16x32_bf16 v[64:67], v[180:183], v[212:215], v[64:67]
	s_setprio 0
	s_add_i32 s66, s59, s47
	v_lshl_add_u64 v[160:161], s[38:39], 0, v[132:133]
	s_mov_b32 m0, s66
	ds_read_b128 v[184:187], v165 offset:16384
	ds_read_b128 v[188:191], v165 offset:17408
	ds_read_b128 v[192:195], v165 offset:18432
	ds_read_b128 v[196:199], v165 offset:19456
	ds_read_b128 v[200:203], v165 offset:20480
	ds_read_b128 v[204:207], v165 offset:21504
	global_load_lds_dwordx4 v[160:161], off
	s_add_i32 m0, s66, 0x2000
	s_add_u32 s66, s38, 0x40000
	v_lshl_add_u64 v[216:217], s[38:39], 0, v[128:129]
	s_addc_u32 s67, s39, 0
	s_add_i32 s68, s60, s47
	global_load_lds_dwordx4 v[216:217], off
	s_mov_b32 m0, s68
	v_lshl_add_u64 v[220:221], s[40:41], 0, v[130:131]
	global_load_lds_dwordx4 v132, s[66:67]
	s_add_i32 m0, s68, 0x2000
	ds_read_b128 v[208:211], v165 offset:22528
	global_load_lds_dwordx4 v128, s[66:67]
	s_mov_b32 m0, s50
	v_lshl_add_u64 v[218:219], s[40:41], 0, v[134:135]
	global_load_lds_dwordx4 v[218:219], off
	s_mov_b32 m0, s51
	ds_read_b128 v[212:215], v165 offset:23552
	global_load_lds_dwordx4 v[220:221], off
	s_waitcnt vmcnt(8)
	s_waitcnt lgkmcnt(0)
	s_barrier
	s_setprio 1
	s_waitcnt lgkmcnt(0)
	v_mfma_f32_16x16x32_bf16 v[60:63], v[144:147], v[184:187], v[60:63]
	v_mfma_f32_16x16x32_bf16 v[56:59], v[152:155], v[184:187], v[56:59]
	v_mfma_f32_16x16x32_bf16 v[44:47], v[144:147], v[192:195], v[44:47]
	v_mfma_f32_16x16x32_bf16 v[40:43], v[152:155], v[192:195], v[40:43]
	v_mfma_f32_16x16x32_bf16 v[28:31], v[144:147], v[200:203], v[28:31]
	v_mfma_f32_16x16x32_bf16 v[24:27], v[152:155], v[200:203], v[24:27]
	v_mfma_f32_16x16x32_bf16 v[12:15], v[144:147], v[208:211], v[12:15]
	v_mfma_f32_16x16x32_bf16 v[8:11], v[152:155], v[208:211], v[8:11]
	v_mfma_f32_16x16x32_bf16 v[60:63], v[148:151], v[188:191], v[60:63]
	v_mfma_f32_16x16x32_bf16 v[56:59], v[156:159], v[188:191], v[56:59]
	v_mfma_f32_16x16x32_bf16 v[44:47], v[148:151], v[196:199], v[44:47]
	v_mfma_f32_16x16x32_bf16 v[40:43], v[156:159], v[196:199], v[40:43]
	v_mfma_f32_16x16x32_bf16 v[28:31], v[148:151], v[204:207], v[28:31]
	v_mfma_f32_16x16x32_bf16 v[24:27], v[156:159], v[204:207], v[24:27]
	v_mfma_f32_16x16x32_bf16 v[12:15], v[148:151], v[212:215], v[12:15]
	v_mfma_f32_16x16x32_bf16 v[8:11], v[156:159], v[212:215], v[8:11]
	s_setprio 0
	s_setprio 1
	v_mfma_f32_16x16x32_bf16 v[52:55], v[168:171], v[184:187], v[52:55]
	v_mfma_f32_16x16x32_bf16 v[48:51], v[176:179], v[184:187], v[48:51]
	v_mfma_f32_16x16x32_bf16 v[36:39], v[168:171], v[192:195], v[36:39]
	v_mfma_f32_16x16x32_bf16 v[32:35], v[176:179], v[192:195], v[32:35]
	v_mfma_f32_16x16x32_bf16 v[20:23], v[168:171], v[200:203], v[20:23]
	v_mfma_f32_16x16x32_bf16 v[16:19], v[176:179], v[200:203], v[16:19]
	v_mfma_f32_16x16x32_bf16 v[4:7], v[168:171], v[208:211], v[4:7]
	v_mfma_f32_16x16x32_bf16 v[0:3], v[176:179], v[208:211], v[0:3]
	v_mfma_f32_16x16x32_bf16 v[52:55], v[172:175], v[188:191], v[52:55]
	v_mfma_f32_16x16x32_bf16 v[48:51], v[180:183], v[188:191], v[48:51]
	v_mfma_f32_16x16x32_bf16 v[36:39], v[172:175], v[196:199], v[36:39]
	v_mfma_f32_16x16x32_bf16 v[32:35], v[180:183], v[196:199], v[32:35]
	s_setprio 2
	s_barrier
	v_mfma_f32_16x16x32_bf16 v[20:23], v[172:175], v[204:207], v[20:23]
	v_mfma_f32_16x16x32_bf16 v[16:19], v[180:183], v[204:207], v[16:19]
	v_mfma_f32_16x16x32_bf16 v[4:7], v[172:175], v[212:215], v[4:7]
	v_mfma_f32_16x16x32_bf16 v[0:3], v[180:183], v[212:215], v[0:3]
	s_setprio 0
	s_add_i32 s66, 0, 0x18000
	s_add_i32 s67, 0, 0x1c000
	v_add_u32_e32 v156, s66, v162
	v_add_u32_e32 v167, s67, v162
	ds_read_b128 v[144:147], v156
	ds_read_b128 v[148:151], v156 offset:1024
	ds_read_b128 v[152:155], v156 offset:2048
	ds_read_b128 v[156:159], v156 offset:3072
	ds_read_b128 v[168:171], v167
	ds_read_b128 v[172:175], v167 offset:1024
	ds_read_b128 v[176:179], v167 offset:2048
	ds_read_b128 v[180:183], v167 offset:3072
	s_add_u32 s40, s40, 0x40000
	s_addc_u32 s41, s41, 0
	s_mov_b32 m0, s54
	v_lshl_add_u64 v[222:223], s[40:41], 0, v[134:135]
	ds_read_b128 v[184:187], v165 offset:32768
	ds_read_b128 v[188:191], v165 offset:33792
	ds_read_b128 v[192:195], v165 offset:34816
	ds_read_b128 v[196:199], v165 offset:35840
	ds_read_b128 v[200:203], v165 offset:36864
	ds_read_b128 v[204:207], v165 offset:37888
	ds_read_b128 v[208:211], v165 offset:38912
	ds_read_b128 v[212:215], v165 offset:39936
	global_load_lds_dwordx4 v[222:223], off
	s_mov_b32 m0, s55
	v_lshl_add_u64 v[222:223], s[40:41], 0, v[130:131]
	global_load_lds_dwordx4 v[222:223], off
	s_waitcnt vmcnt(8)
	s_waitcnt lgkmcnt(0)
	s_barrier
	s_setprio 1
	s_waitcnt lgkmcnt(0)
	v_mfma_f32_16x16x32_bf16 v[124:127], v[144:147], v[184:187], v[124:127]
	v_mfma_f32_16x16x32_bf16 v[120:123], v[152:155], v[184:187], v[120:123]
	v_mfma_f32_16x16x32_bf16 v[108:111], v[144:147], v[192:195], v[108:111]
	v_mfma_f32_16x16x32_bf16 v[104:107], v[152:155], v[192:195], v[104:107]
	v_mfma_f32_16x16x32_bf16 v[92:95], v[144:147], v[200:203], v[92:95]
	v_mfma_f32_16x16x32_bf16 v[88:91], v[152:155], v[200:203], v[88:91]
	v_mfma_f32_16x16x32_bf16 v[76:79], v[144:147], v[208:211], v[76:79]
	v_mfma_f32_16x16x32_bf16 v[72:75], v[152:155], v[208:211], v[72:75]
	v_mfma_f32_16x16x32_bf16 v[124:127], v[148:151], v[188:191], v[124:127]
	v_mfma_f32_16x16x32_bf16 v[120:123], v[156:159], v[188:191], v[120:123]
	v_mfma_f32_16x16x32_bf16 v[108:111], v[148:151], v[196:199], v[108:111]
	v_mfma_f32_16x16x32_bf16 v[104:107], v[156:159], v[196:199], v[104:107]
	v_mfma_f32_16x16x32_bf16 v[92:95], v[148:151], v[204:207], v[92:95]
	v_mfma_f32_16x16x32_bf16 v[88:91], v[156:159], v[204:207], v[88:91]
	v_mfma_f32_16x16x32_bf16 v[76:79], v[148:151], v[212:215], v[76:79]
	v_mfma_f32_16x16x32_bf16 v[72:75], v[156:159], v[212:215], v[72:75]
	s_setprio 0
	s_setprio 1
	v_mfma_f32_16x16x32_bf16 v[116:119], v[168:171], v[184:187], v[116:119]
	v_mfma_f32_16x16x32_bf16 v[112:115], v[176:179], v[184:187], v[112:115]
	v_mfma_f32_16x16x32_bf16 v[100:103], v[168:171], v[192:195], v[100:103]
	v_mfma_f32_16x16x32_bf16 v[96:99], v[176:179], v[192:195], v[96:99]
	v_mfma_f32_16x16x32_bf16 v[84:87], v[168:171], v[200:203], v[84:87]
	v_mfma_f32_16x16x32_bf16 v[80:83], v[176:179], v[200:203], v[80:83]
	v_mfma_f32_16x16x32_bf16 v[68:71], v[168:171], v[208:211], v[68:71]
	v_mfma_f32_16x16x32_bf16 v[64:67], v[176:179], v[208:211], v[64:67]
	v_mfma_f32_16x16x32_bf16 v[116:119], v[172:175], v[188:191], v[116:119]
	v_mfma_f32_16x16x32_bf16 v[112:115], v[180:183], v[188:191], v[112:115]
	v_mfma_f32_16x16x32_bf16 v[100:103], v[172:175], v[196:199], v[100:103]
	v_mfma_f32_16x16x32_bf16 v[96:99], v[180:183], v[196:199], v[96:99]
	s_setprio 2
	s_barrier
	v_mfma_f32_16x16x32_bf16 v[84:87], v[172:175], v[204:207], v[84:87]
	v_mfma_f32_16x16x32_bf16 v[80:83], v[180:183], v[204:207], v[80:83]
	v_mfma_f32_16x16x32_bf16 v[68:71], v[172:175], v[212:215], v[68:71]
	v_mfma_f32_16x16x32_bf16 v[64:67], v[180:183], v[212:215], v[64:67]
	s_setprio 0
	s_add_i32 s40, s66, s47
	s_add_i32 m0, s40, 0xffffff80
	ds_read_b128 v[184:187], v165 offset:49152
	ds_read_b128 v[188:191], v165 offset:50176
	ds_read_b128 v[192:195], v165 offset:51200
	ds_read_b128 v[196:199], v165 offset:52224
	ds_read_b128 v[200:203], v165 offset:53248
	global_load_lds_dwordx4 v[160:161], off offset:128
	s_add_i32 m0, s40, 0x1f80
	s_add_u32 s38, s38, 0x40080
	s_addc_u32 s39, s39, 0
	s_add_i32 s40, s67, s47
	global_load_lds_dwordx4 v[216:217], off offset:128
	s_mov_b32 m0, s40
	ds_read_b128 v[204:207], v165 offset:54272
	global_load_lds_dwordx4 v132, s[38:39]
	s_add_i32 m0, s40, 0x2000
	ds_read_b128 v[208:211], v165 offset:55296
	global_load_lds_dwordx4 v128, s[38:39]
	s_add_i32 m0, s57, 0xffffff80
	ds_read_b128 v[212:215], v165 offset:56320
	global_load_lds_dwordx4 v[218:219], off offset:128
	s_mov_b32 m0, s58
	v_lshl_add_u64 v[160:161], v[220:221], 0, s[16:17]
	global_load_lds_dwordx4 v[160:161], off
	s_waitcnt vmcnt(8)
	s_waitcnt lgkmcnt(0)
	s_barrier
	s_setprio 1
	s_waitcnt lgkmcnt(0)
	v_mfma_f32_16x16x32_bf16 v[60:63], v[144:147], v[184:187], v[60:63]
	v_mfma_f32_16x16x32_bf16 v[56:59], v[152:155], v[184:187], v[56:59]
	v_mfma_f32_16x16x32_bf16 v[44:47], v[144:147], v[192:195], v[44:47]
	v_mfma_f32_16x16x32_bf16 v[40:43], v[152:155], v[192:195], v[40:43]
	v_mfma_f32_16x16x32_bf16 v[28:31], v[144:147], v[200:203], v[28:31]
	v_mfma_f32_16x16x32_bf16 v[24:27], v[152:155], v[200:203], v[24:27]
	v_mfma_f32_16x16x32_bf16 v[12:15], v[144:147], v[208:211], v[12:15]
	v_mfma_f32_16x16x32_bf16 v[8:11], v[152:155], v[208:211], v[8:11]
	v_mfma_f32_16x16x32_bf16 v[60:63], v[148:151], v[188:191], v[60:63]
	v_mfma_f32_16x16x32_bf16 v[56:59], v[156:159], v[188:191], v[56:59]
	v_mfma_f32_16x16x32_bf16 v[44:47], v[148:151], v[196:199], v[44:47]
	v_mfma_f32_16x16x32_bf16 v[40:43], v[156:159], v[196:199], v[40:43]
	v_mfma_f32_16x16x32_bf16 v[28:31], v[148:151], v[204:207], v[28:31]
	v_mfma_f32_16x16x32_bf16 v[24:27], v[156:159], v[204:207], v[24:27]
	v_mfma_f32_16x16x32_bf16 v[12:15], v[148:151], v[212:215], v[12:15]
	v_mfma_f32_16x16x32_bf16 v[8:11], v[156:159], v[212:215], v[8:11]
	s_setprio 0
	s_setprio 1
	v_mfma_f32_16x16x32_bf16 v[52:55], v[168:171], v[184:187], v[52:55]
	v_mfma_f32_16x16x32_bf16 v[48:51], v[176:179], v[184:187], v[48:51]
	v_mfma_f32_16x16x32_bf16 v[36:39], v[168:171], v[192:195], v[36:39]
	v_mfma_f32_16x16x32_bf16 v[32:35], v[176:179], v[192:195], v[32:35]
	v_mfma_f32_16x16x32_bf16 v[20:23], v[168:171], v[200:203], v[20:23]
	v_mfma_f32_16x16x32_bf16 v[16:19], v[176:179], v[200:203], v[16:19]
	v_mfma_f32_16x16x32_bf16 v[4:7], v[168:171], v[208:211], v[4:7]
	v_mfma_f32_16x16x32_bf16 v[0:3], v[176:179], v[208:211], v[0:3]
	v_mfma_f32_16x16x32_bf16 v[52:55], v[172:175], v[188:191], v[52:55]
	v_mfma_f32_16x16x32_bf16 v[48:51], v[180:183], v[188:191], v[48:51]
	v_mfma_f32_16x16x32_bf16 v[36:39], v[172:175], v[196:199], v[36:39]
	v_mfma_f32_16x16x32_bf16 v[32:35], v[180:183], v[196:199], v[32:35]
	s_setprio 2
	s_barrier
	v_mfma_f32_16x16x32_bf16 v[20:23], v[172:175], v[204:207], v[20:23]
	v_mfma_f32_16x16x32_bf16 v[16:19], v[180:183], v[204:207], v[16:19]
	v_mfma_f32_16x16x32_bf16 v[4:7], v[172:175], v[212:215], v[4:7]
	v_mfma_f32_16x16x32_bf16 v[0:3], v[180:183], v[212:215], v[0:3]
	s_setprio 0
	s_add_i32 s65, s65, 2
	s_add_u32 s36, s36, 0x100
	s_addc_u32 s37, s37, 0
	s_add_u32 s63, s63, 0x100
	s_addc_u32 s64, s64, 0
	s_cmp_gt_u32 s65, 13
	s_cbranch_scc0 .LBB0_784

.LBB0_865:
	s_add_u32 s62, s28, 0x100
	s_addc_u32 s63, s29, 0
	s_mov_b32 s64, -2
	ds_read_b128 v[120:123], v233
	ds_read_b128 v[124:127], v233 offset:1024
	ds_read_b128 v[136:139], v233 offset:2048
	ds_read_b128 v[140:143], v233 offset:3072
	ds_read_b128 v[144:147], v234
	ds_read_b128 v[148:151], v234 offset:1024
	ds_read_b128 v[152:155], v234 offset:2048
	ds_read_b128 v[156:159], v234 offset:3072
	s_add_u32 s28, s26, 0x100
	s_addc_u32 s29, s27, 0
	s_cmp_eq_u32 s64, 40
	s_cselect_b32 s37, s7, s29
	s_cselect_b32 s36, s6, s28
	s_cselect_b32 s31, s25, s63
	s_cselect_b32 s30, s24, s62
	v_lshl_add_u64 v[208:209], s[26:27], 0, v[192:193]
	s_add_i32 m0, s44, 0xc000
	ds_read_b128 v[160:163], v235
	ds_read_b128 v[164:167], v235 offset:1024
	ds_read_b128 v[168:171], v235 offset:2048
	ds_read_b128 v[172:175], v235 offset:3072
	ds_read_b128 v[176:179], v235 offset:4096
	ds_read_b128 v[180:183], v235 offset:5120
	ds_read_b128 v[200:203], v235 offset:6144
	ds_read_b128 v[204:207], v235 offset:7168
	global_load_lds_dwordx4 v[208:209], off
	s_add_i32 m0, s44, 0xe000
	v_lshl_add_u64 v[208:209], s[26:27], 0, v[194:195]
	global_load_lds_dwordx4 v[208:209], off
	s_waitcnt vmcnt(8)
	s_waitcnt lgkmcnt(0)
	s_barrier
	s_setprio 1
	s_waitcnt lgkmcnt(0)
	v_mfma_f32_16x16x32_bf16 v[132:135], v[120:123], v[160:163], 0
	v_mfma_f32_16x16x32_bf16 v[128:131], v[136:139], v[160:163], 0
	v_mfma_f32_16x16x32_bf16 v[108:111], v[120:123], v[168:171], 0
	v_mfma_f32_16x16x32_bf16 v[104:107], v[136:139], v[168:171], 0
	v_mfma_f32_16x16x32_bf16 v[92:95], v[120:123], v[176:179], 0
	v_mfma_f32_16x16x32_bf16 v[88:91], v[136:139], v[176:179], 0
	v_mfma_f32_16x16x32_bf16 v[76:79], v[120:123], v[200:203], 0
	v_mfma_f32_16x16x32_bf16 v[72:75], v[136:139], v[200:203], 0
	v_mfma_f32_16x16x32_bf16 v[132:135], v[124:127], v[164:167], v[132:135]
	v_mfma_f32_16x16x32_bf16 v[128:131], v[140:143], v[164:167], v[128:131]
	v_mfma_f32_16x16x32_bf16 v[108:111], v[124:127], v[172:175], v[108:111]
	v_mfma_f32_16x16x32_bf16 v[104:107], v[140:143], v[172:175], v[104:107]
	v_mfma_f32_16x16x32_bf16 v[92:95], v[124:127], v[180:183], v[92:95]
	v_mfma_f32_16x16x32_bf16 v[88:91], v[140:143], v[180:183], v[88:91]
	v_mfma_f32_16x16x32_bf16 v[76:79], v[124:127], v[204:207], v[76:79]
	v_mfma_f32_16x16x32_bf16 v[72:75], v[140:143], v[204:207], v[72:75]
	s_setprio 0
	s_setprio 1
	v_mfma_f32_16x16x32_bf16 v[116:119], v[144:147], v[160:163], 0
	v_mfma_f32_16x16x32_bf16 v[112:115], v[152:155], v[160:163], 0
	v_mfma_f32_16x16x32_bf16 v[100:103], v[144:147], v[168:171], 0
	v_mfma_f32_16x16x32_bf16 v[96:99], v[152:155], v[168:171], 0
	v_mfma_f32_16x16x32_bf16 v[84:87], v[144:147], v[176:179], 0
	v_mfma_f32_16x16x32_bf16 v[80:83], v[152:155], v[176:179], 0
	v_mfma_f32_16x16x32_bf16 v[68:71], v[144:147], v[200:203], 0
	v_mfma_f32_16x16x32_bf16 v[64:67], v[152:155], v[200:203], 0
	v_mfma_f32_16x16x32_bf16 v[116:119], v[148:151], v[164:167], v[116:119]
	v_mfma_f32_16x16x32_bf16 v[112:115], v[156:159], v[164:167], v[112:115]
	v_mfma_f32_16x16x32_bf16 v[100:103], v[148:151], v[172:175], v[100:103]
	v_mfma_f32_16x16x32_bf16 v[96:99], v[156:159], v[172:175], v[96:99]
	s_setprio 2
	s_barrier
	v_mfma_f32_16x16x32_bf16 v[84:87], v[148:151], v[180:183], v[84:87]
	v_mfma_f32_16x16x32_bf16 v[80:83], v[156:159], v[180:183], v[80:83]
	v_mfma_f32_16x16x32_bf16 v[68:71], v[148:151], v[204:207], v[68:71]
	v_mfma_f32_16x16x32_bf16 v[64:67], v[156:159], v[204:207], v[64:67]
	s_setprio 0
	s_add_i32 s26, s56, s43
	v_lshl_add_u64 v[208:209], s[30:31], 0, v[186:187]
	s_mov_b32 m0, s26
	ds_read_b128 v[160:163], v235 offset:16384
	ds_read_b128 v[164:167], v235 offset:17408
	ds_read_b128 v[168:171], v235 offset:18432
	ds_read_b128 v[172:175], v235 offset:19456
	ds_read_b128 v[176:179], v235 offset:20480
	ds_read_b128 v[180:183], v235 offset:21504
	global_load_lds_dwordx4 v[208:209], off
	s_add_i32 m0, s26, 0x2000
	s_add_u32 s26, s30, 0xb0000
	v_lshl_add_u64 v[210:211], s[30:31], 0, v[190:191]
	s_addc_u32 s27, s31, 0
	s_add_i32 s65, s57, s43
	global_load_lds_dwordx4 v[210:211], off
	s_mov_b32 m0, s65
	v_lshl_add_u64 v[214:215], s[36:37], 0, v[188:189]
	global_load_lds_dwordx4 v186, s[26:27]
	s_add_i32 m0, s65, 0x2000
	ds_read_b128 v[200:203], v235 offset:22528
	global_load_lds_dwordx4 v190, s[26:27]
	s_mov_b32 m0, s44
	v_lshl_add_u64 v[212:213], s[36:37], 0, v[184:185]
	global_load_lds_dwordx4 v[212:213], off
	s_mov_b32 m0, s45
	ds_read_b128 v[204:207], v235 offset:23552
	global_load_lds_dwordx4 v[214:215], off
	s_waitcnt vmcnt(8)
	s_waitcnt lgkmcnt(0)
	s_barrier
	s_setprio 1
	s_waitcnt lgkmcnt(0)
	v_mfma_f32_16x16x32_bf16 v[60:63], v[120:123], v[160:163], 0
	v_mfma_f32_16x16x32_bf16 v[56:59], v[136:139], v[160:163], 0
	v_mfma_f32_16x16x32_bf16 v[44:47], v[120:123], v[168:171], 0
	v_mfma_f32_16x16x32_bf16 v[40:43], v[136:139], v[168:171], 0
	v_mfma_f32_16x16x32_bf16 v[28:31], v[120:123], v[176:179], 0
	v_mfma_f32_16x16x32_bf16 v[24:27], v[136:139], v[176:179], 0
	v_mfma_f32_16x16x32_bf16 v[12:15], v[120:123], v[200:203], 0
	v_mfma_f32_16x16x32_bf16 v[8:11], v[136:139], v[200:203], 0
	v_mfma_f32_16x16x32_bf16 v[60:63], v[124:127], v[164:167], v[60:63]
	v_mfma_f32_16x16x32_bf16 v[56:59], v[140:143], v[164:167], v[56:59]
	v_mfma_f32_16x16x32_bf16 v[44:47], v[124:127], v[172:175], v[44:47]
	v_mfma_f32_16x16x32_bf16 v[40:43], v[140:143], v[172:175], v[40:43]
	v_mfma_f32_16x16x32_bf16 v[28:31], v[124:127], v[180:183], v[28:31]
	v_mfma_f32_16x16x32_bf16 v[24:27], v[140:143], v[180:183], v[24:27]
	v_mfma_f32_16x16x32_bf16 v[12:15], v[124:127], v[204:207], v[12:15]
	v_mfma_f32_16x16x32_bf16 v[8:11], v[140:143], v[204:207], v[8:11]
	s_setprio 0
	s_setprio 1
	v_mfma_f32_16x16x32_bf16 v[52:55], v[144:147], v[160:163], 0
	v_mfma_f32_16x16x32_bf16 v[48:51], v[152:155], v[160:163], 0
	v_mfma_f32_16x16x32_bf16 v[36:39], v[144:147], v[168:171], 0
	v_mfma_f32_16x16x32_bf16 v[32:35], v[152:155], v[168:171], 0
	v_mfma_f32_16x16x32_bf16 v[20:23], v[144:147], v[176:179], 0
	v_mfma_f32_16x16x32_bf16 v[16:19], v[152:155], v[176:179], 0
	v_mfma_f32_16x16x32_bf16 v[4:7], v[144:147], v[200:203], 0
	v_mfma_f32_16x16x32_bf16 v[0:3], v[152:155], v[200:203], 0
	v_mfma_f32_16x16x32_bf16 v[52:55], v[148:151], v[164:167], v[52:55]
	v_mfma_f32_16x16x32_bf16 v[48:51], v[156:159], v[164:167], v[48:51]
	v_mfma_f32_16x16x32_bf16 v[36:39], v[148:151], v[172:175], v[36:39]
	v_mfma_f32_16x16x32_bf16 v[32:35], v[156:159], v[172:175], v[32:35]
	s_setprio 2
	s_barrier
	v_mfma_f32_16x16x32_bf16 v[20:23], v[148:151], v[180:183], v[20:23]
	v_mfma_f32_16x16x32_bf16 v[16:19], v[156:159], v[180:183], v[16:19]
	v_mfma_f32_16x16x32_bf16 v[4:7], v[148:151], v[204:207], v[4:7]
	v_mfma_f32_16x16x32_bf16 v[0:3], v[156:159], v[204:207], v[0:3]
	s_setprio 0
	s_add_i32 s65, 0, 0x18000
	s_add_i32 s66, 0, 0x1c000
	v_add_u32_e32 v140, s65, v232
	v_add_u32_e32 v156, s66, v232
	ds_read_b128 v[120:123], v140
	ds_read_b128 v[124:127], v140 offset:1024
	ds_read_b128 v[136:139], v140 offset:2048
	ds_read_b128 v[140:143], v140 offset:3072
	ds_read_b128 v[144:147], v156
	ds_read_b128 v[148:151], v156 offset:1024
	ds_read_b128 v[152:155], v156 offset:2048
	ds_read_b128 v[156:159], v156 offset:3072
	s_add_u32 s26, s36, 0xb0000
	s_addc_u32 s27, s37, 0
	s_mov_b32 m0, s46
	v_lshl_add_u64 v[216:217], s[26:27], 0, v[184:185]
	ds_read_b128 v[160:163], v235 offset:32768
	ds_read_b128 v[164:167], v235 offset:33792
	ds_read_b128 v[168:171], v235 offset:34816
	ds_read_b128 v[172:175], v235 offset:35840
	ds_read_b128 v[176:179], v235 offset:36864
	ds_read_b128 v[180:183], v235 offset:37888
	ds_read_b128 v[200:203], v235 offset:38912
	ds_read_b128 v[204:207], v235 offset:39936
	global_load_lds_dwordx4 v[216:217], off
	s_mov_b32 m0, s47
	v_lshl_add_u64 v[216:217], s[26:27], 0, v[188:189]
	global_load_lds_dwordx4 v[216:217], off
	s_waitcnt vmcnt(8)
	s_waitcnt lgkmcnt(0)
	s_barrier
	s_setprio 1
	s_waitcnt lgkmcnt(0)
	v_mfma_f32_16x16x32_bf16 v[132:135], v[120:123], v[160:163], v[132:135]
	v_mfma_f32_16x16x32_bf16 v[128:131], v[136:139], v[160:163], v[128:131]
	v_mfma_f32_16x16x32_bf16 v[108:111], v[120:123], v[168:171], v[108:111]
	v_mfma_f32_16x16x32_bf16 v[104:107], v[136:139], v[168:171], v[104:107]
	v_mfma_f32_16x16x32_bf16 v[92:95], v[120:123], v[176:179], v[92:95]
	v_mfma_f32_16x16x32_bf16 v[88:91], v[136:139], v[176:179], v[88:91]
	v_mfma_f32_16x16x32_bf16 v[76:79], v[120:123], v[200:203], v[76:79]
	v_mfma_f32_16x16x32_bf16 v[72:75], v[136:139], v[200:203], v[72:75]
	v_mfma_f32_16x16x32_bf16 v[132:135], v[124:127], v[164:167], v[132:135]
	v_mfma_f32_16x16x32_bf16 v[128:131], v[140:143], v[164:167], v[128:131]
	v_mfma_f32_16x16x32_bf16 v[108:111], v[124:127], v[172:175], v[108:111]
	v_mfma_f32_16x16x32_bf16 v[104:107], v[140:143], v[172:175], v[104:107]
	v_mfma_f32_16x16x32_bf16 v[92:95], v[124:127], v[180:183], v[92:95]
	v_mfma_f32_16x16x32_bf16 v[88:91], v[140:143], v[180:183], v[88:91]
	v_mfma_f32_16x16x32_bf16 v[76:79], v[124:127], v[204:207], v[76:79]
	v_mfma_f32_16x16x32_bf16 v[72:75], v[140:143], v[204:207], v[72:75]
	s_setprio 0
	s_setprio 1
	v_mfma_f32_16x16x32_bf16 v[116:119], v[144:147], v[160:163], v[116:119]
	v_mfma_f32_16x16x32_bf16 v[112:115], v[152:155], v[160:163], v[112:115]
	v_mfma_f32_16x16x32_bf16 v[100:103], v[144:147], v[168:171], v[100:103]
	v_mfma_f32_16x16x32_bf16 v[96:99], v[152:155], v[168:171], v[96:99]
	v_mfma_f32_16x16x32_bf16 v[84:87], v[144:147], v[176:179], v[84:87]
	v_mfma_f32_16x16x32_bf16 v[80:83], v[152:155], v[176:179], v[80:83]
	v_mfma_f32_16x16x32_bf16 v[68:71], v[144:147], v[200:203], v[68:71]
	v_mfma_f32_16x16x32_bf16 v[64:67], v[152:155], v[200:203], v[64:67]
	v_mfma_f32_16x16x32_bf16 v[116:119], v[148:151], v[164:167], v[116:119]
	v_mfma_f32_16x16x32_bf16 v[112:115], v[156:159], v[164:167], v[112:115]
	v_mfma_f32_16x16x32_bf16 v[100:103], v[148:151], v[172:175], v[100:103]
	v_mfma_f32_16x16x32_bf16 v[96:99], v[156:159], v[172:175], v[96:99]
	s_setprio 2
	s_barrier
	v_mfma_f32_16x16x32_bf16 v[84:87], v[148:151], v[180:183], v[84:87]
	v_mfma_f32_16x16x32_bf16 v[80:83], v[156:159], v[180:183], v[80:83]
	v_mfma_f32_16x16x32_bf16 v[68:71], v[148:151], v[204:207], v[68:71]
	v_mfma_f32_16x16x32_bf16 v[64:67], v[156:159], v[204:207], v[64:67]
	s_setprio 0
	s_add_i32 s26, s65, s43
	s_add_i32 m0, s26, 0xffffff80
	ds_read_b128 v[160:163], v235 offset:49152
	ds_read_b128 v[164:167], v235 offset:50176
	ds_read_b128 v[168:171], v235 offset:51200
	ds_read_b128 v[172:175], v235 offset:52224
	global_load_lds_dwordx4 v[208:209], off offset:128
	s_add_i32 m0, s26, 0x1f80
	s_add_u32 s26, s30, 0xb0080
	s_addc_u32 s27, s31, 0
	s_add_i32 s30, s66, s43
	global_load_lds_dwordx4 v[210:211], off offset:128
	s_mov_b32 m0, s30
	ds_read_b128 v[176:179], v235 offset:53248
	global_load_lds_dwordx4 v186, s[26:27]
	s_add_i32 m0, s30, 0x2000
	ds_read_b128 v[180:183], v235 offset:54272
	global_load_lds_dwordx4 v190, s[26:27]
	s_add_i32 m0, s49, 0xffffff80
	ds_read_b128 v[200:203], v235 offset:55296
	global_load_lds_dwordx4 v[212:213], off offset:128
	s_add_i32 m0, s50, 0xffffff80
	ds_read_b128 v[204:207], v235 offset:56320
	global_load_lds_dwordx4 v[214:215], off offset:128
	s_waitcnt vmcnt(8)
	s_waitcnt lgkmcnt(0)
	s_barrier
	s_setprio 1
	s_waitcnt lgkmcnt(0)
	v_mfma_f32_16x16x32_bf16 v[60:63], v[120:123], v[160:163], v[60:63]
	v_mfma_f32_16x16x32_bf16 v[56:59], v[136:139], v[160:163], v[56:59]
	v_mfma_f32_16x16x32_bf16 v[44:47], v[120:123], v[168:171], v[44:47]
	v_mfma_f32_16x16x32_bf16 v[40:43], v[136:139], v[168:171], v[40:43]
	v_mfma_f32_16x16x32_bf16 v[28:31], v[120:123], v[176:179], v[28:31]
	v_mfma_f32_16x16x32_bf16 v[24:27], v[136:139], v[176:179], v[24:27]
	v_mfma_f32_16x16x32_bf16 v[12:15], v[120:123], v[200:203], v[12:15]
	v_mfma_f32_16x16x32_bf16 v[8:11], v[136:139], v[200:203], v[8:11]
	v_mfma_f32_16x16x32_bf16 v[60:63], v[124:127], v[164:167], v[60:63]
	v_mfma_f32_16x16x32_bf16 v[56:59], v[140:143], v[164:167], v[56:59]
	v_mfma_f32_16x16x32_bf16 v[44:47], v[124:127], v[172:175], v[44:47]
	v_mfma_f32_16x16x32_bf16 v[40:43], v[140:143], v[172:175], v[40:43]
	v_mfma_f32_16x16x32_bf16 v[28:31], v[124:127], v[180:183], v[28:31]
	v_mfma_f32_16x16x32_bf16 v[24:27], v[140:143], v[180:183], v[24:27]
	v_mfma_f32_16x16x32_bf16 v[12:15], v[124:127], v[204:207], v[12:15]
	v_mfma_f32_16x16x32_bf16 v[8:11], v[140:143], v[204:207], v[8:11]
	s_setprio 0
	s_setprio 1
	v_mfma_f32_16x16x32_bf16 v[52:55], v[144:147], v[160:163], v[52:55]
	v_mfma_f32_16x16x32_bf16 v[48:51], v[152:155], v[160:163], v[48:51]
	v_mfma_f32_16x16x32_bf16 v[36:39], v[144:147], v[168:171], v[36:39]
	v_mfma_f32_16x16x32_bf16 v[32:35], v[152:155], v[168:171], v[32:35]
	v_mfma_f32_16x16x32_bf16 v[20:23], v[144:147], v[176:179], v[20:23]
	v_mfma_f32_16x16x32_bf16 v[16:19], v[152:155], v[176:179], v[16:19]
	v_mfma_f32_16x16x32_bf16 v[4:7], v[144:147], v[200:203], v[4:7]
	v_mfma_f32_16x16x32_bf16 v[0:3], v[152:155], v[200:203], v[0:3]
	v_mfma_f32_16x16x32_bf16 v[52:55], v[148:151], v[164:167], v[52:55]
	v_mfma_f32_16x16x32_bf16 v[48:51], v[156:159], v[164:167], v[48:51]
	v_mfma_f32_16x16x32_bf16 v[36:39], v[148:151], v[172:175], v[36:39]
	v_mfma_f32_16x16x32_bf16 v[32:35], v[156:159], v[172:175], v[32:35]
	s_setprio 2
	s_barrier
	v_mfma_f32_16x16x32_bf16 v[20:23], v[148:151], v[180:183], v[20:23]
	v_mfma_f32_16x16x32_bf16 v[16:19], v[156:159], v[180:183], v[16:19]
	v_mfma_f32_16x16x32_bf16 v[4:7], v[148:151], v[204:207], v[4:7]
	v_mfma_f32_16x16x32_bf16 v[0:3], v[156:159], v[204:207], v[0:3]
	s_setprio 0
	s_add_i32 s64, s64, 2
	s_add_u32 s62, s62, 0x100
	s_addc_u32 s63, s63, 0
	s_cmp_gt_u32 s64, 41
	s_mov_b64 s[26:27], s[28:29]
.LBB0_866:
	ds_read_b128 v[120:123], v233
	ds_read_b128 v[124:127], v233 offset:1024
	ds_read_b128 v[136:139], v233 offset:2048
	ds_read_b128 v[140:143], v233 offset:3072
	ds_read_b128 v[144:147], v234
	ds_read_b128 v[148:151], v234 offset:1024
	ds_read_b128 v[152:155], v234 offset:2048
	ds_read_b128 v[156:159], v234 offset:3072
	s_add_u32 s28, s26, 0x100
	s_addc_u32 s29, s27, 0
	s_cmp_eq_u32 s64, 40
	s_cselect_b32 s37, s7, s29
	s_cselect_b32 s36, s6, s28
	s_cselect_b32 s31, s25, s63
	s_cselect_b32 s30, s24, s62
	v_lshl_add_u64 v[208:209], s[26:27], 0, v[192:193]
	s_add_i32 m0, s44, 0xc000
	ds_read_b128 v[160:163], v235
	ds_read_b128 v[164:167], v235 offset:1024
	ds_read_b128 v[168:171], v235 offset:2048
	ds_read_b128 v[172:175], v235 offset:3072
	ds_read_b128 v[176:179], v235 offset:4096
	ds_read_b128 v[180:183], v235 offset:5120
	ds_read_b128 v[200:203], v235 offset:6144
	ds_read_b128 v[204:207], v235 offset:7168
	global_load_lds_dwordx4 v[208:209], off
	s_add_i32 m0, s44, 0xe000
	v_lshl_add_u64 v[208:209], s[26:27], 0, v[194:195]
	global_load_lds_dwordx4 v[208:209], off
	s_waitcnt vmcnt(8)
	s_waitcnt lgkmcnt(0)
	s_barrier
	s_setprio 1
	s_waitcnt lgkmcnt(0)
	v_mfma_f32_16x16x32_bf16 v[132:135], v[120:123], v[160:163], v[132:135]
	v_mfma_f32_16x16x32_bf16 v[128:131], v[136:139], v[160:163], v[128:131]
	v_mfma_f32_16x16x32_bf16 v[108:111], v[120:123], v[168:171], v[108:111]
	v_mfma_f32_16x16x32_bf16 v[104:107], v[136:139], v[168:171], v[104:107]
	v_mfma_f32_16x16x32_bf16 v[92:95], v[120:123], v[176:179], v[92:95]
	v_mfma_f32_16x16x32_bf16 v[88:91], v[136:139], v[176:179], v[88:91]
	v_mfma_f32_16x16x32_bf16 v[76:79], v[120:123], v[200:203], v[76:79]
	v_mfma_f32_16x16x32_bf16 v[72:75], v[136:139], v[200:203], v[72:75]
	v_mfma_f32_16x16x32_bf16 v[132:135], v[124:127], v[164:167], v[132:135]
	v_mfma_f32_16x16x32_bf16 v[128:131], v[140:143], v[164:167], v[128:131]
	v_mfma_f32_16x16x32_bf16 v[108:111], v[124:127], v[172:175], v[108:111]
	v_mfma_f32_16x16x32_bf16 v[104:107], v[140:143], v[172:175], v[104:107]
	v_mfma_f32_16x16x32_bf16 v[92:95], v[124:127], v[180:183], v[92:95]
	v_mfma_f32_16x16x32_bf16 v[88:91], v[140:143], v[180:183], v[88:91]
	v_mfma_f32_16x16x32_bf16 v[76:79], v[124:127], v[204:207], v[76:79]
	v_mfma_f32_16x16x32_bf16 v[72:75], v[140:143], v[204:207], v[72:75]
	s_setprio 0
	s_setprio 1
	v_mfma_f32_16x16x32_bf16 v[116:119], v[144:147], v[160:163], v[116:119]
	v_mfma_f32_16x16x32_bf16 v[112:115], v[152:155], v[160:163], v[112:115]
	v_mfma_f32_16x16x32_bf16 v[100:103], v[144:147], v[168:171], v[100:103]
	v_mfma_f32_16x16x32_bf16 v[96:99], v[152:155], v[168:171], v[96:99]
	v_mfma_f32_16x16x32_bf16 v[84:87], v[144:147], v[176:179], v[84:87]
	v_mfma_f32_16x16x32_bf16 v[80:83], v[152:155], v[176:179], v[80:83]
	v_mfma_f32_16x16x32_bf16 v[68:71], v[144:147], v[200:203], v[68:71]
	v_mfma_f32_16x16x32_bf16 v[64:67], v[152:155], v[200:203], v[64:67]
	v_mfma_f32_16x16x32_bf16 v[116:119], v[148:151], v[164:167], v[116:119]
	v_mfma_f32_16x16x32_bf16 v[112:115], v[156:159], v[164:167], v[112:115]
	v_mfma_f32_16x16x32_bf16 v[100:103], v[148:151], v[172:175], v[100:103]
	v_mfma_f32_16x16x32_bf16 v[96:99], v[156:159], v[172:175], v[96:99]
	s_setprio 2
	s_barrier
	v_mfma_f32_16x16x32_bf16 v[84:87], v[148:151], v[180:183], v[84:87]
	v_mfma_f32_16x16x32_bf16 v[80:83], v[156:159], v[180:183], v[80:83]
	v_mfma_f32_16x16x32_bf16 v[68:71], v[148:151], v[204:207], v[68:71]
	v_mfma_f32_16x16x32_bf16 v[64:67], v[156:159], v[204:207], v[64:67]
	s_setprio 0
	s_add_i32 s26, s56, s43
	v_lshl_add_u64 v[208:209], s[30:31], 0, v[186:187]
	s_mov_b32 m0, s26
	ds_read_b128 v[160:163], v235 offset:16384
	ds_read_b128 v[164:167], v235 offset:17408
	ds_read_b128 v[168:171], v235 offset:18432
	ds_read_b128 v[172:175], v235 offset:19456
	ds_read_b128 v[176:179], v235 offset:20480
	ds_read_b128 v[180:183], v235 offset:21504
	global_load_lds_dwordx4 v[208:209], off
	s_add_i32 m0, s26, 0x2000
	s_add_u32 s26, s30, 0xb0000
	v_lshl_add_u64 v[210:211], s[30:31], 0, v[190:191]
	s_addc_u32 s27, s31, 0
	s_add_i32 s65, s57, s43
	global_load_lds_dwordx4 v[210:211], off
	s_mov_b32 m0, s65
	v_lshl_add_u64 v[214:215], s[36:37], 0, v[188:189]
	global_load_lds_dwordx4 v186, s[26:27]
	s_add_i32 m0, s65, 0x2000
	ds_read_b128 v[200:203], v235 offset:22528
	global_load_lds_dwordx4 v190, s[26:27]
	s_mov_b32 m0, s44
	v_lshl_add_u64 v[212:213], s[36:37], 0, v[184:185]
	global_load_lds_dwordx4 v[212:213], off
	s_mov_b32 m0, s45
	ds_read_b128 v[204:207], v235 offset:23552
	global_load_lds_dwordx4 v[214:215], off
	s_waitcnt vmcnt(8)
	s_waitcnt lgkmcnt(0)
	s_barrier
	s_setprio 1
	s_waitcnt lgkmcnt(0)
	v_mfma_f32_16x16x32_bf16 v[60:63], v[120:123], v[160:163], v[60:63]
	v_mfma_f32_16x16x32_bf16 v[56:59], v[136:139], v[160:163], v[56:59]
	v_mfma_f32_16x16x32_bf16 v[44:47], v[120:123], v[168:171], v[44:47]
	v_mfma_f32_16x16x32_bf16 v[40:43], v[136:139], v[168:171], v[40:43]
	v_mfma_f32_16x16x32_bf16 v[28:31], v[120:123], v[176:179], v[28:31]
	v_mfma_f32_16x16x32_bf16 v[24:27], v[136:139], v[176:179], v[24:27]
	v_mfma_f32_16x16x32_bf16 v[12:15], v[120:123], v[200:203], v[12:15]
	v_mfma_f32_16x16x32_bf16 v[8:11], v[136:139], v[200:203], v[8:11]
	v_mfma_f32_16x16x32_bf16 v[60:63], v[124:127], v[164:167], v[60:63]
	v_mfma_f32_16x16x32_bf16 v[56:59], v[140:143], v[164:167], v[56:59]
	v_mfma_f32_16x16x32_bf16 v[44:47], v[124:127], v[172:175], v[44:47]
	v_mfma_f32_16x16x32_bf16 v[40:43], v[140:143], v[172:175], v[40:43]
	v_mfma_f32_16x16x32_bf16 v[28:31], v[124:127], v[180:183], v[28:31]
	v_mfma_f32_16x16x32_bf16 v[24:27], v[140:143], v[180:183], v[24:27]
	v_mfma_f32_16x16x32_bf16 v[12:15], v[124:127], v[204:207], v[12:15]
	v_mfma_f32_16x16x32_bf16 v[8:11], v[140:143], v[204:207], v[8:11]
	s_setprio 0
	s_setprio 1
	v_mfma_f32_16x16x32_bf16 v[52:55], v[144:147], v[160:163], v[52:55]
	v_mfma_f32_16x16x32_bf16 v[48:51], v[152:155], v[160:163], v[48:51]
	v_mfma_f32_16x16x32_bf16 v[36:39], v[144:147], v[168:171], v[36:39]
	v_mfma_f32_16x16x32_bf16 v[32:35], v[152:155], v[168:171], v[32:35]
	v_mfma_f32_16x16x32_bf16 v[20:23], v[144:147], v[176:179], v[20:23]
	v_mfma_f32_16x16x32_bf16 v[16:19], v[152:155], v[176:179], v[16:19]
	v_mfma_f32_16x16x32_bf16 v[4:7], v[144:147], v[200:203], v[4:7]
	v_mfma_f32_16x16x32_bf16 v[0:3], v[152:155], v[200:203], v[0:3]
	v_mfma_f32_16x16x32_bf16 v[52:55], v[148:151], v[164:167], v[52:55]
	v_mfma_f32_16x16x32_bf16 v[48:51], v[156:159], v[164:167], v[48:51]
	v_mfma_f32_16x16x32_bf16 v[36:39], v[148:151], v[172:175], v[36:39]
	v_mfma_f32_16x16x32_bf16 v[32:35], v[156:159], v[172:175], v[32:35]
	s_setprio 2
	s_barrier
	v_mfma_f32_16x16x32_bf16 v[20:23], v[148:151], v[180:183], v[20:23]
	v_mfma_f32_16x16x32_bf16 v[16:19], v[156:159], v[180:183], v[16:19]
	v_mfma_f32_16x16x32_bf16 v[4:7], v[148:151], v[204:207], v[4:7]
	v_mfma_f32_16x16x32_bf16 v[0:3], v[156:159], v[204:207], v[0:3]
	s_setprio 0
	s_add_i32 s65, 0, 0x18000
	s_add_i32 s66, 0, 0x1c000
	v_add_u32_e32 v140, s65, v232
	v_add_u32_e32 v156, s66, v232
	ds_read_b128 v[120:123], v140
	ds_read_b128 v[124:127], v140 offset:1024
	ds_read_b128 v[136:139], v140 offset:2048
	ds_read_b128 v[140:143], v140 offset:3072
	ds_read_b128 v[144:147], v156
	ds_read_b128 v[148:151], v156 offset:1024
	ds_read_b128 v[152:155], v156 offset:2048
	ds_read_b128 v[156:159], v156 offset:3072
	s_add_u32 s26, s36, 0xb0000
	s_addc_u32 s27, s37, 0
	s_mov_b32 m0, s46
	v_lshl_add_u64 v[216:217], s[26:27], 0, v[184:185]
	ds_read_b128 v[160:163], v235 offset:32768
	ds_read_b128 v[164:167], v235 offset:33792
	ds_read_b128 v[168:171], v235 offset:34816
	ds_read_b128 v[172:175], v235 offset:35840
	ds_read_b128 v[176:179], v235 offset:36864
	ds_read_b128 v[180:183], v235 offset:37888
	ds_read_b128 v[200:203], v235 offset:38912
	ds_read_b128 v[204:207], v235 offset:39936
	global_load_lds_dwordx4 v[216:217], off
	s_mov_b32 m0, s47
	v_lshl_add_u64 v[216:217], s[26:27], 0, v[188:189]
	global_load_lds_dwordx4 v[216:217], off
	s_waitcnt vmcnt(8)
	s_waitcnt lgkmcnt(0)
	s_barrier
	s_setprio 1
	s_waitcnt lgkmcnt(0)
	v_mfma_f32_16x16x32_bf16 v[132:135], v[120:123], v[160:163], v[132:135]
	v_mfma_f32_16x16x32_bf16 v[128:131], v[136:139], v[160:163], v[128:131]
	v_mfma_f32_16x16x32_bf16 v[108:111], v[120:123], v[168:171], v[108:111]
	v_mfma_f32_16x16x32_bf16 v[104:107], v[136:139], v[168:171], v[104:107]
	v_mfma_f32_16x16x32_bf16 v[92:95], v[120:123], v[176:179], v[92:95]
	v_mfma_f32_16x16x32_bf16 v[88:91], v[136:139], v[176:179], v[88:91]
	v_mfma_f32_16x16x32_bf16 v[76:79], v[120:123], v[200:203], v[76:79]
	v_mfma_f32_16x16x32_bf16 v[72:75], v[136:139], v[200:203], v[72:75]
	v_mfma_f32_16x16x32_bf16 v[132:135], v[124:127], v[164:167], v[132:135]
	v_mfma_f32_16x16x32_bf16 v[128:131], v[140:143], v[164:167], v[128:131]
	v_mfma_f32_16x16x32_bf16 v[108:111], v[124:127], v[172:175], v[108:111]
	v_mfma_f32_16x16x32_bf16 v[104:107], v[140:143], v[172:175], v[104:107]
	v_mfma_f32_16x16x32_bf16 v[92:95], v[124:127], v[180:183], v[92:95]
	v_mfma_f32_16x16x32_bf16 v[88:91], v[140:143], v[180:183], v[88:91]
	v_mfma_f32_16x16x32_bf16 v[76:79], v[124:127], v[204:207], v[76:79]
	v_mfma_f32_16x16x32_bf16 v[72:75], v[140:143], v[204:207], v[72:75]
	s_setprio 0
	s_setprio 1
	v_mfma_f32_16x16x32_bf16 v[116:119], v[144:147], v[160:163], v[116:119]
	v_mfma_f32_16x16x32_bf16 v[112:115], v[152:155], v[160:163], v[112:115]
	v_mfma_f32_16x16x32_bf16 v[100:103], v[144:147], v[168:171], v[100:103]
	v_mfma_f32_16x16x32_bf16 v[96:99], v[152:155], v[168:171], v[96:99]
	v_mfma_f32_16x16x32_bf16 v[84:87], v[144:147], v[176:179], v[84:87]
	v_mfma_f32_16x16x32_bf16 v[80:83], v[152:155], v[176:179], v[80:83]
	v_mfma_f32_16x16x32_bf16 v[68:71], v[144:147], v[200:203], v[68:71]
	v_mfma_f32_16x16x32_bf16 v[64:67], v[152:155], v[200:203], v[64:67]
	v_mfma_f32_16x16x32_bf16 v[116:119], v[148:151], v[164:167], v[116:119]
	v_mfma_f32_16x16x32_bf16 v[112:115], v[156:159], v[164:167], v[112:115]
	v_mfma_f32_16x16x32_bf16 v[100:103], v[148:151], v[172:175], v[100:103]
	v_mfma_f32_16x16x32_bf16 v[96:99], v[156:159], v[172:175], v[96:99]
	s_setprio 2
	s_barrier
	v_mfma_f32_16x16x32_bf16 v[84:87], v[148:151], v[180:183], v[84:87]
	v_mfma_f32_16x16x32_bf16 v[80:83], v[156:159], v[180:183], v[80:83]
	v_mfma_f32_16x16x32_bf16 v[68:71], v[148:151], v[204:207], v[68:71]
	v_mfma_f32_16x16x32_bf16 v[64:67], v[156:159], v[204:207], v[64:67]
	s_setprio 0
	s_add_i32 s26, s65, s43
	s_add_i32 m0, s26, 0xffffff80
	ds_read_b128 v[160:163], v235 offset:49152
	ds_read_b128 v[164:167], v235 offset:50176
	ds_read_b128 v[168:171], v235 offset:51200
	ds_read_b128 v[172:175], v235 offset:52224
	ds_read_b128 v[176:179], v235 offset:53248
	global_load_lds_dwordx4 v[208:209], off offset:128
	s_add_i32 m0, s26, 0x1f80
	s_add_u32 s26, s30, 0xb0080
	s_addc_u32 s27, s31, 0
	s_add_i32 s30, s66, s43
	global_load_lds_dwordx4 v[210:211], off offset:128
	s_mov_b32 m0, s30
	ds_read_b128 v[180:183], v235 offset:54272
	global_load_lds_dwordx4 v186, s[26:27]
	s_add_i32 m0, s30, 0x2000
	ds_read_b128 v[200:203], v235 offset:55296
	global_load_lds_dwordx4 v190, s[26:27]
	s_add_i32 m0, s49, 0xffffff80
	ds_read_b128 v[204:207], v235 offset:56320
	global_load_lds_dwordx4 v[212:213], off offset:128
	s_mov_b32 m0, s50
	v_lshl_add_u64 v[208:209], v[214:215], 0, s[20:21]
	global_load_lds_dwordx4 v[208:209], off
	s_waitcnt vmcnt(8)
	s_waitcnt lgkmcnt(0)
	s_barrier
	s_setprio 1
	s_waitcnt lgkmcnt(0)
	v_mfma_f32_16x16x32_bf16 v[60:63], v[120:123], v[160:163], v[60:63]
	v_mfma_f32_16x16x32_bf16 v[56:59], v[136:139], v[160:163], v[56:59]
	v_mfma_f32_16x16x32_bf16 v[44:47], v[120:123], v[168:171], v[44:47]
	v_mfma_f32_16x16x32_bf16 v[40:43], v[136:139], v[168:171], v[40:43]
	v_mfma_f32_16x16x32_bf16 v[28:31], v[120:123], v[176:179], v[28:31]
	v_mfma_f32_16x16x32_bf16 v[24:27], v[136:139], v[176:179], v[24:27]
	v_mfma_f32_16x16x32_bf16 v[12:15], v[120:123], v[200:203], v[12:15]
	v_mfma_f32_16x16x32_bf16 v[8:11], v[136:139], v[200:203], v[8:11]
	v_mfma_f32_16x16x32_bf16 v[60:63], v[124:127], v[164:167], v[60:63]
	v_mfma_f32_16x16x32_bf16 v[56:59], v[140:143], v[164:167], v[56:59]
	v_mfma_f32_16x16x32_bf16 v[44:47], v[124:127], v[172:175], v[44:47]
	v_mfma_f32_16x16x32_bf16 v[40:43], v[140:143], v[172:175], v[40:43]
	v_mfma_f32_16x16x32_bf16 v[28:31], v[124:127], v[180:183], v[28:31]
	v_mfma_f32_16x16x32_bf16 v[24:27], v[140:143], v[180:183], v[24:27]
	v_mfma_f32_16x16x32_bf16 v[12:15], v[124:127], v[204:207], v[12:15]
	v_mfma_f32_16x16x32_bf16 v[8:11], v[140:143], v[204:207], v[8:11]
	s_setprio 0
	s_setprio 1
	v_mfma_f32_16x16x32_bf16 v[52:55], v[144:147], v[160:163], v[52:55]
	v_mfma_f32_16x16x32_bf16 v[48:51], v[152:155], v[160:163], v[48:51]
	v_mfma_f32_16x16x32_bf16 v[36:39], v[144:147], v[168:171], v[36:39]
	v_mfma_f32_16x16x32_bf16 v[32:35], v[152:155], v[168:171], v[32:35]
	v_mfma_f32_16x16x32_bf16 v[20:23], v[144:147], v[176:179], v[20:23]
	v_mfma_f32_16x16x32_bf16 v[16:19], v[152:155], v[176:179], v[16:19]
	v_mfma_f32_16x16x32_bf16 v[4:7], v[144:147], v[200:203], v[4:7]
	v_mfma_f32_16x16x32_bf16 v[0:3], v[152:155], v[200:203], v[0:3]
	v_mfma_f32_16x16x32_bf16 v[52:55], v[148:151], v[164:167], v[52:55]
	v_mfma_f32_16x16x32_bf16 v[48:51], v[156:159], v[164:167], v[48:51]
	v_mfma_f32_16x16x32_bf16 v[36:39], v[148:151], v[172:175], v[36:39]
	v_mfma_f32_16x16x32_bf16 v[32:35], v[156:159], v[172:175], v[32:35]
	s_setprio 2
	s_barrier
	v_mfma_f32_16x16x32_bf16 v[20:23], v[148:151], v[180:183], v[20:23]
	v_mfma_f32_16x16x32_bf16 v[16:19], v[156:159], v[180:183], v[16:19]
	v_mfma_f32_16x16x32_bf16 v[4:7], v[148:151], v[204:207], v[4:7]
	v_mfma_f32_16x16x32_bf16 v[0:3], v[156:159], v[204:207], v[0:3]
	s_setprio 0
	s_add_i32 s64, s64, 2
	s_add_u32 s62, s62, 0x100
	s_addc_u32 s63, s63, 0
	s_cmp_gt_u32 s64, 41
	s_mov_b64 s[26:27], s[28:29]
	s_cbranch_scc0 .LBB0_866

.LBB0_951:
	s_ashr_i32 s27, s26, 31
	s_lshl_b64 s[30:31], s[26:27], 19
	s_add_u32 s30, s47, s30
	s_addc_u32 s31, s48, s31
	s_and_b64 s[36:37], s[4:5], exec
	s_cselect_b32 s27, s31, s7
	s_cselect_b32 s39, s30, s6
	s_ashr_i32 s29, s28, 31
	s_lshl_b64 s[36:37], s[28:29], 19
	s_add_u32 s36, s49, s36
	s_addc_u32 s37, s50, s37
	s_and_b64 s[44:45], s[4:5], exec
	s_cselect_b32 s29, s37, s41
	s_cselect_b32 s43, s36, s40
	s_add_u32 s6, s6, 0x40080
	s_addc_u32 s7, s7, 0
	s_add_u32 s71, s40, 0x100
	s_addc_u32 s72, s41, 0
	s_mov_b32 s73, -2
	ds_read_b128 v[144:147], v179
	ds_read_b128 v[148:151], v179 offset:1024
	ds_read_b128 v[152:155], v179 offset:2048
	ds_read_b128 v[156:159], v179 offset:3072
	ds_read_b128 v[160:163], v180
	ds_read_b128 v[164:167], v180 offset:1024
	ds_read_b128 v[168:171], v180 offset:2048
	ds_read_b128 v[172:175], v180 offset:3072
	s_add_u32 s40, s6, 0xfffc0080
	s_addc_u32 s41, s7, -1
	s_cmp_eq_u32 s73, 12
	s_cselect_b32 s45, s27, s41
	s_cselect_b32 s44, s39, s40
	s_cselect_b32 s41, s29, s72
	s_cselect_b32 s40, s43, s71
	v_lshl_add_u64 v[176:177], s[6:7], 0, v[136:137]
	s_add_i32 m0, s54, 0xc000
	ds_read_b128 v[184:187], v181
	ds_read_b128 v[188:191], v181 offset:1024
	ds_read_b128 v[192:195], v181 offset:2048
	ds_read_b128 v[196:199], v181 offset:3072
	ds_read_b128 v[200:203], v181 offset:4096
	ds_read_b128 v[204:207], v181 offset:5120
	ds_read_b128 v[208:211], v181 offset:6144
	ds_read_b128 v[212:215], v181 offset:7168
	global_load_lds_dwordx4 v[176:177], off
	s_add_i32 m0, s54, 0xe000
	v_lshl_add_u64 v[176:177], s[6:7], 0, v[138:139]
	global_load_lds_dwordx4 v[176:177], off
	s_waitcnt vmcnt(8)
	s_waitcnt lgkmcnt(0)
	s_barrier
	s_setprio 1
	s_waitcnt lgkmcnt(0)
	v_mfma_f32_16x16x32_bf16 v[124:127], v[144:147], v[184:187], 0
	v_mfma_f32_16x16x32_bf16 v[120:123], v[152:155], v[184:187], 0
	v_mfma_f32_16x16x32_bf16 v[108:111], v[144:147], v[192:195], 0
	v_mfma_f32_16x16x32_bf16 v[104:107], v[152:155], v[192:195], 0
	v_mfma_f32_16x16x32_bf16 v[92:95], v[144:147], v[200:203], 0
	v_mfma_f32_16x16x32_bf16 v[88:91], v[152:155], v[200:203], 0
	v_mfma_f32_16x16x32_bf16 v[76:79], v[144:147], v[208:211], 0
	v_mfma_f32_16x16x32_bf16 v[72:75], v[152:155], v[208:211], 0
	v_mfma_f32_16x16x32_bf16 v[124:127], v[148:151], v[188:191], v[124:127]
	v_mfma_f32_16x16x32_bf16 v[120:123], v[156:159], v[188:191], v[120:123]
	v_mfma_f32_16x16x32_bf16 v[108:111], v[148:151], v[196:199], v[108:111]
	v_mfma_f32_16x16x32_bf16 v[104:107], v[156:159], v[196:199], v[104:107]
	v_mfma_f32_16x16x32_bf16 v[92:95], v[148:151], v[204:207], v[92:95]
	v_mfma_f32_16x16x32_bf16 v[88:91], v[156:159], v[204:207], v[88:91]
	v_mfma_f32_16x16x32_bf16 v[76:79], v[148:151], v[212:215], v[76:79]
	v_mfma_f32_16x16x32_bf16 v[72:75], v[156:159], v[212:215], v[72:75]
	s_setprio 0
	s_setprio 1
	v_mfma_f32_16x16x32_bf16 v[116:119], v[160:163], v[184:187], 0
	v_mfma_f32_16x16x32_bf16 v[112:115], v[168:171], v[184:187], 0
	v_mfma_f32_16x16x32_bf16 v[100:103], v[160:163], v[192:195], 0
	v_mfma_f32_16x16x32_bf16 v[96:99], v[168:171], v[192:195], 0
	v_mfma_f32_16x16x32_bf16 v[84:87], v[160:163], v[200:203], 0
	v_mfma_f32_16x16x32_bf16 v[80:83], v[168:171], v[200:203], 0
	v_mfma_f32_16x16x32_bf16 v[68:71], v[160:163], v[208:211], 0
	v_mfma_f32_16x16x32_bf16 v[64:67], v[168:171], v[208:211], 0
	v_mfma_f32_16x16x32_bf16 v[116:119], v[164:167], v[188:191], v[116:119]
	v_mfma_f32_16x16x32_bf16 v[112:115], v[172:175], v[188:191], v[112:115]
	v_mfma_f32_16x16x32_bf16 v[100:103], v[164:167], v[196:199], v[100:103]
	v_mfma_f32_16x16x32_bf16 v[96:99], v[172:175], v[196:199], v[96:99]
	s_setprio 2
	s_barrier
	v_mfma_f32_16x16x32_bf16 v[84:87], v[164:167], v[204:207], v[84:87]
	v_mfma_f32_16x16x32_bf16 v[80:83], v[172:175], v[204:207], v[80:83]
	v_mfma_f32_16x16x32_bf16 v[68:71], v[164:167], v[212:215], v[68:71]
	v_mfma_f32_16x16x32_bf16 v[64:67], v[172:175], v[212:215], v[64:67]
	s_setprio 0
	s_add_i32 s74, s69, s51
	v_lshl_add_u64 v[176:177], s[40:41], 0, v[130:131]
	s_mov_b32 m0, s74
	ds_read_b128 v[184:187], v181 offset:16384
	ds_read_b128 v[188:191], v181 offset:17408
	ds_read_b128 v[192:195], v181 offset:18432
	ds_read_b128 v[196:199], v181 offset:19456
	ds_read_b128 v[200:203], v181 offset:20480
	ds_read_b128 v[204:207], v181 offset:21504
	global_load_lds_dwordx4 v[176:177], off
	s_add_i32 m0, s74, 0x2000
	s_add_u32 s74, s40, 0x40000
	v_lshl_add_u64 v[216:217], s[40:41], 0, v[134:135]
	s_addc_u32 s75, s41, 0
	s_add_i32 s76, s70, s51
	global_load_lds_dwordx4 v[216:217], off
	s_mov_b32 m0, s76
	v_lshl_add_u64 v[220:221], s[44:45], 0, v[132:133]
	global_load_lds_dwordx4 v130, s[74:75]
	s_add_i32 m0, s76, 0x2000
	ds_read_b128 v[208:211], v181 offset:22528
	global_load_lds_dwordx4 v134, s[74:75]
	s_mov_b32 m0, s54
	v_lshl_add_u64 v[218:219], s[44:45], 0, v[128:129]
	global_load_lds_dwordx4 v[218:219], off
	s_mov_b32 m0, s55
	ds_read_b128 v[212:215], v181 offset:23552
	global_load_lds_dwordx4 v[220:221], off
	s_waitcnt vmcnt(8)
	s_waitcnt lgkmcnt(0)
	s_barrier
	s_setprio 1
	s_waitcnt lgkmcnt(0)
	v_mfma_f32_16x16x32_bf16 v[60:63], v[144:147], v[184:187], 0
	v_mfma_f32_16x16x32_bf16 v[56:59], v[152:155], v[184:187], 0
	v_mfma_f32_16x16x32_bf16 v[44:47], v[144:147], v[192:195], 0
	v_mfma_f32_16x16x32_bf16 v[40:43], v[152:155], v[192:195], 0
	v_mfma_f32_16x16x32_bf16 v[28:31], v[144:147], v[200:203], 0
	v_mfma_f32_16x16x32_bf16 v[24:27], v[152:155], v[200:203], 0
	v_mfma_f32_16x16x32_bf16 v[12:15], v[144:147], v[208:211], 0
	v_mfma_f32_16x16x32_bf16 v[8:11], v[152:155], v[208:211], 0
	v_mfma_f32_16x16x32_bf16 v[60:63], v[148:151], v[188:191], v[60:63]
	v_mfma_f32_16x16x32_bf16 v[56:59], v[156:159], v[188:191], v[56:59]
	v_mfma_f32_16x16x32_bf16 v[44:47], v[148:151], v[196:199], v[44:47]
	v_mfma_f32_16x16x32_bf16 v[40:43], v[156:159], v[196:199], v[40:43]
	v_mfma_f32_16x16x32_bf16 v[28:31], v[148:151], v[204:207], v[28:31]
	v_mfma_f32_16x16x32_bf16 v[24:27], v[156:159], v[204:207], v[24:27]
	v_mfma_f32_16x16x32_bf16 v[12:15], v[148:151], v[212:215], v[12:15]
	v_mfma_f32_16x16x32_bf16 v[8:11], v[156:159], v[212:215], v[8:11]
	s_setprio 0
	s_setprio 1
	v_mfma_f32_16x16x32_bf16 v[52:55], v[160:163], v[184:187], 0
	v_mfma_f32_16x16x32_bf16 v[48:51], v[168:171], v[184:187], 0
	v_mfma_f32_16x16x32_bf16 v[36:39], v[160:163], v[192:195], 0
	v_mfma_f32_16x16x32_bf16 v[32:35], v[168:171], v[192:195], 0
	v_mfma_f32_16x16x32_bf16 v[20:23], v[160:163], v[200:203], 0
	v_mfma_f32_16x16x32_bf16 v[16:19], v[168:171], v[200:203], 0
	v_mfma_f32_16x16x32_bf16 v[4:7], v[160:163], v[208:211], 0
	v_mfma_f32_16x16x32_bf16 v[0:3], v[168:171], v[208:211], 0
	v_mfma_f32_16x16x32_bf16 v[52:55], v[164:167], v[188:191], v[52:55]
	v_mfma_f32_16x16x32_bf16 v[48:51], v[172:175], v[188:191], v[48:51]
	v_mfma_f32_16x16x32_bf16 v[36:39], v[164:167], v[196:199], v[36:39]
	v_mfma_f32_16x16x32_bf16 v[32:35], v[172:175], v[196:199], v[32:35]
	s_setprio 2
	s_barrier
	v_mfma_f32_16x16x32_bf16 v[20:23], v[164:167], v[204:207], v[20:23]
	v_mfma_f32_16x16x32_bf16 v[16:19], v[172:175], v[204:207], v[16:19]
	v_mfma_f32_16x16x32_bf16 v[4:7], v[164:167], v[212:215], v[4:7]
	v_mfma_f32_16x16x32_bf16 v[0:3], v[172:175], v[212:215], v[0:3]
	s_setprio 0
	s_add_i32 s74, 0, 0x18000
	s_add_i32 s75, 0, 0x1c000
	v_add_u32_e32 v156, s74, v178
	v_add_u32_e32 v172, s75, v178
	ds_read_b128 v[144:147], v156
	ds_read_b128 v[148:151], v156 offset:1024
	ds_read_b128 v[152:155], v156 offset:2048
	ds_read_b128 v[156:159], v156 offset:3072
	ds_read_b128 v[160:163], v172
	ds_read_b128 v[164:167], v172 offset:1024
	ds_read_b128 v[168:171], v172 offset:2048
	ds_read_b128 v[172:175], v172 offset:3072
	s_add_u32 s44, s44, 0x40000
	s_addc_u32 s45, s45, 0
	s_mov_b32 m0, s56
	v_lshl_add_u64 v[222:223], s[44:45], 0, v[128:129]
	ds_read_b128 v[184:187], v181 offset:32768
	ds_read_b128 v[188:191], v181 offset:33792
	ds_read_b128 v[192:195], v181 offset:34816
	ds_read_b128 v[196:199], v181 offset:35840
	ds_read_b128 v[200:203], v181 offset:36864
	ds_read_b128 v[204:207], v181 offset:37888
	ds_read_b128 v[208:211], v181 offset:38912
	ds_read_b128 v[212:215], v181 offset:39936
	global_load_lds_dwordx4 v[222:223], off
	s_mov_b32 m0, s57
	v_lshl_add_u64 v[222:223], s[44:45], 0, v[132:133]
	global_load_lds_dwordx4 v[222:223], off
	s_waitcnt vmcnt(8)
	s_waitcnt lgkmcnt(0)
	s_barrier
	s_setprio 1
	s_waitcnt lgkmcnt(0)
	v_mfma_f32_16x16x32_bf16 v[124:127], v[144:147], v[184:187], v[124:127]
	v_mfma_f32_16x16x32_bf16 v[120:123], v[152:155], v[184:187], v[120:123]
	v_mfma_f32_16x16x32_bf16 v[108:111], v[144:147], v[192:195], v[108:111]
	v_mfma_f32_16x16x32_bf16 v[104:107], v[152:155], v[192:195], v[104:107]
	v_mfma_f32_16x16x32_bf16 v[92:95], v[144:147], v[200:203], v[92:95]
	v_mfma_f32_16x16x32_bf16 v[88:91], v[152:155], v[200:203], v[88:91]
	v_mfma_f32_16x16x32_bf16 v[76:79], v[144:147], v[208:211], v[76:79]
	v_mfma_f32_16x16x32_bf16 v[72:75], v[152:155], v[208:211], v[72:75]
	v_mfma_f32_16x16x32_bf16 v[124:127], v[148:151], v[188:191], v[124:127]
	v_mfma_f32_16x16x32_bf16 v[120:123], v[156:159], v[188:191], v[120:123]
	v_mfma_f32_16x16x32_bf16 v[108:111], v[148:151], v[196:199], v[108:111]
	v_mfma_f32_16x16x32_bf16 v[104:107], v[156:159], v[196:199], v[104:107]
	v_mfma_f32_16x16x32_bf16 v[92:95], v[148:151], v[204:207], v[92:95]
	v_mfma_f32_16x16x32_bf16 v[88:91], v[156:159], v[204:207], v[88:91]
	v_mfma_f32_16x16x32_bf16 v[76:79], v[148:151], v[212:215], v[76:79]
	v_mfma_f32_16x16x32_bf16 v[72:75], v[156:159], v[212:215], v[72:75]
	s_setprio 0
	s_setprio 1
	v_mfma_f32_16x16x32_bf16 v[116:119], v[160:163], v[184:187], v[116:119]
	v_mfma_f32_16x16x32_bf16 v[112:115], v[168:171], v[184:187], v[112:115]
	v_mfma_f32_16x16x32_bf16 v[100:103], v[160:163], v[192:195], v[100:103]
	v_mfma_f32_16x16x32_bf16 v[96:99], v[168:171], v[192:195], v[96:99]
	v_mfma_f32_16x16x32_bf16 v[84:87], v[160:163], v[200:203], v[84:87]
	v_mfma_f32_16x16x32_bf16 v[80:83], v[168:171], v[200:203], v[80:83]
	v_mfma_f32_16x16x32_bf16 v[68:71], v[160:163], v[208:211], v[68:71]
	v_mfma_f32_16x16x32_bf16 v[64:67], v[168:171], v[208:211], v[64:67]
	v_mfma_f32_16x16x32_bf16 v[116:119], v[164:167], v[188:191], v[116:119]
	v_mfma_f32_16x16x32_bf16 v[112:115], v[172:175], v[188:191], v[112:115]
	v_mfma_f32_16x16x32_bf16 v[100:103], v[164:167], v[196:199], v[100:103]
	v_mfma_f32_16x16x32_bf16 v[96:99], v[172:175], v[196:199], v[96:99]
	s_setprio 2
	s_barrier
	v_mfma_f32_16x16x32_bf16 v[84:87], v[164:167], v[204:207], v[84:87]
	v_mfma_f32_16x16x32_bf16 v[80:83], v[172:175], v[204:207], v[80:83]
	v_mfma_f32_16x16x32_bf16 v[68:71], v[164:167], v[212:215], v[68:71]
	v_mfma_f32_16x16x32_bf16 v[64:67], v[172:175], v[212:215], v[64:67]
	s_setprio 0
	s_add_i32 s44, s74, s51
	s_add_i32 m0, s44, 0xffffff80
	ds_read_b128 v[184:187], v181 offset:49152
	ds_read_b128 v[188:191], v181 offset:50176
	ds_read_b128 v[192:195], v181 offset:51200
	ds_read_b128 v[196:199], v181 offset:52224
	global_load_lds_dwordx4 v[176:177], off offset:128
	s_add_i32 m0, s44, 0x1f80
	s_add_u32 s40, s40, 0x40080
	s_addc_u32 s41, s41, 0
	s_add_i32 s44, s75, s51
	global_load_lds_dwordx4 v[216:217], off offset:128
	s_mov_b32 m0, s44
	ds_read_b128 v[200:203], v181 offset:53248
	global_load_lds_dwordx4 v130, s[40:41]
	s_add_i32 m0, s44, 0x2000
	ds_read_b128 v[204:207], v181 offset:54272
	global_load_lds_dwordx4 v134, s[40:41]
	s_add_i32 m0, s64, 0xffffff80
	ds_read_b128 v[208:211], v181 offset:55296
	global_load_lds_dwordx4 v[218:219], off offset:128
	s_add_i32 m0, s65, 0xffffff80
	ds_read_b128 v[212:215], v181 offset:56320
	global_load_lds_dwordx4 v[220:221], off offset:128
	s_waitcnt vmcnt(8)
	s_waitcnt lgkmcnt(0)
	s_barrier
	s_setprio 1
	s_waitcnt lgkmcnt(0)
	v_mfma_f32_16x16x32_bf16 v[60:63], v[144:147], v[184:187], v[60:63]
	v_mfma_f32_16x16x32_bf16 v[56:59], v[152:155], v[184:187], v[56:59]
	v_mfma_f32_16x16x32_bf16 v[44:47], v[144:147], v[192:195], v[44:47]
	v_mfma_f32_16x16x32_bf16 v[40:43], v[152:155], v[192:195], v[40:43]
	v_mfma_f32_16x16x32_bf16 v[28:31], v[144:147], v[200:203], v[28:31]
	v_mfma_f32_16x16x32_bf16 v[24:27], v[152:155], v[200:203], v[24:27]
	v_mfma_f32_16x16x32_bf16 v[12:15], v[144:147], v[208:211], v[12:15]
	v_mfma_f32_16x16x32_bf16 v[8:11], v[152:155], v[208:211], v[8:11]
	v_mfma_f32_16x16x32_bf16 v[60:63], v[148:151], v[188:191], v[60:63]
	v_mfma_f32_16x16x32_bf16 v[56:59], v[156:159], v[188:191], v[56:59]
	v_mfma_f32_16x16x32_bf16 v[44:47], v[148:151], v[196:199], v[44:47]
	v_mfma_f32_16x16x32_bf16 v[40:43], v[156:159], v[196:199], v[40:43]
	v_mfma_f32_16x16x32_bf16 v[28:31], v[148:151], v[204:207], v[28:31]
	v_mfma_f32_16x16x32_bf16 v[24:27], v[156:159], v[204:207], v[24:27]
	v_mfma_f32_16x16x32_bf16 v[12:15], v[148:151], v[212:215], v[12:15]
	v_mfma_f32_16x16x32_bf16 v[8:11], v[156:159], v[212:215], v[8:11]
	s_setprio 0
	s_setprio 1
	v_mfma_f32_16x16x32_bf16 v[52:55], v[160:163], v[184:187], v[52:55]
	v_mfma_f32_16x16x32_bf16 v[48:51], v[168:171], v[184:187], v[48:51]
	v_mfma_f32_16x16x32_bf16 v[36:39], v[160:163], v[192:195], v[36:39]
	v_mfma_f32_16x16x32_bf16 v[32:35], v[168:171], v[192:195], v[32:35]
	v_mfma_f32_16x16x32_bf16 v[20:23], v[160:163], v[200:203], v[20:23]
	v_mfma_f32_16x16x32_bf16 v[16:19], v[168:171], v[200:203], v[16:19]
	v_mfma_f32_16x16x32_bf16 v[4:7], v[160:163], v[208:211], v[4:7]
	v_mfma_f32_16x16x32_bf16 v[0:3], v[168:171], v[208:211], v[0:3]
	v_mfma_f32_16x16x32_bf16 v[52:55], v[164:167], v[188:191], v[52:55]
	v_mfma_f32_16x16x32_bf16 v[48:51], v[172:175], v[188:191], v[48:51]
	v_mfma_f32_16x16x32_bf16 v[36:39], v[164:167], v[196:199], v[36:39]
	v_mfma_f32_16x16x32_bf16 v[32:35], v[172:175], v[196:199], v[32:35]
	s_setprio 2
	s_barrier
	v_mfma_f32_16x16x32_bf16 v[20:23], v[164:167], v[204:207], v[20:23]
	v_mfma_f32_16x16x32_bf16 v[16:19], v[172:175], v[204:207], v[16:19]
	v_mfma_f32_16x16x32_bf16 v[4:7], v[164:167], v[212:215], v[4:7]
	v_mfma_f32_16x16x32_bf16 v[0:3], v[172:175], v[212:215], v[0:3]
	s_setprio 0
	s_add_i32 s73, s73, 2
	s_add_u32 s6, s6, 0x100
	s_addc_u32 s7, s7, 0
	s_add_u32 s71, s71, 0x100
	s_addc_u32 s72, s72, 0
	s_cmp_gt_u32 s73, 13
.LBB0_952:
	ds_read_b128 v[144:147], v179
	ds_read_b128 v[148:151], v179 offset:1024
	ds_read_b128 v[152:155], v179 offset:2048
	ds_read_b128 v[156:159], v179 offset:3072
	ds_read_b128 v[160:163], v180
	ds_read_b128 v[164:167], v180 offset:1024
	ds_read_b128 v[168:171], v180 offset:2048
	ds_read_b128 v[172:175], v180 offset:3072
	s_add_u32 s40, s6, 0xfffc0080
	s_addc_u32 s41, s7, -1
	s_cmp_eq_u32 s73, 12
	s_cselect_b32 s45, s27, s41
	s_cselect_b32 s44, s39, s40
	s_cselect_b32 s41, s29, s72
	s_cselect_b32 s40, s43, s71
	v_lshl_add_u64 v[176:177], s[6:7], 0, v[136:137]
	s_add_i32 m0, s54, 0xc000
	ds_read_b128 v[184:187], v181
	ds_read_b128 v[188:191], v181 offset:1024
	ds_read_b128 v[192:195], v181 offset:2048
	ds_read_b128 v[196:199], v181 offset:3072
	ds_read_b128 v[200:203], v181 offset:4096
	ds_read_b128 v[204:207], v181 offset:5120
	ds_read_b128 v[208:211], v181 offset:6144
	ds_read_b128 v[212:215], v181 offset:7168
	global_load_lds_dwordx4 v[176:177], off
	s_add_i32 m0, s54, 0xe000
	v_lshl_add_u64 v[176:177], s[6:7], 0, v[138:139]
	global_load_lds_dwordx4 v[176:177], off
	s_waitcnt vmcnt(8)
	s_waitcnt lgkmcnt(0)
	s_barrier
	s_setprio 1
	s_waitcnt lgkmcnt(0)
	v_mfma_f32_16x16x32_bf16 v[124:127], v[144:147], v[184:187], v[124:127]
	v_mfma_f32_16x16x32_bf16 v[120:123], v[152:155], v[184:187], v[120:123]
	v_mfma_f32_16x16x32_bf16 v[108:111], v[144:147], v[192:195], v[108:111]
	v_mfma_f32_16x16x32_bf16 v[104:107], v[152:155], v[192:195], v[104:107]
	v_mfma_f32_16x16x32_bf16 v[92:95], v[144:147], v[200:203], v[92:95]
	v_mfma_f32_16x16x32_bf16 v[88:91], v[152:155], v[200:203], v[88:91]
	v_mfma_f32_16x16x32_bf16 v[76:79], v[144:147], v[208:211], v[76:79]
	v_mfma_f32_16x16x32_bf16 v[72:75], v[152:155], v[208:211], v[72:75]
	v_mfma_f32_16x16x32_bf16 v[124:127], v[148:151], v[188:191], v[124:127]
	v_mfma_f32_16x16x32_bf16 v[120:123], v[156:159], v[188:191], v[120:123]
	v_mfma_f32_16x16x32_bf16 v[108:111], v[148:151], v[196:199], v[108:111]
	v_mfma_f32_16x16x32_bf16 v[104:107], v[156:159], v[196:199], v[104:107]
	v_mfma_f32_16x16x32_bf16 v[92:95], v[148:151], v[204:207], v[92:95]
	v_mfma_f32_16x16x32_bf16 v[88:91], v[156:159], v[204:207], v[88:91]
	v_mfma_f32_16x16x32_bf16 v[76:79], v[148:151], v[212:215], v[76:79]
	v_mfma_f32_16x16x32_bf16 v[72:75], v[156:159], v[212:215], v[72:75]
	s_setprio 0
	s_setprio 1
	v_mfma_f32_16x16x32_bf16 v[116:119], v[160:163], v[184:187], v[116:119]
	v_mfma_f32_16x16x32_bf16 v[112:115], v[168:171], v[184:187], v[112:115]
	v_mfma_f32_16x16x32_bf16 v[100:103], v[160:163], v[192:195], v[100:103]
	v_mfma_f32_16x16x32_bf16 v[96:99], v[168:171], v[192:195], v[96:99]
	v_mfma_f32_16x16x32_bf16 v[84:87], v[160:163], v[200:203], v[84:87]
	v_mfma_f32_16x16x32_bf16 v[80:83], v[168:171], v[200:203], v[80:83]
	v_mfma_f32_16x16x32_bf16 v[68:71], v[160:163], v[208:211], v[68:71]
	v_mfma_f32_16x16x32_bf16 v[64:67], v[168:171], v[208:211], v[64:67]
	v_mfma_f32_16x16x32_bf16 v[116:119], v[164:167], v[188:191], v[116:119]
	v_mfma_f32_16x16x32_bf16 v[112:115], v[172:175], v[188:191], v[112:115]
	v_mfma_f32_16x16x32_bf16 v[100:103], v[164:167], v[196:199], v[100:103]
	v_mfma_f32_16x16x32_bf16 v[96:99], v[172:175], v[196:199], v[96:99]
	s_setprio 2
	s_barrier
	v_mfma_f32_16x16x32_bf16 v[84:87], v[164:167], v[204:207], v[84:87]
	v_mfma_f32_16x16x32_bf16 v[80:83], v[172:175], v[204:207], v[80:83]
	v_mfma_f32_16x16x32_bf16 v[68:71], v[164:167], v[212:215], v[68:71]
	v_mfma_f32_16x16x32_bf16 v[64:67], v[172:175], v[212:215], v[64:67]
	s_setprio 0
	s_add_i32 s74, s69, s51
	v_lshl_add_u64 v[176:177], s[40:41], 0, v[130:131]
	s_mov_b32 m0, s74
	ds_read_b128 v[184:187], v181 offset:16384
	ds_read_b128 v[188:191], v181 offset:17408
	ds_read_b128 v[192:195], v181 offset:18432
	ds_read_b128 v[196:199], v181 offset:19456
	ds_read_b128 v[200:203], v181 offset:20480
	ds_read_b128 v[204:207], v181 offset:21504
	global_load_lds_dwordx4 v[176:177], off
	s_add_i32 m0, s74, 0x2000
	s_add_u32 s74, s40, 0x40000
	v_lshl_add_u64 v[216:217], s[40:41], 0, v[134:135]
	s_addc_u32 s75, s41, 0
	s_add_i32 s76, s70, s51
	global_load_lds_dwordx4 v[216:217], off
	s_mov_b32 m0, s76
	v_lshl_add_u64 v[220:221], s[44:45], 0, v[132:133]
	global_load_lds_dwordx4 v130, s[74:75]
	s_add_i32 m0, s76, 0x2000
	ds_read_b128 v[208:211], v181 offset:22528
	global_load_lds_dwordx4 v134, s[74:75]
	s_mov_b32 m0, s54
	v_lshl_add_u64 v[218:219], s[44:45], 0, v[128:129]
	global_load_lds_dwordx4 v[218:219], off
	s_mov_b32 m0, s55
	ds_read_b128 v[212:215], v181 offset:23552
	global_load_lds_dwordx4 v[220:221], off
	s_waitcnt vmcnt(8)
	s_waitcnt lgkmcnt(0)
	s_barrier
	s_setprio 1
	s_waitcnt lgkmcnt(0)
	v_mfma_f32_16x16x32_bf16 v[60:63], v[144:147], v[184:187], v[60:63]
	v_mfma_f32_16x16x32_bf16 v[56:59], v[152:155], v[184:187], v[56:59]
	v_mfma_f32_16x16x32_bf16 v[44:47], v[144:147], v[192:195], v[44:47]
	v_mfma_f32_16x16x32_bf16 v[40:43], v[152:155], v[192:195], v[40:43]
	v_mfma_f32_16x16x32_bf16 v[28:31], v[144:147], v[200:203], v[28:31]
	v_mfma_f32_16x16x32_bf16 v[24:27], v[152:155], v[200:203], v[24:27]
	v_mfma_f32_16x16x32_bf16 v[12:15], v[144:147], v[208:211], v[12:15]
	v_mfma_f32_16x16x32_bf16 v[8:11], v[152:155], v[208:211], v[8:11]
	v_mfma_f32_16x16x32_bf16 v[60:63], v[148:151], v[188:191], v[60:63]
	v_mfma_f32_16x16x32_bf16 v[56:59], v[156:159], v[188:191], v[56:59]
	v_mfma_f32_16x16x32_bf16 v[44:47], v[148:151], v[196:199], v[44:47]
	v_mfma_f32_16x16x32_bf16 v[40:43], v[156:159], v[196:199], v[40:43]
	v_mfma_f32_16x16x32_bf16 v[28:31], v[148:151], v[204:207], v[28:31]
	v_mfma_f32_16x16x32_bf16 v[24:27], v[156:159], v[204:207], v[24:27]
	v_mfma_f32_16x16x32_bf16 v[12:15], v[148:151], v[212:215], v[12:15]
	v_mfma_f32_16x16x32_bf16 v[8:11], v[156:159], v[212:215], v[8:11]
	s_setprio 0
	s_setprio 1
	v_mfma_f32_16x16x32_bf16 v[52:55], v[160:163], v[184:187], v[52:55]
	v_mfma_f32_16x16x32_bf16 v[48:51], v[168:171], v[184:187], v[48:51]
	v_mfma_f32_16x16x32_bf16 v[36:39], v[160:163], v[192:195], v[36:39]
	v_mfma_f32_16x16x32_bf16 v[32:35], v[168:171], v[192:195], v[32:35]
	v_mfma_f32_16x16x32_bf16 v[20:23], v[160:163], v[200:203], v[20:23]
	v_mfma_f32_16x16x32_bf16 v[16:19], v[168:171], v[200:203], v[16:19]
	v_mfma_f32_16x16x32_bf16 v[4:7], v[160:163], v[208:211], v[4:7]
	v_mfma_f32_16x16x32_bf16 v[0:3], v[168:171], v[208:211], v[0:3]
	v_mfma_f32_16x16x32_bf16 v[52:55], v[164:167], v[188:191], v[52:55]
	v_mfma_f32_16x16x32_bf16 v[48:51], v[172:175], v[188:191], v[48:51]
	v_mfma_f32_16x16x32_bf16 v[36:39], v[164:167], v[196:199], v[36:39]
	v_mfma_f32_16x16x32_bf16 v[32:35], v[172:175], v[196:199], v[32:35]
	s_setprio 2
	s_barrier
	v_mfma_f32_16x16x32_bf16 v[20:23], v[164:167], v[204:207], v[20:23]
	v_mfma_f32_16x16x32_bf16 v[16:19], v[172:175], v[204:207], v[16:19]
	v_mfma_f32_16x16x32_bf16 v[4:7], v[164:167], v[212:215], v[4:7]
	v_mfma_f32_16x16x32_bf16 v[0:3], v[172:175], v[212:215], v[0:3]
	s_setprio 0
	s_add_i32 s74, 0, 0x18000
	s_add_i32 s75, 0, 0x1c000
	v_add_u32_e32 v156, s74, v178
	v_add_u32_e32 v172, s75, v178
	ds_read_b128 v[144:147], v156
	ds_read_b128 v[148:151], v156 offset:1024
	ds_read_b128 v[152:155], v156 offset:2048
	ds_read_b128 v[156:159], v156 offset:3072
	ds_read_b128 v[160:163], v172
	ds_read_b128 v[164:167], v172 offset:1024
	ds_read_b128 v[168:171], v172 offset:2048
	ds_read_b128 v[172:175], v172 offset:3072
	s_add_u32 s44, s44, 0x40000
	s_addc_u32 s45, s45, 0
	s_mov_b32 m0, s56
	v_lshl_add_u64 v[222:223], s[44:45], 0, v[128:129]
	ds_read_b128 v[184:187], v181 offset:32768
	ds_read_b128 v[188:191], v181 offset:33792
	ds_read_b128 v[192:195], v181 offset:34816
	ds_read_b128 v[196:199], v181 offset:35840
	ds_read_b128 v[200:203], v181 offset:36864
	ds_read_b128 v[204:207], v181 offset:37888
	ds_read_b128 v[208:211], v181 offset:38912
	ds_read_b128 v[212:215], v181 offset:39936
	global_load_lds_dwordx4 v[222:223], off
	s_mov_b32 m0, s57
	v_lshl_add_u64 v[222:223], s[44:45], 0, v[132:133]
	global_load_lds_dwordx4 v[222:223], off
	s_waitcnt vmcnt(8)
	s_waitcnt lgkmcnt(0)
	s_barrier
	s_setprio 1
	s_waitcnt lgkmcnt(0)
	v_mfma_f32_16x16x32_bf16 v[124:127], v[144:147], v[184:187], v[124:127]
	v_mfma_f32_16x16x32_bf16 v[120:123], v[152:155], v[184:187], v[120:123]
	v_mfma_f32_16x16x32_bf16 v[108:111], v[144:147], v[192:195], v[108:111]
	v_mfma_f32_16x16x32_bf16 v[104:107], v[152:155], v[192:195], v[104:107]
	v_mfma_f32_16x16x32_bf16 v[92:95], v[144:147], v[200:203], v[92:95]
	v_mfma_f32_16x16x32_bf16 v[88:91], v[152:155], v[200:203], v[88:91]
	v_mfma_f32_16x16x32_bf16 v[76:79], v[144:147], v[208:211], v[76:79]
	v_mfma_f32_16x16x32_bf16 v[72:75], v[152:155], v[208:211], v[72:75]
	v_mfma_f32_16x16x32_bf16 v[124:127], v[148:151], v[188:191], v[124:127]
	v_mfma_f32_16x16x32_bf16 v[120:123], v[156:159], v[188:191], v[120:123]
	v_mfma_f32_16x16x32_bf16 v[108:111], v[148:151], v[196:199], v[108:111]
	v_mfma_f32_16x16x32_bf16 v[104:107], v[156:159], v[196:199], v[104:107]
	v_mfma_f32_16x16x32_bf16 v[92:95], v[148:151], v[204:207], v[92:95]
	v_mfma_f32_16x16x32_bf16 v[88:91], v[156:159], v[204:207], v[88:91]
	v_mfma_f32_16x16x32_bf16 v[76:79], v[148:151], v[212:215], v[76:79]
	v_mfma_f32_16x16x32_bf16 v[72:75], v[156:159], v[212:215], v[72:75]
	s_setprio 0
	s_setprio 1
	v_mfma_f32_16x16x32_bf16 v[116:119], v[160:163], v[184:187], v[116:119]
	v_mfma_f32_16x16x32_bf16 v[112:115], v[168:171], v[184:187], v[112:115]
	v_mfma_f32_16x16x32_bf16 v[100:103], v[160:163], v[192:195], v[100:103]
	v_mfma_f32_16x16x32_bf16 v[96:99], v[168:171], v[192:195], v[96:99]
	v_mfma_f32_16x16x32_bf16 v[84:87], v[160:163], v[200:203], v[84:87]
	v_mfma_f32_16x16x32_bf16 v[80:83], v[168:171], v[200:203], v[80:83]
	v_mfma_f32_16x16x32_bf16 v[68:71], v[160:163], v[208:211], v[68:71]
	v_mfma_f32_16x16x32_bf16 v[64:67], v[168:171], v[208:211], v[64:67]
	v_mfma_f32_16x16x32_bf16 v[116:119], v[164:167], v[188:191], v[116:119]
	v_mfma_f32_16x16x32_bf16 v[112:115], v[172:175], v[188:191], v[112:115]
	v_mfma_f32_16x16x32_bf16 v[100:103], v[164:167], v[196:199], v[100:103]
	v_mfma_f32_16x16x32_bf16 v[96:99], v[172:175], v[196:199], v[96:99]
	s_setprio 2
	s_barrier
	v_mfma_f32_16x16x32_bf16 v[84:87], v[164:167], v[204:207], v[84:87]
	v_mfma_f32_16x16x32_bf16 v[80:83], v[172:175], v[204:207], v[80:83]
	v_mfma_f32_16x16x32_bf16 v[68:71], v[164:167], v[212:215], v[68:71]
	v_mfma_f32_16x16x32_bf16 v[64:67], v[172:175], v[212:215], v[64:67]
	s_setprio 0
	s_add_i32 s44, s74, s51
	s_add_i32 m0, s44, 0xffffff80
	ds_read_b128 v[184:187], v181 offset:49152
	ds_read_b128 v[188:191], v181 offset:50176
	ds_read_b128 v[192:195], v181 offset:51200
	ds_read_b128 v[196:199], v181 offset:52224
	ds_read_b128 v[200:203], v181 offset:53248
	global_load_lds_dwordx4 v[176:177], off offset:128
	s_add_i32 m0, s44, 0x1f80
	s_add_u32 s40, s40, 0x40080
	s_addc_u32 s41, s41, 0
	s_add_i32 s44, s75, s51
	global_load_lds_dwordx4 v[216:217], off offset:128
	s_mov_b32 m0, s44
	ds_read_b128 v[204:207], v181 offset:54272
	global_load_lds_dwordx4 v130, s[40:41]
	s_add_i32 m0, s44, 0x2000
	ds_read_b128 v[208:211], v181 offset:55296
	global_load_lds_dwordx4 v134, s[40:41]
	s_add_i32 m0, s64, 0xffffff80
	ds_read_b128 v[212:215], v181 offset:56320
	global_load_lds_dwordx4 v[218:219], off offset:128
	s_mov_b32 m0, s65
	v_lshl_add_u64 v[176:177], v[220:221], 0, s[22:23]
	global_load_lds_dwordx4 v[176:177], off
	s_waitcnt vmcnt(8)
	s_waitcnt lgkmcnt(0)
	s_barrier
	s_setprio 1
	s_waitcnt lgkmcnt(0)
	v_mfma_f32_16x16x32_bf16 v[60:63], v[144:147], v[184:187], v[60:63]
	v_mfma_f32_16x16x32_bf16 v[56:59], v[152:155], v[184:187], v[56:59]
	v_mfma_f32_16x16x32_bf16 v[44:47], v[144:147], v[192:195], v[44:47]
	v_mfma_f32_16x16x32_bf16 v[40:43], v[152:155], v[192:195], v[40:43]
	v_mfma_f32_16x16x32_bf16 v[28:31], v[144:147], v[200:203], v[28:31]
	v_mfma_f32_16x16x32_bf16 v[24:27], v[152:155], v[200:203], v[24:27]
	v_mfma_f32_16x16x32_bf16 v[12:15], v[144:147], v[208:211], v[12:15]
	v_mfma_f32_16x16x32_bf16 v[8:11], v[152:155], v[208:211], v[8:11]
	v_mfma_f32_16x16x32_bf16 v[60:63], v[148:151], v[188:191], v[60:63]
	v_mfma_f32_16x16x32_bf16 v[56:59], v[156:159], v[188:191], v[56:59]
	v_mfma_f32_16x16x32_bf16 v[44:47], v[148:151], v[196:199], v[44:47]
	v_mfma_f32_16x16x32_bf16 v[40:43], v[156:159], v[196:199], v[40:43]
	v_mfma_f32_16x16x32_bf16 v[28:31], v[148:151], v[204:207], v[28:31]
	v_mfma_f32_16x16x32_bf16 v[24:27], v[156:159], v[204:207], v[24:27]
	v_mfma_f32_16x16x32_bf16 v[12:15], v[148:151], v[212:215], v[12:15]
	v_mfma_f32_16x16x32_bf16 v[8:11], v[156:159], v[212:215], v[8:11]
	s_setprio 0
	s_setprio 1
	v_mfma_f32_16x16x32_bf16 v[52:55], v[160:163], v[184:187], v[52:55]
	v_mfma_f32_16x16x32_bf16 v[48:51], v[168:171], v[184:187], v[48:51]
	v_mfma_f32_16x16x32_bf16 v[36:39], v[160:163], v[192:195], v[36:39]
	v_mfma_f32_16x16x32_bf16 v[32:35], v[168:171], v[192:195], v[32:35]
	v_mfma_f32_16x16x32_bf16 v[20:23], v[160:163], v[200:203], v[20:23]
	v_mfma_f32_16x16x32_bf16 v[16:19], v[168:171], v[200:203], v[16:19]
	v_mfma_f32_16x16x32_bf16 v[4:7], v[160:163], v[208:211], v[4:7]
	v_mfma_f32_16x16x32_bf16 v[0:3], v[168:171], v[208:211], v[0:3]
	v_mfma_f32_16x16x32_bf16 v[52:55], v[164:167], v[188:191], v[52:55]
	v_mfma_f32_16x16x32_bf16 v[48:51], v[172:175], v[188:191], v[48:51]
	v_mfma_f32_16x16x32_bf16 v[36:39], v[164:167], v[196:199], v[36:39]
	v_mfma_f32_16x16x32_bf16 v[32:35], v[172:175], v[196:199], v[32:35]
	s_setprio 2
	s_barrier
	v_mfma_f32_16x16x32_bf16 v[20:23], v[164:167], v[204:207], v[20:23]
	v_mfma_f32_16x16x32_bf16 v[16:19], v[172:175], v[204:207], v[16:19]
	v_mfma_f32_16x16x32_bf16 v[4:7], v[164:167], v[212:215], v[4:7]
	v_mfma_f32_16x16x32_bf16 v[0:3], v[172:175], v[212:215], v[0:3]
	s_setprio 0
	s_add_i32 s73, s73, 2
	s_add_u32 s6, s6, 0x100
	s_addc_u32 s7, s7, 0
	s_add_u32 s71, s71, 0x100
	s_addc_u32 s72, s72, 0
	s_cmp_gt_u32 s73, 13
	s_cbranch_scc0 .LBB0_952

.LBB0_1145:
	s_ashr_i32 s23, s22, 31
	s_lshl_b64 s[26:27], s[22:23], 19
	s_add_u32 s26, s45, s26
	s_addc_u32 s27, s46, s27
	s_and_b64 s[28:29], s[4:5], exec
	s_cselect_b32 s23, s27, s39
	s_cselect_b32 s31, s26, s38
	s_ashr_i32 s25, s24, 31
	s_lshl_b64 s[28:29], s[24:25], 19
	s_add_u32 s28, s47, s28
	s_addc_u32 s29, s48, s29
	s_and_b64 s[42:43], s[4:5], exec
	s_cselect_b32 s25, s29, s41
	s_cselect_b32 s37, s28, s40
	s_add_u32 s38, s38, 0x40080
	s_addc_u32 s39, s39, 0
	s_add_u32 s64, s40, 0x100
	s_addc_u32 s65, s41, 0
	s_mov_b32 s66, -2
	ds_read_b128 v[120:123], v233
	ds_read_b128 v[132:135], v233 offset:1024
	ds_read_b128 v[136:139], v233 offset:2048
	ds_read_b128 v[140:143], v233 offset:3072
	ds_read_b128 v[144:147], v234
	ds_read_b128 v[148:151], v234 offset:1024
	ds_read_b128 v[152:155], v234 offset:2048
	ds_read_b128 v[156:159], v234 offset:3072
	s_add_u32 s40, s38, 0xfffc0080
	s_addc_u32 s41, s39, -1
	s_cmp_eq_u32 s66, 12
	s_cselect_b32 s43, s23, s41
	s_cselect_b32 s42, s31, s40
	s_cselect_b32 s41, s25, s65
	s_cselect_b32 s40, s37, s64
	v_lshl_add_u64 v[208:209], s[38:39], 0, v[192:193]
	s_add_i32 m0, s50, 0xc000
	ds_read_b128 v[160:163], v235
	ds_read_b128 v[164:167], v235 offset:1024
	ds_read_b128 v[168:171], v235 offset:2048
	ds_read_b128 v[172:175], v235 offset:3072
	ds_read_b128 v[176:179], v235 offset:4096
	ds_read_b128 v[180:183], v235 offset:5120
	ds_read_b128 v[200:203], v235 offset:6144
	ds_read_b128 v[204:207], v235 offset:7168
	global_load_lds_dwordx4 v[208:209], off
	s_add_i32 m0, s50, 0xe000
	v_lshl_add_u64 v[208:209], s[38:39], 0, v[194:195]
	global_load_lds_dwordx4 v[208:209], off
	s_waitcnt vmcnt(8)
	s_waitcnt lgkmcnt(0)
	s_barrier
	s_setprio 1
	s_waitcnt lgkmcnt(0)
	v_mfma_f32_16x16x32_bf16 v[128:131], v[120:123], v[160:163], 0
	v_mfma_f32_16x16x32_bf16 v[124:127], v[136:139], v[160:163], 0
	v_mfma_f32_16x16x32_bf16 v[108:111], v[120:123], v[168:171], 0
	v_mfma_f32_16x16x32_bf16 v[104:107], v[136:139], v[168:171], 0
	v_mfma_f32_16x16x32_bf16 v[92:95], v[120:123], v[176:179], 0
	v_mfma_f32_16x16x32_bf16 v[88:91], v[136:139], v[176:179], 0
	v_mfma_f32_16x16x32_bf16 v[76:79], v[120:123], v[200:203], 0
	v_mfma_f32_16x16x32_bf16 v[72:75], v[136:139], v[200:203], 0
	v_mfma_f32_16x16x32_bf16 v[128:131], v[132:135], v[164:167], v[128:131]
	v_mfma_f32_16x16x32_bf16 v[124:127], v[140:143], v[164:167], v[124:127]
	v_mfma_f32_16x16x32_bf16 v[108:111], v[132:135], v[172:175], v[108:111]
	v_mfma_f32_16x16x32_bf16 v[104:107], v[140:143], v[172:175], v[104:107]
	v_mfma_f32_16x16x32_bf16 v[92:95], v[132:135], v[180:183], v[92:95]
	v_mfma_f32_16x16x32_bf16 v[88:91], v[140:143], v[180:183], v[88:91]
	v_mfma_f32_16x16x32_bf16 v[76:79], v[132:135], v[204:207], v[76:79]
	v_mfma_f32_16x16x32_bf16 v[72:75], v[140:143], v[204:207], v[72:75]
	s_setprio 0
	s_setprio 1
	v_mfma_f32_16x16x32_bf16 v[116:119], v[144:147], v[160:163], 0
	v_mfma_f32_16x16x32_bf16 v[112:115], v[152:155], v[160:163], 0
	v_mfma_f32_16x16x32_bf16 v[100:103], v[144:147], v[168:171], 0
	v_mfma_f32_16x16x32_bf16 v[96:99], v[152:155], v[168:171], 0
	v_mfma_f32_16x16x32_bf16 v[84:87], v[144:147], v[176:179], 0
	v_mfma_f32_16x16x32_bf16 v[80:83], v[152:155], v[176:179], 0
	v_mfma_f32_16x16x32_bf16 v[68:71], v[144:147], v[200:203], 0
	v_mfma_f32_16x16x32_bf16 v[64:67], v[152:155], v[200:203], 0
	v_mfma_f32_16x16x32_bf16 v[116:119], v[148:151], v[164:167], v[116:119]
	v_mfma_f32_16x16x32_bf16 v[112:115], v[156:159], v[164:167], v[112:115]
	v_mfma_f32_16x16x32_bf16 v[100:103], v[148:151], v[172:175], v[100:103]
	v_mfma_f32_16x16x32_bf16 v[96:99], v[156:159], v[172:175], v[96:99]
	s_setprio 2
	s_barrier
	v_mfma_f32_16x16x32_bf16 v[84:87], v[148:151], v[180:183], v[84:87]
	v_mfma_f32_16x16x32_bf16 v[80:83], v[156:159], v[180:183], v[80:83]
	v_mfma_f32_16x16x32_bf16 v[68:71], v[148:151], v[204:207], v[68:71]
	v_mfma_f32_16x16x32_bf16 v[64:67], v[156:159], v[204:207], v[64:67]
	s_setprio 0
	s_add_i32 s67, s62, s49
	v_lshl_add_u64 v[208:209], s[40:41], 0, v[186:187]
	s_mov_b32 m0, s67
	ds_read_b128 v[160:163], v235 offset:16384
	ds_read_b128 v[164:167], v235 offset:17408
	ds_read_b128 v[168:171], v235 offset:18432
	ds_read_b128 v[172:175], v235 offset:19456
	ds_read_b128 v[176:179], v235 offset:20480
	ds_read_b128 v[180:183], v235 offset:21504
	global_load_lds_dwordx4 v[208:209], off
	s_add_i32 m0, s67, 0x2000
	s_add_u32 s68, s40, 0x40000
	v_lshl_add_u64 v[210:211], s[40:41], 0, v[190:191]
	s_addc_u32 s69, s41, 0
	s_add_i32 s67, s63, s49
	global_load_lds_dwordx4 v[210:211], off
	s_mov_b32 m0, s67
	v_lshl_add_u64 v[214:215], s[42:43], 0, v[188:189]
	global_load_lds_dwordx4 v186, s[68:69]
	s_add_i32 m0, s67, 0x2000
	ds_read_b128 v[200:203], v235 offset:22528
	global_load_lds_dwordx4 v190, s[68:69]
	s_mov_b32 m0, s50
	v_lshl_add_u64 v[212:213], s[42:43], 0, v[184:185]
	global_load_lds_dwordx4 v[212:213], off
	s_mov_b32 m0, s51
	ds_read_b128 v[204:207], v235 offset:23552
	global_load_lds_dwordx4 v[214:215], off
	s_waitcnt vmcnt(8)
	s_waitcnt lgkmcnt(0)
	s_barrier
	s_setprio 1
	s_waitcnt lgkmcnt(0)
	v_mfma_f32_16x16x32_bf16 v[60:63], v[120:123], v[160:163], 0
	v_mfma_f32_16x16x32_bf16 v[56:59], v[136:139], v[160:163], 0
	v_mfma_f32_16x16x32_bf16 v[44:47], v[120:123], v[168:171], 0
	v_mfma_f32_16x16x32_bf16 v[40:43], v[136:139], v[168:171], 0
	v_mfma_f32_16x16x32_bf16 v[28:31], v[120:123], v[176:179], 0
	v_mfma_f32_16x16x32_bf16 v[24:27], v[136:139], v[176:179], 0
	v_mfma_f32_16x16x32_bf16 v[12:15], v[120:123], v[200:203], 0
	v_mfma_f32_16x16x32_bf16 v[8:11], v[136:139], v[200:203], 0
	v_mfma_f32_16x16x32_bf16 v[60:63], v[132:135], v[164:167], v[60:63]
	v_mfma_f32_16x16x32_bf16 v[56:59], v[140:143], v[164:167], v[56:59]
	v_mfma_f32_16x16x32_bf16 v[44:47], v[132:135], v[172:175], v[44:47]
	v_mfma_f32_16x16x32_bf16 v[40:43], v[140:143], v[172:175], v[40:43]
	v_mfma_f32_16x16x32_bf16 v[28:31], v[132:135], v[180:183], v[28:31]
	v_mfma_f32_16x16x32_bf16 v[24:27], v[140:143], v[180:183], v[24:27]
	v_mfma_f32_16x16x32_bf16 v[12:15], v[132:135], v[204:207], v[12:15]
	v_mfma_f32_16x16x32_bf16 v[8:11], v[140:143], v[204:207], v[8:11]
	s_setprio 0
	s_setprio 1
	v_mfma_f32_16x16x32_bf16 v[52:55], v[144:147], v[160:163], 0
	v_mfma_f32_16x16x32_bf16 v[48:51], v[152:155], v[160:163], 0
	v_mfma_f32_16x16x32_bf16 v[36:39], v[144:147], v[168:171], 0
	v_mfma_f32_16x16x32_bf16 v[32:35], v[152:155], v[168:171], 0
	v_mfma_f32_16x16x32_bf16 v[20:23], v[144:147], v[176:179], 0
	v_mfma_f32_16x16x32_bf16 v[16:19], v[152:155], v[176:179], 0
	v_mfma_f32_16x16x32_bf16 v[4:7], v[144:147], v[200:203], 0
	v_mfma_f32_16x16x32_bf16 v[0:3], v[152:155], v[200:203], 0
	v_mfma_f32_16x16x32_bf16 v[52:55], v[148:151], v[164:167], v[52:55]
	v_mfma_f32_16x16x32_bf16 v[48:51], v[156:159], v[164:167], v[48:51]
	v_mfma_f32_16x16x32_bf16 v[36:39], v[148:151], v[172:175], v[36:39]
	v_mfma_f32_16x16x32_bf16 v[32:35], v[156:159], v[172:175], v[32:35]
	s_setprio 2
	s_barrier
	v_mfma_f32_16x16x32_bf16 v[20:23], v[148:151], v[180:183], v[20:23]
	v_mfma_f32_16x16x32_bf16 v[16:19], v[156:159], v[180:183], v[16:19]
	v_mfma_f32_16x16x32_bf16 v[4:7], v[148:151], v[204:207], v[4:7]
	v_mfma_f32_16x16x32_bf16 v[0:3], v[156:159], v[204:207], v[0:3]
	s_setprio 0
	s_add_i32 s67, 0, 0x18000
	s_add_i32 s68, 0, 0x1c000
	v_add_u32_e32 v140, s67, v232
	v_add_u32_e32 v156, s68, v232
	ds_read_b128 v[120:123], v140
	ds_read_b128 v[132:135], v140 offset:1024
	ds_read_b128 v[136:139], v140 offset:2048
	ds_read_b128 v[140:143], v140 offset:3072
	ds_read_b128 v[144:147], v156
	ds_read_b128 v[148:151], v156 offset:1024
	ds_read_b128 v[152:155], v156 offset:2048
	ds_read_b128 v[156:159], v156 offset:3072
	s_add_u32 s42, s42, 0x40000
	s_addc_u32 s43, s43, 0
	s_mov_b32 m0, s54
	v_lshl_add_u64 v[216:217], s[42:43], 0, v[184:185]
	ds_read_b128 v[160:163], v235 offset:32768
	ds_read_b128 v[164:167], v235 offset:33792
	ds_read_b128 v[168:171], v235 offset:34816
	ds_read_b128 v[172:175], v235 offset:35840
	ds_read_b128 v[176:179], v235 offset:36864
	ds_read_b128 v[180:183], v235 offset:37888
	ds_read_b128 v[200:203], v235 offset:38912
	ds_read_b128 v[204:207], v235 offset:39936
	global_load_lds_dwordx4 v[216:217], off
	s_mov_b32 m0, s55
	v_lshl_add_u64 v[216:217], s[42:43], 0, v[188:189]
	global_load_lds_dwordx4 v[216:217], off
	s_waitcnt vmcnt(8)
	s_waitcnt lgkmcnt(0)
	s_barrier
	s_setprio 1
	s_waitcnt lgkmcnt(0)
	v_mfma_f32_16x16x32_bf16 v[128:131], v[120:123], v[160:163], v[128:131]
	v_mfma_f32_16x16x32_bf16 v[124:127], v[136:139], v[160:163], v[124:127]
	v_mfma_f32_16x16x32_bf16 v[108:111], v[120:123], v[168:171], v[108:111]
	v_mfma_f32_16x16x32_bf16 v[104:107], v[136:139], v[168:171], v[104:107]
	v_mfma_f32_16x16x32_bf16 v[92:95], v[120:123], v[176:179], v[92:95]
	v_mfma_f32_16x16x32_bf16 v[88:91], v[136:139], v[176:179], v[88:91]
	v_mfma_f32_16x16x32_bf16 v[76:79], v[120:123], v[200:203], v[76:79]
	v_mfma_f32_16x16x32_bf16 v[72:75], v[136:139], v[200:203], v[72:75]
	v_mfma_f32_16x16x32_bf16 v[128:131], v[132:135], v[164:167], v[128:131]
	v_mfma_f32_16x16x32_bf16 v[124:127], v[140:143], v[164:167], v[124:127]
	v_mfma_f32_16x16x32_bf16 v[108:111], v[132:135], v[172:175], v[108:111]
	v_mfma_f32_16x16x32_bf16 v[104:107], v[140:143], v[172:175], v[104:107]
	v_mfma_f32_16x16x32_bf16 v[92:95], v[132:135], v[180:183], v[92:95]
	v_mfma_f32_16x16x32_bf16 v[88:91], v[140:143], v[180:183], v[88:91]
	v_mfma_f32_16x16x32_bf16 v[76:79], v[132:135], v[204:207], v[76:79]
	v_mfma_f32_16x16x32_bf16 v[72:75], v[140:143], v[204:207], v[72:75]
	s_setprio 0
	s_setprio 1
	v_mfma_f32_16x16x32_bf16 v[116:119], v[144:147], v[160:163], v[116:119]
	v_mfma_f32_16x16x32_bf16 v[112:115], v[152:155], v[160:163], v[112:115]
	v_mfma_f32_16x16x32_bf16 v[100:103], v[144:147], v[168:171], v[100:103]
	v_mfma_f32_16x16x32_bf16 v[96:99], v[152:155], v[168:171], v[96:99]
	v_mfma_f32_16x16x32_bf16 v[84:87], v[144:147], v[176:179], v[84:87]
	v_mfma_f32_16x16x32_bf16 v[80:83], v[152:155], v[176:179], v[80:83]
	v_mfma_f32_16x16x32_bf16 v[68:71], v[144:147], v[200:203], v[68:71]
	v_mfma_f32_16x16x32_bf16 v[64:67], v[152:155], v[200:203], v[64:67]
	v_mfma_f32_16x16x32_bf16 v[116:119], v[148:151], v[164:167], v[116:119]
	v_mfma_f32_16x16x32_bf16 v[112:115], v[156:159], v[164:167], v[112:115]
	v_mfma_f32_16x16x32_bf16 v[100:103], v[148:151], v[172:175], v[100:103]
	v_mfma_f32_16x16x32_bf16 v[96:99], v[156:159], v[172:175], v[96:99]
	s_setprio 2
	s_barrier
	v_mfma_f32_16x16x32_bf16 v[84:87], v[148:151], v[180:183], v[84:87]
	v_mfma_f32_16x16x32_bf16 v[80:83], v[156:159], v[180:183], v[80:83]
	v_mfma_f32_16x16x32_bf16 v[68:71], v[148:151], v[204:207], v[68:71]
	v_mfma_f32_16x16x32_bf16 v[64:67], v[156:159], v[204:207], v[64:67]
	s_setprio 0
	s_add_i32 s42, s67, s49
	s_add_i32 m0, s42, 0xffffff80
	ds_read_b128 v[160:163], v235 offset:49152
	ds_read_b128 v[164:167], v235 offset:50176
	ds_read_b128 v[168:171], v235 offset:51200
	ds_read_b128 v[172:175], v235 offset:52224
	global_load_lds_dwordx4 v[208:209], off offset:128
	s_add_i32 m0, s42, 0x1f80
	s_add_u32 s40, s40, 0x40080
	s_addc_u32 s41, s41, 0
	s_add_i32 s42, s68, s49
	global_load_lds_dwordx4 v[210:211], off offset:128
	s_mov_b32 m0, s42
	ds_read_b128 v[176:179], v235 offset:53248
	global_load_lds_dwordx4 v186, s[40:41]
	s_add_i32 m0, s42, 0x2000
	ds_read_b128 v[180:183], v235 offset:54272
	global_load_lds_dwordx4 v190, s[40:41]
	s_add_i32 m0, s57, 0xffffff80
	ds_read_b128 v[200:203], v235 offset:55296
	global_load_lds_dwordx4 v[212:213], off offset:128
	s_add_i32 m0, s58, 0xffffff80
	ds_read_b128 v[204:207], v235 offset:56320
	global_load_lds_dwordx4 v[214:215], off offset:128
	s_waitcnt vmcnt(8)
	s_waitcnt lgkmcnt(0)
	s_barrier
	s_setprio 1
	s_waitcnt lgkmcnt(0)
	v_mfma_f32_16x16x32_bf16 v[60:63], v[120:123], v[160:163], v[60:63]
	v_mfma_f32_16x16x32_bf16 v[56:59], v[136:139], v[160:163], v[56:59]
	v_mfma_f32_16x16x32_bf16 v[44:47], v[120:123], v[168:171], v[44:47]
	v_mfma_f32_16x16x32_bf16 v[40:43], v[136:139], v[168:171], v[40:43]
	v_mfma_f32_16x16x32_bf16 v[28:31], v[120:123], v[176:179], v[28:31]
	v_mfma_f32_16x16x32_bf16 v[24:27], v[136:139], v[176:179], v[24:27]
	v_mfma_f32_16x16x32_bf16 v[12:15], v[120:123], v[200:203], v[12:15]
	v_mfma_f32_16x16x32_bf16 v[8:11], v[136:139], v[200:203], v[8:11]
	v_mfma_f32_16x16x32_bf16 v[60:63], v[132:135], v[164:167], v[60:63]
	v_mfma_f32_16x16x32_bf16 v[56:59], v[140:143], v[164:167], v[56:59]
	v_mfma_f32_16x16x32_bf16 v[44:47], v[132:135], v[172:175], v[44:47]
	v_mfma_f32_16x16x32_bf16 v[40:43], v[140:143], v[172:175], v[40:43]
	v_mfma_f32_16x16x32_bf16 v[28:31], v[132:135], v[180:183], v[28:31]
	v_mfma_f32_16x16x32_bf16 v[24:27], v[140:143], v[180:183], v[24:27]
	v_mfma_f32_16x16x32_bf16 v[12:15], v[132:135], v[204:207], v[12:15]
	v_mfma_f32_16x16x32_bf16 v[8:11], v[140:143], v[204:207], v[8:11]
	s_setprio 0
	s_setprio 1
	v_mfma_f32_16x16x32_bf16 v[52:55], v[144:147], v[160:163], v[52:55]
	v_mfma_f32_16x16x32_bf16 v[48:51], v[152:155], v[160:163], v[48:51]
	v_mfma_f32_16x16x32_bf16 v[36:39], v[144:147], v[168:171], v[36:39]
	v_mfma_f32_16x16x32_bf16 v[32:35], v[152:155], v[168:171], v[32:35]
	v_mfma_f32_16x16x32_bf16 v[20:23], v[144:147], v[176:179], v[20:23]
	v_mfma_f32_16x16x32_bf16 v[16:19], v[152:155], v[176:179], v[16:19]
	v_mfma_f32_16x16x32_bf16 v[4:7], v[144:147], v[200:203], v[4:7]
	v_mfma_f32_16x16x32_bf16 v[0:3], v[152:155], v[200:203], v[0:3]
	v_mfma_f32_16x16x32_bf16 v[52:55], v[148:151], v[164:167], v[52:55]
	v_mfma_f32_16x16x32_bf16 v[48:51], v[156:159], v[164:167], v[48:51]
	v_mfma_f32_16x16x32_bf16 v[36:39], v[148:151], v[172:175], v[36:39]
	v_mfma_f32_16x16x32_bf16 v[32:35], v[156:159], v[172:175], v[32:35]
	s_setprio 2
	s_barrier
	v_mfma_f32_16x16x32_bf16 v[20:23], v[148:151], v[180:183], v[20:23]
	v_mfma_f32_16x16x32_bf16 v[16:19], v[156:159], v[180:183], v[16:19]
	v_mfma_f32_16x16x32_bf16 v[4:7], v[148:151], v[204:207], v[4:7]
	v_mfma_f32_16x16x32_bf16 v[0:3], v[156:159], v[204:207], v[0:3]
	s_setprio 0
	s_add_i32 s66, s66, 2
	s_add_u32 s38, s38, 0x100
	s_addc_u32 s39, s39, 0
	s_add_u32 s64, s64, 0x100
	s_addc_u32 s65, s65, 0
	s_cmp_gt_u32 s66, 13
.LBB0_1146:
	ds_read_b128 v[120:123], v233
	ds_read_b128 v[132:135], v233 offset:1024
	ds_read_b128 v[136:139], v233 offset:2048
	ds_read_b128 v[140:143], v233 offset:3072
	ds_read_b128 v[144:147], v234
	ds_read_b128 v[148:151], v234 offset:1024
	ds_read_b128 v[152:155], v234 offset:2048
	ds_read_b128 v[156:159], v234 offset:3072
	s_add_u32 s40, s38, 0xfffc0080
	s_addc_u32 s41, s39, -1
	s_cmp_eq_u32 s66, 12
	s_cselect_b32 s43, s23, s41
	s_cselect_b32 s42, s31, s40
	s_cselect_b32 s41, s25, s65
	s_cselect_b32 s40, s37, s64
	v_lshl_add_u64 v[208:209], s[38:39], 0, v[192:193]
	s_add_i32 m0, s50, 0xc000
	ds_read_b128 v[160:163], v235
	ds_read_b128 v[164:167], v235 offset:1024
	ds_read_b128 v[168:171], v235 offset:2048
	ds_read_b128 v[172:175], v235 offset:3072
	ds_read_b128 v[176:179], v235 offset:4096
	ds_read_b128 v[180:183], v235 offset:5120
	ds_read_b128 v[200:203], v235 offset:6144
	ds_read_b128 v[204:207], v235 offset:7168
	global_load_lds_dwordx4 v[208:209], off
	s_add_i32 m0, s50, 0xe000
	v_lshl_add_u64 v[208:209], s[38:39], 0, v[194:195]
	global_load_lds_dwordx4 v[208:209], off
	s_waitcnt vmcnt(8)
	s_waitcnt lgkmcnt(0)
	s_barrier
	s_setprio 1
	s_waitcnt lgkmcnt(0)
	v_mfma_f32_16x16x32_bf16 v[128:131], v[120:123], v[160:163], v[128:131]
	v_mfma_f32_16x16x32_bf16 v[124:127], v[136:139], v[160:163], v[124:127]
	v_mfma_f32_16x16x32_bf16 v[108:111], v[120:123], v[168:171], v[108:111]
	v_mfma_f32_16x16x32_bf16 v[104:107], v[136:139], v[168:171], v[104:107]
	v_mfma_f32_16x16x32_bf16 v[92:95], v[120:123], v[176:179], v[92:95]
	v_mfma_f32_16x16x32_bf16 v[88:91], v[136:139], v[176:179], v[88:91]
	v_mfma_f32_16x16x32_bf16 v[76:79], v[120:123], v[200:203], v[76:79]
	v_mfma_f32_16x16x32_bf16 v[72:75], v[136:139], v[200:203], v[72:75]
	v_mfma_f32_16x16x32_bf16 v[128:131], v[132:135], v[164:167], v[128:131]
	v_mfma_f32_16x16x32_bf16 v[124:127], v[140:143], v[164:167], v[124:127]
	v_mfma_f32_16x16x32_bf16 v[108:111], v[132:135], v[172:175], v[108:111]
	v_mfma_f32_16x16x32_bf16 v[104:107], v[140:143], v[172:175], v[104:107]
	v_mfma_f32_16x16x32_bf16 v[92:95], v[132:135], v[180:183], v[92:95]
	v_mfma_f32_16x16x32_bf16 v[88:91], v[140:143], v[180:183], v[88:91]
	v_mfma_f32_16x16x32_bf16 v[76:79], v[132:135], v[204:207], v[76:79]
	v_mfma_f32_16x16x32_bf16 v[72:75], v[140:143], v[204:207], v[72:75]
	s_setprio 0
	s_setprio 1
	v_mfma_f32_16x16x32_bf16 v[116:119], v[144:147], v[160:163], v[116:119]
	v_mfma_f32_16x16x32_bf16 v[112:115], v[152:155], v[160:163], v[112:115]
	v_mfma_f32_16x16x32_bf16 v[100:103], v[144:147], v[168:171], v[100:103]
	v_mfma_f32_16x16x32_bf16 v[96:99], v[152:155], v[168:171], v[96:99]
	v_mfma_f32_16x16x32_bf16 v[84:87], v[144:147], v[176:179], v[84:87]
	v_mfma_f32_16x16x32_bf16 v[80:83], v[152:155], v[176:179], v[80:83]
	v_mfma_f32_16x16x32_bf16 v[68:71], v[144:147], v[200:203], v[68:71]
	v_mfma_f32_16x16x32_bf16 v[64:67], v[152:155], v[200:203], v[64:67]
	v_mfma_f32_16x16x32_bf16 v[116:119], v[148:151], v[164:167], v[116:119]
	v_mfma_f32_16x16x32_bf16 v[112:115], v[156:159], v[164:167], v[112:115]
	v_mfma_f32_16x16x32_bf16 v[100:103], v[148:151], v[172:175], v[100:103]
	v_mfma_f32_16x16x32_bf16 v[96:99], v[156:159], v[172:175], v[96:99]
	s_setprio 2
	s_barrier
	v_mfma_f32_16x16x32_bf16 v[84:87], v[148:151], v[180:183], v[84:87]
	v_mfma_f32_16x16x32_bf16 v[80:83], v[156:159], v[180:183], v[80:83]
	v_mfma_f32_16x16x32_bf16 v[68:71], v[148:151], v[204:207], v[68:71]
	v_mfma_f32_16x16x32_bf16 v[64:67], v[156:159], v[204:207], v[64:67]
	s_setprio 0
	s_add_i32 s67, s62, s49
	v_lshl_add_u64 v[208:209], s[40:41], 0, v[186:187]
	s_mov_b32 m0, s67
	ds_read_b128 v[160:163], v235 offset:16384
	ds_read_b128 v[164:167], v235 offset:17408
	ds_read_b128 v[168:171], v235 offset:18432
	ds_read_b128 v[172:175], v235 offset:19456
	ds_read_b128 v[176:179], v235 offset:20480
	ds_read_b128 v[180:183], v235 offset:21504
	global_load_lds_dwordx4 v[208:209], off
	s_add_i32 m0, s67, 0x2000
	s_add_u32 s68, s40, 0x40000
	v_lshl_add_u64 v[210:211], s[40:41], 0, v[190:191]
	s_addc_u32 s69, s41, 0
	s_add_i32 s67, s63, s49
	global_load_lds_dwordx4 v[210:211], off
	s_mov_b32 m0, s67
	v_lshl_add_u64 v[214:215], s[42:43], 0, v[188:189]
	global_load_lds_dwordx4 v186, s[68:69]
	s_add_i32 m0, s67, 0x2000
	ds_read_b128 v[200:203], v235 offset:22528
	global_load_lds_dwordx4 v190, s[68:69]
	s_mov_b32 m0, s50
	v_lshl_add_u64 v[212:213], s[42:43], 0, v[184:185]
	global_load_lds_dwordx4 v[212:213], off
	s_mov_b32 m0, s51
	ds_read_b128 v[204:207], v235 offset:23552
	global_load_lds_dwordx4 v[214:215], off
	s_waitcnt vmcnt(8)
	s_waitcnt lgkmcnt(0)
	s_barrier
	s_setprio 1
	s_waitcnt lgkmcnt(0)
	v_mfma_f32_16x16x32_bf16 v[60:63], v[120:123], v[160:163], v[60:63]
	v_mfma_f32_16x16x32_bf16 v[56:59], v[136:139], v[160:163], v[56:59]
	v_mfma_f32_16x16x32_bf16 v[44:47], v[120:123], v[168:171], v[44:47]
	v_mfma_f32_16x16x32_bf16 v[40:43], v[136:139], v[168:171], v[40:43]
	v_mfma_f32_16x16x32_bf16 v[28:31], v[120:123], v[176:179], v[28:31]
	v_mfma_f32_16x16x32_bf16 v[24:27], v[136:139], v[176:179], v[24:27]
	v_mfma_f32_16x16x32_bf16 v[12:15], v[120:123], v[200:203], v[12:15]
	v_mfma_f32_16x16x32_bf16 v[8:11], v[136:139], v[200:203], v[8:11]
	v_mfma_f32_16x16x32_bf16 v[60:63], v[132:135], v[164:167], v[60:63]
	v_mfma_f32_16x16x32_bf16 v[56:59], v[140:143], v[164:167], v[56:59]
	v_mfma_f32_16x16x32_bf16 v[44:47], v[132:135], v[172:175], v[44:47]
	v_mfma_f32_16x16x32_bf16 v[40:43], v[140:143], v[172:175], v[40:43]
	v_mfma_f32_16x16x32_bf16 v[28:31], v[132:135], v[180:183], v[28:31]
	v_mfma_f32_16x16x32_bf16 v[24:27], v[140:143], v[180:183], v[24:27]
	v_mfma_f32_16x16x32_bf16 v[12:15], v[132:135], v[204:207], v[12:15]
	v_mfma_f32_16x16x32_bf16 v[8:11], v[140:143], v[204:207], v[8:11]
	s_setprio 0
	s_setprio 1
	v_mfma_f32_16x16x32_bf16 v[52:55], v[144:147], v[160:163], v[52:55]
	v_mfma_f32_16x16x32_bf16 v[48:51], v[152:155], v[160:163], v[48:51]
	v_mfma_f32_16x16x32_bf16 v[36:39], v[144:147], v[168:171], v[36:39]
	v_mfma_f32_16x16x32_bf16 v[32:35], v[152:155], v[168:171], v[32:35]
	v_mfma_f32_16x16x32_bf16 v[20:23], v[144:147], v[176:179], v[20:23]
	v_mfma_f32_16x16x32_bf16 v[16:19], v[152:155], v[176:179], v[16:19]
	v_mfma_f32_16x16x32_bf16 v[4:7], v[144:147], v[200:203], v[4:7]
	v_mfma_f32_16x16x32_bf16 v[0:3], v[152:155], v[200:203], v[0:3]
	v_mfma_f32_16x16x32_bf16 v[52:55], v[148:151], v[164:167], v[52:55]
	v_mfma_f32_16x16x32_bf16 v[48:51], v[156:159], v[164:167], v[48:51]
	v_mfma_f32_16x16x32_bf16 v[36:39], v[148:151], v[172:175], v[36:39]
	v_mfma_f32_16x16x32_bf16 v[32:35], v[156:159], v[172:175], v[32:35]
	s_setprio 2
	s_barrier
	v_mfma_f32_16x16x32_bf16 v[20:23], v[148:151], v[180:183], v[20:23]
	v_mfma_f32_16x16x32_bf16 v[16:19], v[156:159], v[180:183], v[16:19]
	v_mfma_f32_16x16x32_bf16 v[4:7], v[148:151], v[204:207], v[4:7]
	v_mfma_f32_16x16x32_bf16 v[0:3], v[156:159], v[204:207], v[0:3]
	s_setprio 0
	s_add_i32 s67, 0, 0x18000
	s_add_i32 s68, 0, 0x1c000
	v_add_u32_e32 v140, s67, v232
	v_add_u32_e32 v156, s68, v232
	ds_read_b128 v[120:123], v140
	ds_read_b128 v[132:135], v140 offset:1024
	ds_read_b128 v[136:139], v140 offset:2048
	ds_read_b128 v[140:143], v140 offset:3072
	ds_read_b128 v[144:147], v156
	ds_read_b128 v[148:151], v156 offset:1024
	ds_read_b128 v[152:155], v156 offset:2048
	ds_read_b128 v[156:159], v156 offset:3072
	s_add_u32 s42, s42, 0x40000
	s_addc_u32 s43, s43, 0
	s_mov_b32 m0, s54
	v_lshl_add_u64 v[216:217], s[42:43], 0, v[184:185]
	ds_read_b128 v[160:163], v235 offset:32768
	ds_read_b128 v[164:167], v235 offset:33792
	ds_read_b128 v[168:171], v235 offset:34816
	ds_read_b128 v[172:175], v235 offset:35840
	ds_read_b128 v[176:179], v235 offset:36864
	ds_read_b128 v[180:183], v235 offset:37888
	ds_read_b128 v[200:203], v235 offset:38912
	ds_read_b128 v[204:207], v235 offset:39936
	global_load_lds_dwordx4 v[216:217], off
	s_mov_b32 m0, s55
	v_lshl_add_u64 v[216:217], s[42:43], 0, v[188:189]
	global_load_lds_dwordx4 v[216:217], off
	s_waitcnt vmcnt(8)
	s_waitcnt lgkmcnt(0)
	s_barrier
	s_setprio 1
	s_waitcnt lgkmcnt(0)
	v_mfma_f32_16x16x32_bf16 v[128:131], v[120:123], v[160:163], v[128:131]
	v_mfma_f32_16x16x32_bf16 v[124:127], v[136:139], v[160:163], v[124:127]
	v_mfma_f32_16x16x32_bf16 v[108:111], v[120:123], v[168:171], v[108:111]
	v_mfma_f32_16x16x32_bf16 v[104:107], v[136:139], v[168:171], v[104:107]
	v_mfma_f32_16x16x32_bf16 v[92:95], v[120:123], v[176:179], v[92:95]
	v_mfma_f32_16x16x32_bf16 v[88:91], v[136:139], v[176:179], v[88:91]
	v_mfma_f32_16x16x32_bf16 v[76:79], v[120:123], v[200:203], v[76:79]
	v_mfma_f32_16x16x32_bf16 v[72:75], v[136:139], v[200:203], v[72:75]
	v_mfma_f32_16x16x32_bf16 v[128:131], v[132:135], v[164:167], v[128:131]
	v_mfma_f32_16x16x32_bf16 v[124:127], v[140:143], v[164:167], v[124:127]
	v_mfma_f32_16x16x32_bf16 v[108:111], v[132:135], v[172:175], v[108:111]
	v_mfma_f32_16x16x32_bf16 v[104:107], v[140:143], v[172:175], v[104:107]
	v_mfma_f32_16x16x32_bf16 v[92:95], v[132:135], v[180:183], v[92:95]
	v_mfma_f32_16x16x32_bf16 v[88:91], v[140:143], v[180:183], v[88:91]
	v_mfma_f32_16x16x32_bf16 v[76:79], v[132:135], v[204:207], v[76:79]
	v_mfma_f32_16x16x32_bf16 v[72:75], v[140:143], v[204:207], v[72:75]
	s_setprio 0
	s_setprio 1
	v_mfma_f32_16x16x32_bf16 v[116:119], v[144:147], v[160:163], v[116:119]
	v_mfma_f32_16x16x32_bf16 v[112:115], v[152:155], v[160:163], v[112:115]
	v_mfma_f32_16x16x32_bf16 v[100:103], v[144:147], v[168:171], v[100:103]
	v_mfma_f32_16x16x32_bf16 v[96:99], v[152:155], v[168:171], v[96:99]
	v_mfma_f32_16x16x32_bf16 v[84:87], v[144:147], v[176:179], v[84:87]
	v_mfma_f32_16x16x32_bf16 v[80:83], v[152:155], v[176:179], v[80:83]
	v_mfma_f32_16x16x32_bf16 v[68:71], v[144:147], v[200:203], v[68:71]
	v_mfma_f32_16x16x32_bf16 v[64:67], v[152:155], v[200:203], v[64:67]
	v_mfma_f32_16x16x32_bf16 v[116:119], v[148:151], v[164:167], v[116:119]
	v_mfma_f32_16x16x32_bf16 v[112:115], v[156:159], v[164:167], v[112:115]
	v_mfma_f32_16x16x32_bf16 v[100:103], v[148:151], v[172:175], v[100:103]
	v_mfma_f32_16x16x32_bf16 v[96:99], v[156:159], v[172:175], v[96:99]
	s_setprio 2
	s_barrier
	v_mfma_f32_16x16x32_bf16 v[84:87], v[148:151], v[180:183], v[84:87]
	v_mfma_f32_16x16x32_bf16 v[80:83], v[156:159], v[180:183], v[80:83]
	v_mfma_f32_16x16x32_bf16 v[68:71], v[148:151], v[204:207], v[68:71]
	v_mfma_f32_16x16x32_bf16 v[64:67], v[156:159], v[204:207], v[64:67]
	s_setprio 0
	s_add_i32 s42, s67, s49
	s_add_i32 m0, s42, 0xffffff80
	ds_read_b128 v[160:163], v235 offset:49152
	ds_read_b128 v[164:167], v235 offset:50176
	ds_read_b128 v[168:171], v235 offset:51200
	ds_read_b128 v[172:175], v235 offset:52224
	ds_read_b128 v[176:179], v235 offset:53248
	global_load_lds_dwordx4 v[208:209], off offset:128
	s_add_i32 m0, s42, 0x1f80
	s_add_u32 s40, s40, 0x40080
	s_addc_u32 s41, s41, 0
	s_add_i32 s42, s68, s49
	global_load_lds_dwordx4 v[210:211], off offset:128
	s_mov_b32 m0, s42
	ds_read_b128 v[180:183], v235 offset:54272
	global_load_lds_dwordx4 v186, s[40:41]
	s_add_i32 m0, s42, 0x2000
	ds_read_b128 v[200:203], v235 offset:55296
	global_load_lds_dwordx4 v190, s[40:41]
	s_add_i32 m0, s57, 0xffffff80
	ds_read_b128 v[204:207], v235 offset:56320
	global_load_lds_dwordx4 v[212:213], off offset:128
	s_mov_b32 m0, s58
	v_lshl_add_u64 v[208:209], v[214:215], 0, s[18:19]
	global_load_lds_dwordx4 v[208:209], off
	s_waitcnt vmcnt(8)
	s_waitcnt lgkmcnt(0)
	s_barrier
	s_setprio 1
	s_waitcnt lgkmcnt(0)
	v_mfma_f32_16x16x32_bf16 v[60:63], v[120:123], v[160:163], v[60:63]
	v_mfma_f32_16x16x32_bf16 v[56:59], v[136:139], v[160:163], v[56:59]
	v_mfma_f32_16x16x32_bf16 v[44:47], v[120:123], v[168:171], v[44:47]
	v_mfma_f32_16x16x32_bf16 v[40:43], v[136:139], v[168:171], v[40:43]
	v_mfma_f32_16x16x32_bf16 v[28:31], v[120:123], v[176:179], v[28:31]
	v_mfma_f32_16x16x32_bf16 v[24:27], v[136:139], v[176:179], v[24:27]
	v_mfma_f32_16x16x32_bf16 v[12:15], v[120:123], v[200:203], v[12:15]
	v_mfma_f32_16x16x32_bf16 v[8:11], v[136:139], v[200:203], v[8:11]
	v_mfma_f32_16x16x32_bf16 v[60:63], v[132:135], v[164:167], v[60:63]
	v_mfma_f32_16x16x32_bf16 v[56:59], v[140:143], v[164:167], v[56:59]
	v_mfma_f32_16x16x32_bf16 v[44:47], v[132:135], v[172:175], v[44:47]
	v_mfma_f32_16x16x32_bf16 v[40:43], v[140:143], v[172:175], v[40:43]
	v_mfma_f32_16x16x32_bf16 v[28:31], v[132:135], v[180:183], v[28:31]
	v_mfma_f32_16x16x32_bf16 v[24:27], v[140:143], v[180:183], v[24:27]
	v_mfma_f32_16x16x32_bf16 v[12:15], v[132:135], v[204:207], v[12:15]
	v_mfma_f32_16x16x32_bf16 v[8:11], v[140:143], v[204:207], v[8:11]
	s_setprio 0
	s_setprio 1
	v_mfma_f32_16x16x32_bf16 v[52:55], v[144:147], v[160:163], v[52:55]
	v_mfma_f32_16x16x32_bf16 v[48:51], v[152:155], v[160:163], v[48:51]
	v_mfma_f32_16x16x32_bf16 v[36:39], v[144:147], v[168:171], v[36:39]
	v_mfma_f32_16x16x32_bf16 v[32:35], v[152:155], v[168:171], v[32:35]
	v_mfma_f32_16x16x32_bf16 v[20:23], v[144:147], v[176:179], v[20:23]
	v_mfma_f32_16x16x32_bf16 v[16:19], v[152:155], v[176:179], v[16:19]
	v_mfma_f32_16x16x32_bf16 v[4:7], v[144:147], v[200:203], v[4:7]
	v_mfma_f32_16x16x32_bf16 v[0:3], v[152:155], v[200:203], v[0:3]
	v_mfma_f32_16x16x32_bf16 v[52:55], v[148:151], v[164:167], v[52:55]
	v_mfma_f32_16x16x32_bf16 v[48:51], v[156:159], v[164:167], v[48:51]
	v_mfma_f32_16x16x32_bf16 v[36:39], v[148:151], v[172:175], v[36:39]
	v_mfma_f32_16x16x32_bf16 v[32:35], v[156:159], v[172:175], v[32:35]
	s_setprio 2
	s_barrier
	v_mfma_f32_16x16x32_bf16 v[20:23], v[148:151], v[180:183], v[20:23]
	v_mfma_f32_16x16x32_bf16 v[16:19], v[156:159], v[180:183], v[16:19]
	v_mfma_f32_16x16x32_bf16 v[4:7], v[148:151], v[204:207], v[4:7]
	v_mfma_f32_16x16x32_bf16 v[0:3], v[156:159], v[204:207], v[0:3]
	s_setprio 0
	s_add_i32 s66, s66, 2
	s_add_u32 s38, s38, 0x100
	s_addc_u32 s39, s39, 0
	s_add_u32 s64, s64, 0x100
	s_addc_u32 s65, s65, 0
	s_cmp_gt_u32 s66, 13
	s_cbranch_scc0 .LBB0_1146

.LBB0_1309:
	s_add_u32 s51, s26, 0x100
	s_addc_u32 s52, s27, 0
	s_mov_b32 s53, -2
	ds_read_b128 v[128:131], v197
	ds_read_b128 v[132:135], v197 offset:1024
	ds_read_b128 v[136:139], v197 offset:2048
	ds_read_b128 v[140:143], v197 offset:3072
	ds_read_b128 v[144:147], v198
	ds_read_b128 v[148:151], v198 offset:1024
	ds_read_b128 v[152:155], v198 offset:2048
	ds_read_b128 v[156:159], v198 offset:3072
	s_add_u32 s4, s24, 0x100
	s_addc_u32 s5, s25, 0
	s_cmp_eq_u32 s53, 40
	s_cselect_b32 s29, s21, s5
	s_cselect_b32 s28, s20, s4
	s_cselect_b32 s27, s23, s52
	s_cselect_b32 s26, s22, s51
	v_lshl_add_u64 v[212:213], s[24:25], 0, v[172:173]
	s_add_i32 m0, s36, 0xc000
	ds_read_b128 v[160:163], v199
	ds_read_b128 v[180:183], v199 offset:1024
	ds_read_b128 v[184:187], v199 offset:2048
	ds_read_b128 v[188:191], v199 offset:3072
	ds_read_b128 v[192:195], v199 offset:4096
	ds_read_b128 v[200:203], v199 offset:5120
	ds_read_b128 v[204:207], v199 offset:6144
	ds_read_b128 v[208:211], v199 offset:7168
	global_load_lds_dwordx4 v[212:213], off
	s_add_i32 m0, s36, 0xe000
	v_lshl_add_u64 v[212:213], s[24:25], 0, v[174:175]
	global_load_lds_dwordx4 v[212:213], off
	s_waitcnt vmcnt(8)
	s_waitcnt lgkmcnt(0)
	s_barrier
	s_setprio 1
	s_waitcnt lgkmcnt(0)
	v_mfma_f32_16x16x32_bf16 v[124:127], v[128:131], v[160:163], 0
	v_mfma_f32_16x16x32_bf16 v[120:123], v[136:139], v[160:163], 0
	v_mfma_f32_16x16x32_bf16 v[116:119], v[128:131], v[184:187], 0
	v_mfma_f32_16x16x32_bf16 v[108:111], v[136:139], v[184:187], 0
	v_mfma_f32_16x16x32_bf16 v[88:91], v[128:131], v[192:195], 0
	v_mfma_f32_16x16x32_bf16 v[100:103], v[136:139], v[192:195], 0
	v_mfma_f32_16x16x32_bf16 v[72:75], v[128:131], v[204:207], 0
	v_mfma_f32_16x16x32_bf16 v[76:79], v[136:139], v[204:207], 0
	v_mfma_f32_16x16x32_bf16 v[124:127], v[132:135], v[180:183], v[124:127]
	v_mfma_f32_16x16x32_bf16 v[120:123], v[140:143], v[180:183], v[120:123]
	v_mfma_f32_16x16x32_bf16 v[116:119], v[132:135], v[188:191], v[116:119]
	v_mfma_f32_16x16x32_bf16 v[108:111], v[140:143], v[188:191], v[108:111]
	v_mfma_f32_16x16x32_bf16 v[88:91], v[132:135], v[200:203], v[88:91]
	v_mfma_f32_16x16x32_bf16 v[100:103], v[140:143], v[200:203], v[100:103]
	v_mfma_f32_16x16x32_bf16 v[72:75], v[132:135], v[208:211], v[72:75]
	v_mfma_f32_16x16x32_bf16 v[76:79], v[140:143], v[208:211], v[76:79]
	s_setprio 0
	s_setprio 1
	v_mfma_f32_16x16x32_bf16 v[112:115], v[144:147], v[160:163], 0
	v_mfma_f32_16x16x32_bf16 v[104:107], v[152:155], v[160:163], 0
	v_mfma_f32_16x16x32_bf16 v[96:99], v[144:147], v[184:187], 0
	v_mfma_f32_16x16x32_bf16 v[92:95], v[152:155], v[184:187], 0
	v_mfma_f32_16x16x32_bf16 v[80:83], v[144:147], v[192:195], 0
	v_mfma_f32_16x16x32_bf16 v[84:87], v[152:155], v[192:195], 0
	v_mfma_f32_16x16x32_bf16 v[64:67], v[144:147], v[204:207], 0
	v_mfma_f32_16x16x32_bf16 v[68:71], v[152:155], v[204:207], 0
	v_mfma_f32_16x16x32_bf16 v[112:115], v[148:151], v[180:183], v[112:115]
	v_mfma_f32_16x16x32_bf16 v[104:107], v[156:159], v[180:183], v[104:107]
	v_mfma_f32_16x16x32_bf16 v[96:99], v[148:151], v[188:191], v[96:99]
	v_mfma_f32_16x16x32_bf16 v[92:95], v[156:159], v[188:191], v[92:95]
	s_setprio 2
	s_barrier
	v_mfma_f32_16x16x32_bf16 v[80:83], v[148:151], v[200:203], v[80:83]
	v_mfma_f32_16x16x32_bf16 v[84:87], v[156:159], v[200:203], v[84:87]
	v_mfma_f32_16x16x32_bf16 v[64:67], v[148:151], v[208:211], v[64:67]
	v_mfma_f32_16x16x32_bf16 v[68:71], v[156:159], v[208:211], v[68:71]
	s_setprio 0
	s_add_i32 s24, s45, s35
	v_lshl_add_u64 v[212:213], s[26:27], 0, v[166:167]
	s_mov_b32 m0, s24
	ds_read_b128 v[160:163], v199 offset:16384
	ds_read_b128 v[180:183], v199 offset:17408
	ds_read_b128 v[184:187], v199 offset:18432
	ds_read_b128 v[188:191], v199 offset:19456
	ds_read_b128 v[192:195], v199 offset:20480
	ds_read_b128 v[200:203], v199 offset:21504
	global_load_lds_dwordx4 v[212:213], off
	s_add_i32 m0, s24, 0x2000
	s_add_u32 s24, s26, 0xb0000
	v_lshl_add_u64 v[214:215], s[26:27], 0, v[170:171]
	s_addc_u32 s25, s27, 0
	s_add_i32 s54, s46, s35
	global_load_lds_dwordx4 v[214:215], off
	s_mov_b32 m0, s54
	v_lshl_add_u64 v[218:219], s[28:29], 0, v[168:169]
	global_load_lds_dwordx4 v166, s[24:25]
	s_add_i32 m0, s54, 0x2000
	ds_read_b128 v[204:207], v199 offset:22528
	global_load_lds_dwordx4 v170, s[24:25]
	s_mov_b32 m0, s36
	v_lshl_add_u64 v[216:217], s[28:29], 0, v[164:165]
	global_load_lds_dwordx4 v[216:217], off
	s_mov_b32 m0, s37
	ds_read_b128 v[208:211], v199 offset:23552
	global_load_lds_dwordx4 v[218:219], off
	s_waitcnt vmcnt(8)
	s_waitcnt lgkmcnt(0)
	s_barrier
	s_setprio 1
	s_waitcnt lgkmcnt(0)
	v_mfma_f32_16x16x32_bf16 v[56:59], v[128:131], v[160:163], 0
	v_mfma_f32_16x16x32_bf16 v[60:63], v[136:139], v[160:163], 0
	v_mfma_f32_16x16x32_bf16 v[40:43], v[128:131], v[184:187], 0
	v_mfma_f32_16x16x32_bf16 v[44:47], v[136:139], v[184:187], 0
	v_mfma_f32_16x16x32_bf16 v[24:27], v[128:131], v[192:195], 0
	v_mfma_f32_16x16x32_bf16 v[28:31], v[136:139], v[192:195], 0
	v_mfma_f32_16x16x32_bf16 v[8:11], v[128:131], v[204:207], 0
	v_mfma_f32_16x16x32_bf16 v[12:15], v[136:139], v[204:207], 0
	v_mfma_f32_16x16x32_bf16 v[56:59], v[132:135], v[180:183], v[56:59]
	v_mfma_f32_16x16x32_bf16 v[60:63], v[140:143], v[180:183], v[60:63]
	v_mfma_f32_16x16x32_bf16 v[40:43], v[132:135], v[188:191], v[40:43]
	v_mfma_f32_16x16x32_bf16 v[44:47], v[140:143], v[188:191], v[44:47]
	v_mfma_f32_16x16x32_bf16 v[24:27], v[132:135], v[200:203], v[24:27]
	v_mfma_f32_16x16x32_bf16 v[28:31], v[140:143], v[200:203], v[28:31]
	v_mfma_f32_16x16x32_bf16 v[8:11], v[132:135], v[208:211], v[8:11]
	v_mfma_f32_16x16x32_bf16 v[12:15], v[140:143], v[208:211], v[12:15]
	s_setprio 0
	s_setprio 1
	v_mfma_f32_16x16x32_bf16 v[48:51], v[144:147], v[160:163], 0
	v_mfma_f32_16x16x32_bf16 v[52:55], v[152:155], v[160:163], 0
	v_mfma_f32_16x16x32_bf16 v[32:35], v[144:147], v[184:187], 0
	v_mfma_f32_16x16x32_bf16 v[36:39], v[152:155], v[184:187], 0
	v_mfma_f32_16x16x32_bf16 v[16:19], v[144:147], v[192:195], 0
	v_mfma_f32_16x16x32_bf16 v[20:23], v[152:155], v[192:195], 0
	v_mfma_f32_16x16x32_bf16 v[0:3], v[144:147], v[204:207], 0
	v_mfma_f32_16x16x32_bf16 v[4:7], v[152:155], v[204:207], 0
	v_mfma_f32_16x16x32_bf16 v[48:51], v[148:151], v[180:183], v[48:51]
	v_mfma_f32_16x16x32_bf16 v[52:55], v[156:159], v[180:183], v[52:55]
	v_mfma_f32_16x16x32_bf16 v[32:35], v[148:151], v[188:191], v[32:35]
	v_mfma_f32_16x16x32_bf16 v[36:39], v[156:159], v[188:191], v[36:39]
	s_setprio 2
	s_barrier
	v_mfma_f32_16x16x32_bf16 v[16:19], v[148:151], v[200:203], v[16:19]
	v_mfma_f32_16x16x32_bf16 v[20:23], v[156:159], v[200:203], v[20:23]
	v_mfma_f32_16x16x32_bf16 v[0:3], v[148:151], v[208:211], v[0:3]
	v_mfma_f32_16x16x32_bf16 v[4:7], v[156:159], v[208:211], v[4:7]
	s_setprio 0
	s_add_i32 s54, 0, 0x18000
	s_add_i32 s55, 0, 0x1c000
	v_add_u32_e32 v140, s54, v196
	v_add_u32_e32 v156, s55, v196
	ds_read_b128 v[128:131], v140
	ds_read_b128 v[132:135], v140 offset:1024
	ds_read_b128 v[136:139], v140 offset:2048
	ds_read_b128 v[140:143], v140 offset:3072
	ds_read_b128 v[144:147], v156
	ds_read_b128 v[148:151], v156 offset:1024
	ds_read_b128 v[152:155], v156 offset:2048
	ds_read_b128 v[156:159], v156 offset:3072
	s_add_u32 s24, s28, 0xb0000
	s_addc_u32 s25, s29, 0
	s_mov_b32 m0, s38
	v_lshl_add_u64 v[220:221], s[24:25], 0, v[164:165]
	ds_read_b128 v[160:163], v199 offset:32768
	ds_read_b128 v[180:183], v199 offset:33792
	ds_read_b128 v[184:187], v199 offset:34816
	ds_read_b128 v[188:191], v199 offset:35840
	ds_read_b128 v[192:195], v199 offset:36864
	ds_read_b128 v[200:203], v199 offset:37888
	ds_read_b128 v[204:207], v199 offset:38912
	ds_read_b128 v[208:211], v199 offset:39936
	global_load_lds_dwordx4 v[220:221], off
	s_mov_b32 m0, s39
	v_lshl_add_u64 v[220:221], s[24:25], 0, v[168:169]
	global_load_lds_dwordx4 v[220:221], off
	s_waitcnt vmcnt(8)
	s_waitcnt lgkmcnt(0)
	s_barrier
	s_setprio 1
	s_waitcnt lgkmcnt(0)
	v_mfma_f32_16x16x32_bf16 v[124:127], v[128:131], v[160:163], v[124:127]
	v_mfma_f32_16x16x32_bf16 v[120:123], v[136:139], v[160:163], v[120:123]
	v_mfma_f32_16x16x32_bf16 v[116:119], v[128:131], v[184:187], v[116:119]
	v_mfma_f32_16x16x32_bf16 v[108:111], v[136:139], v[184:187], v[108:111]
	v_mfma_f32_16x16x32_bf16 v[88:91], v[128:131], v[192:195], v[88:91]
	v_mfma_f32_16x16x32_bf16 v[100:103], v[136:139], v[192:195], v[100:103]
	v_mfma_f32_16x16x32_bf16 v[72:75], v[128:131], v[204:207], v[72:75]
	v_mfma_f32_16x16x32_bf16 v[76:79], v[136:139], v[204:207], v[76:79]
	v_mfma_f32_16x16x32_bf16 v[124:127], v[132:135], v[180:183], v[124:127]
	v_mfma_f32_16x16x32_bf16 v[120:123], v[140:143], v[180:183], v[120:123]
	v_mfma_f32_16x16x32_bf16 v[116:119], v[132:135], v[188:191], v[116:119]
	v_mfma_f32_16x16x32_bf16 v[108:111], v[140:143], v[188:191], v[108:111]
	v_mfma_f32_16x16x32_bf16 v[88:91], v[132:135], v[200:203], v[88:91]
	v_mfma_f32_16x16x32_bf16 v[100:103], v[140:143], v[200:203], v[100:103]
	v_mfma_f32_16x16x32_bf16 v[72:75], v[132:135], v[208:211], v[72:75]
	v_mfma_f32_16x16x32_bf16 v[76:79], v[140:143], v[208:211], v[76:79]
	s_setprio 0
	s_setprio 1
	v_mfma_f32_16x16x32_bf16 v[112:115], v[144:147], v[160:163], v[112:115]
	v_mfma_f32_16x16x32_bf16 v[104:107], v[152:155], v[160:163], v[104:107]
	v_mfma_f32_16x16x32_bf16 v[96:99], v[144:147], v[184:187], v[96:99]
	v_mfma_f32_16x16x32_bf16 v[92:95], v[152:155], v[184:187], v[92:95]
	v_mfma_f32_16x16x32_bf16 v[80:83], v[144:147], v[192:195], v[80:83]
	v_mfma_f32_16x16x32_bf16 v[84:87], v[152:155], v[192:195], v[84:87]
	v_mfma_f32_16x16x32_bf16 v[64:67], v[144:147], v[204:207], v[64:67]
	v_mfma_f32_16x16x32_bf16 v[68:71], v[152:155], v[204:207], v[68:71]
	v_mfma_f32_16x16x32_bf16 v[112:115], v[148:151], v[180:183], v[112:115]
	v_mfma_f32_16x16x32_bf16 v[104:107], v[156:159], v[180:183], v[104:107]
	v_mfma_f32_16x16x32_bf16 v[96:99], v[148:151], v[188:191], v[96:99]
	v_mfma_f32_16x16x32_bf16 v[92:95], v[156:159], v[188:191], v[92:95]
	s_setprio 2
	s_barrier
	v_mfma_f32_16x16x32_bf16 v[80:83], v[148:151], v[200:203], v[80:83]
	v_mfma_f32_16x16x32_bf16 v[84:87], v[156:159], v[200:203], v[84:87]
	v_mfma_f32_16x16x32_bf16 v[64:67], v[148:151], v[208:211], v[64:67]
	v_mfma_f32_16x16x32_bf16 v[68:71], v[156:159], v[208:211], v[68:71]
	s_setprio 0
	s_add_i32 s24, s54, s35
	s_add_i32 m0, s24, 0xffffff80
	ds_read_b128 v[160:163], v199 offset:49152
	ds_read_b128 v[180:183], v199 offset:50176
	ds_read_b128 v[184:187], v199 offset:51200
	ds_read_b128 v[188:191], v199 offset:52224
	global_load_lds_dwordx4 v[212:213], off offset:128
	s_add_i32 m0, s24, 0x1f80
	s_add_u32 s24, s26, 0xb0080
	s_addc_u32 s25, s27, 0
	s_add_i32 s26, s55, s35
	global_load_lds_dwordx4 v[214:215], off offset:128
	s_mov_b32 m0, s26
	ds_read_b128 v[192:195], v199 offset:53248
	global_load_lds_dwordx4 v166, s[24:25]
	s_add_i32 m0, s26, 0x2000
	ds_read_b128 v[200:203], v199 offset:54272
	global_load_lds_dwordx4 v170, s[24:25]
	s_add_i32 m0, s41, 0xffffff80
	ds_read_b128 v[204:207], v199 offset:55296
	global_load_lds_dwordx4 v[216:217], off offset:128
	s_add_i32 m0, s42, 0xffffff80
	ds_read_b128 v[208:211], v199 offset:56320
	global_load_lds_dwordx4 v[218:219], off offset:128
	s_waitcnt vmcnt(8)
	s_waitcnt lgkmcnt(0)
	s_barrier
	s_setprio 1
	s_waitcnt lgkmcnt(0)
	v_mfma_f32_16x16x32_bf16 v[56:59], v[128:131], v[160:163], v[56:59]
	v_mfma_f32_16x16x32_bf16 v[60:63], v[136:139], v[160:163], v[60:63]
	v_mfma_f32_16x16x32_bf16 v[40:43], v[128:131], v[184:187], v[40:43]
	v_mfma_f32_16x16x32_bf16 v[44:47], v[136:139], v[184:187], v[44:47]
	v_mfma_f32_16x16x32_bf16 v[24:27], v[128:131], v[192:195], v[24:27]
	v_mfma_f32_16x16x32_bf16 v[28:31], v[136:139], v[192:195], v[28:31]
	v_mfma_f32_16x16x32_bf16 v[8:11], v[128:131], v[204:207], v[8:11]
	v_mfma_f32_16x16x32_bf16 v[12:15], v[136:139], v[204:207], v[12:15]
	v_mfma_f32_16x16x32_bf16 v[56:59], v[132:135], v[180:183], v[56:59]
	v_mfma_f32_16x16x32_bf16 v[60:63], v[140:143], v[180:183], v[60:63]
	v_mfma_f32_16x16x32_bf16 v[40:43], v[132:135], v[188:191], v[40:43]
	v_mfma_f32_16x16x32_bf16 v[44:47], v[140:143], v[188:191], v[44:47]
	v_mfma_f32_16x16x32_bf16 v[24:27], v[132:135], v[200:203], v[24:27]
	v_mfma_f32_16x16x32_bf16 v[28:31], v[140:143], v[200:203], v[28:31]
	v_mfma_f32_16x16x32_bf16 v[8:11], v[132:135], v[208:211], v[8:11]
	v_mfma_f32_16x16x32_bf16 v[12:15], v[140:143], v[208:211], v[12:15]
	s_setprio 0
	s_setprio 1
	v_mfma_f32_16x16x32_bf16 v[48:51], v[144:147], v[160:163], v[48:51]
	v_mfma_f32_16x16x32_bf16 v[52:55], v[152:155], v[160:163], v[52:55]
	v_mfma_f32_16x16x32_bf16 v[32:35], v[144:147], v[184:187], v[32:35]
	v_mfma_f32_16x16x32_bf16 v[36:39], v[152:155], v[184:187], v[36:39]
	v_mfma_f32_16x16x32_bf16 v[16:19], v[144:147], v[192:195], v[16:19]
	v_mfma_f32_16x16x32_bf16 v[20:23], v[152:155], v[192:195], v[20:23]
	v_mfma_f32_16x16x32_bf16 v[0:3], v[144:147], v[204:207], v[0:3]
	v_mfma_f32_16x16x32_bf16 v[4:7], v[152:155], v[204:207], v[4:7]
	v_mfma_f32_16x16x32_bf16 v[48:51], v[148:151], v[180:183], v[48:51]
	v_mfma_f32_16x16x32_bf16 v[52:55], v[156:159], v[180:183], v[52:55]
	v_mfma_f32_16x16x32_bf16 v[32:35], v[148:151], v[188:191], v[32:35]
	v_mfma_f32_16x16x32_bf16 v[36:39], v[156:159], v[188:191], v[36:39]
	s_setprio 2
	s_barrier
	v_mfma_f32_16x16x32_bf16 v[16:19], v[148:151], v[200:203], v[16:19]
	v_mfma_f32_16x16x32_bf16 v[20:23], v[156:159], v[200:203], v[20:23]
	v_mfma_f32_16x16x32_bf16 v[0:3], v[148:151], v[208:211], v[0:3]
	v_mfma_f32_16x16x32_bf16 v[4:7], v[156:159], v[208:211], v[4:7]
	s_setprio 0
	s_add_i32 s53, s53, 2
	s_add_u32 s51, s51, 0x100
	s_addc_u32 s52, s52, 0
	s_cmp_gt_u32 s53, 41
	s_mov_b64 s[24:25], s[4:5]
.LBB0_1310:
	ds_read_b128 v[128:131], v197
	ds_read_b128 v[132:135], v197 offset:1024
	ds_read_b128 v[136:139], v197 offset:2048
	ds_read_b128 v[140:143], v197 offset:3072
	ds_read_b128 v[144:147], v198
	ds_read_b128 v[148:151], v198 offset:1024
	ds_read_b128 v[152:155], v198 offset:2048
	ds_read_b128 v[156:159], v198 offset:3072
	s_add_u32 s4, s24, 0x100
	s_addc_u32 s5, s25, 0
	s_cmp_eq_u32 s53, 40
	s_cselect_b32 s29, s21, s5
	s_cselect_b32 s28, s20, s4
	s_cselect_b32 s27, s23, s52
	s_cselect_b32 s26, s22, s51
	v_lshl_add_u64 v[212:213], s[24:25], 0, v[172:173]
	s_add_i32 m0, s36, 0xc000
	ds_read_b128 v[160:163], v199
	ds_read_b128 v[180:183], v199 offset:1024
	ds_read_b128 v[184:187], v199 offset:2048
	ds_read_b128 v[188:191], v199 offset:3072
	ds_read_b128 v[192:195], v199 offset:4096
	ds_read_b128 v[200:203], v199 offset:5120
	ds_read_b128 v[204:207], v199 offset:6144
	ds_read_b128 v[208:211], v199 offset:7168
	global_load_lds_dwordx4 v[212:213], off
	s_add_i32 m0, s36, 0xe000
	v_lshl_add_u64 v[212:213], s[24:25], 0, v[174:175]
	global_load_lds_dwordx4 v[212:213], off
	s_waitcnt vmcnt(8)
	s_waitcnt lgkmcnt(0)
	s_barrier
	s_setprio 1
	s_waitcnt lgkmcnt(0)
	v_mfma_f32_16x16x32_bf16 v[124:127], v[128:131], v[160:163], v[124:127]
	v_mfma_f32_16x16x32_bf16 v[120:123], v[136:139], v[160:163], v[120:123]
	v_mfma_f32_16x16x32_bf16 v[116:119], v[128:131], v[184:187], v[116:119]
	v_mfma_f32_16x16x32_bf16 v[108:111], v[136:139], v[184:187], v[108:111]
	v_mfma_f32_16x16x32_bf16 v[88:91], v[128:131], v[192:195], v[88:91]
	v_mfma_f32_16x16x32_bf16 v[100:103], v[136:139], v[192:195], v[100:103]
	v_mfma_f32_16x16x32_bf16 v[72:75], v[128:131], v[204:207], v[72:75]
	v_mfma_f32_16x16x32_bf16 v[76:79], v[136:139], v[204:207], v[76:79]
	v_mfma_f32_16x16x32_bf16 v[124:127], v[132:135], v[180:183], v[124:127]
	v_mfma_f32_16x16x32_bf16 v[120:123], v[140:143], v[180:183], v[120:123]
	v_mfma_f32_16x16x32_bf16 v[116:119], v[132:135], v[188:191], v[116:119]
	v_mfma_f32_16x16x32_bf16 v[108:111], v[140:143], v[188:191], v[108:111]
	v_mfma_f32_16x16x32_bf16 v[88:91], v[132:135], v[200:203], v[88:91]
	v_mfma_f32_16x16x32_bf16 v[100:103], v[140:143], v[200:203], v[100:103]
	v_mfma_f32_16x16x32_bf16 v[72:75], v[132:135], v[208:211], v[72:75]
	v_mfma_f32_16x16x32_bf16 v[76:79], v[140:143], v[208:211], v[76:79]
	s_setprio 0
	s_setprio 1
	v_mfma_f32_16x16x32_bf16 v[112:115], v[144:147], v[160:163], v[112:115]
	v_mfma_f32_16x16x32_bf16 v[104:107], v[152:155], v[160:163], v[104:107]
	v_mfma_f32_16x16x32_bf16 v[96:99], v[144:147], v[184:187], v[96:99]
	v_mfma_f32_16x16x32_bf16 v[92:95], v[152:155], v[184:187], v[92:95]
	v_mfma_f32_16x16x32_bf16 v[80:83], v[144:147], v[192:195], v[80:83]
	v_mfma_f32_16x16x32_bf16 v[84:87], v[152:155], v[192:195], v[84:87]
	v_mfma_f32_16x16x32_bf16 v[64:67], v[144:147], v[204:207], v[64:67]
	v_mfma_f32_16x16x32_bf16 v[68:71], v[152:155], v[204:207], v[68:71]
	v_mfma_f32_16x16x32_bf16 v[112:115], v[148:151], v[180:183], v[112:115]
	v_mfma_f32_16x16x32_bf16 v[104:107], v[156:159], v[180:183], v[104:107]
	v_mfma_f32_16x16x32_bf16 v[96:99], v[148:151], v[188:191], v[96:99]
	v_mfma_f32_16x16x32_bf16 v[92:95], v[156:159], v[188:191], v[92:95]
	s_setprio 2
	s_barrier
	v_mfma_f32_16x16x32_bf16 v[80:83], v[148:151], v[200:203], v[80:83]
	v_mfma_f32_16x16x32_bf16 v[84:87], v[156:159], v[200:203], v[84:87]
	v_mfma_f32_16x16x32_bf16 v[64:67], v[148:151], v[208:211], v[64:67]
	v_mfma_f32_16x16x32_bf16 v[68:71], v[156:159], v[208:211], v[68:71]
	s_setprio 0
	s_add_i32 s24, s45, s35
	v_lshl_add_u64 v[212:213], s[26:27], 0, v[166:167]
	s_mov_b32 m0, s24
	ds_read_b128 v[160:163], v199 offset:16384
	ds_read_b128 v[180:183], v199 offset:17408
	ds_read_b128 v[184:187], v199 offset:18432
	ds_read_b128 v[188:191], v199 offset:19456
	ds_read_b128 v[192:195], v199 offset:20480
	ds_read_b128 v[200:203], v199 offset:21504
	global_load_lds_dwordx4 v[212:213], off
	s_add_i32 m0, s24, 0x2000
	s_add_u32 s24, s26, 0xb0000
	v_lshl_add_u64 v[214:215], s[26:27], 0, v[170:171]
	s_addc_u32 s25, s27, 0
	s_add_i32 s54, s46, s35
	global_load_lds_dwordx4 v[214:215], off
	s_mov_b32 m0, s54
	v_lshl_add_u64 v[218:219], s[28:29], 0, v[168:169]
	global_load_lds_dwordx4 v166, s[24:25]
	s_add_i32 m0, s54, 0x2000
	ds_read_b128 v[204:207], v199 offset:22528
	global_load_lds_dwordx4 v170, s[24:25]
	s_mov_b32 m0, s36
	v_lshl_add_u64 v[216:217], s[28:29], 0, v[164:165]
	global_load_lds_dwordx4 v[216:217], off
	s_mov_b32 m0, s37
	ds_read_b128 v[208:211], v199 offset:23552
	global_load_lds_dwordx4 v[218:219], off
	s_waitcnt vmcnt(8)
	s_waitcnt lgkmcnt(0)
	s_barrier
	s_setprio 1
	s_waitcnt lgkmcnt(0)
	v_mfma_f32_16x16x32_bf16 v[56:59], v[128:131], v[160:163], v[56:59]
	v_mfma_f32_16x16x32_bf16 v[60:63], v[136:139], v[160:163], v[60:63]
	v_mfma_f32_16x16x32_bf16 v[40:43], v[128:131], v[184:187], v[40:43]
	v_mfma_f32_16x16x32_bf16 v[44:47], v[136:139], v[184:187], v[44:47]
	v_mfma_f32_16x16x32_bf16 v[24:27], v[128:131], v[192:195], v[24:27]
	v_mfma_f32_16x16x32_bf16 v[28:31], v[136:139], v[192:195], v[28:31]
	v_mfma_f32_16x16x32_bf16 v[8:11], v[128:131], v[204:207], v[8:11]
	v_mfma_f32_16x16x32_bf16 v[12:15], v[136:139], v[204:207], v[12:15]
	v_mfma_f32_16x16x32_bf16 v[56:59], v[132:135], v[180:183], v[56:59]
	v_mfma_f32_16x16x32_bf16 v[60:63], v[140:143], v[180:183], v[60:63]
	v_mfma_f32_16x16x32_bf16 v[40:43], v[132:135], v[188:191], v[40:43]
	v_mfma_f32_16x16x32_bf16 v[44:47], v[140:143], v[188:191], v[44:47]
	v_mfma_f32_16x16x32_bf16 v[24:27], v[132:135], v[200:203], v[24:27]
	v_mfma_f32_16x16x32_bf16 v[28:31], v[140:143], v[200:203], v[28:31]
	v_mfma_f32_16x16x32_bf16 v[8:11], v[132:135], v[208:211], v[8:11]
	v_mfma_f32_16x16x32_bf16 v[12:15], v[140:143], v[208:211], v[12:15]
	s_setprio 0
	s_setprio 1
	v_mfma_f32_16x16x32_bf16 v[48:51], v[144:147], v[160:163], v[48:51]
	v_mfma_f32_16x16x32_bf16 v[52:55], v[152:155], v[160:163], v[52:55]
	v_mfma_f32_16x16x32_bf16 v[32:35], v[144:147], v[184:187], v[32:35]
	v_mfma_f32_16x16x32_bf16 v[36:39], v[152:155], v[184:187], v[36:39]
	v_mfma_f32_16x16x32_bf16 v[16:19], v[144:147], v[192:195], v[16:19]
	v_mfma_f32_16x16x32_bf16 v[20:23], v[152:155], v[192:195], v[20:23]
	v_mfma_f32_16x16x32_bf16 v[0:3], v[144:147], v[204:207], v[0:3]
	v_mfma_f32_16x16x32_bf16 v[4:7], v[152:155], v[204:207], v[4:7]
	v_mfma_f32_16x16x32_bf16 v[48:51], v[148:151], v[180:183], v[48:51]
	v_mfma_f32_16x16x32_bf16 v[52:55], v[156:159], v[180:183], v[52:55]
	v_mfma_f32_16x16x32_bf16 v[32:35], v[148:151], v[188:191], v[32:35]
	v_mfma_f32_16x16x32_bf16 v[36:39], v[156:159], v[188:191], v[36:39]
	s_setprio 2
	s_barrier
	v_mfma_f32_16x16x32_bf16 v[16:19], v[148:151], v[200:203], v[16:19]
	v_mfma_f32_16x16x32_bf16 v[20:23], v[156:159], v[200:203], v[20:23]
	v_mfma_f32_16x16x32_bf16 v[0:3], v[148:151], v[208:211], v[0:3]
	v_mfma_f32_16x16x32_bf16 v[4:7], v[156:159], v[208:211], v[4:7]
	s_setprio 0
	s_add_i32 s54, 0, 0x18000
	s_add_i32 s55, 0, 0x1c000
	v_add_u32_e32 v140, s54, v196
	v_add_u32_e32 v156, s55, v196
	ds_read_b128 v[128:131], v140
	ds_read_b128 v[132:135], v140 offset:1024
	ds_read_b128 v[136:139], v140 offset:2048
	ds_read_b128 v[140:143], v140 offset:3072
	ds_read_b128 v[144:147], v156
	ds_read_b128 v[148:151], v156 offset:1024
	ds_read_b128 v[152:155], v156 offset:2048
	ds_read_b128 v[156:159], v156 offset:3072
	s_add_u32 s24, s28, 0xb0000
	s_addc_u32 s25, s29, 0
	s_mov_b32 m0, s38
	v_lshl_add_u64 v[220:221], s[24:25], 0, v[164:165]
	ds_read_b128 v[160:163], v199 offset:32768
	ds_read_b128 v[180:183], v199 offset:33792
	ds_read_b128 v[184:187], v199 offset:34816
	ds_read_b128 v[188:191], v199 offset:35840
	ds_read_b128 v[192:195], v199 offset:36864
	ds_read_b128 v[200:203], v199 offset:37888
	ds_read_b128 v[204:207], v199 offset:38912
	ds_read_b128 v[208:211], v199 offset:39936
	global_load_lds_dwordx4 v[220:221], off
	s_mov_b32 m0, s39
	v_lshl_add_u64 v[220:221], s[24:25], 0, v[168:169]
	global_load_lds_dwordx4 v[220:221], off
	s_waitcnt vmcnt(8)
	s_waitcnt lgkmcnt(0)
	s_barrier
	s_setprio 1
	s_waitcnt lgkmcnt(0)
	v_mfma_f32_16x16x32_bf16 v[124:127], v[128:131], v[160:163], v[124:127]
	v_mfma_f32_16x16x32_bf16 v[120:123], v[136:139], v[160:163], v[120:123]
	v_mfma_f32_16x16x32_bf16 v[116:119], v[128:131], v[184:187], v[116:119]
	v_mfma_f32_16x16x32_bf16 v[108:111], v[136:139], v[184:187], v[108:111]
	v_mfma_f32_16x16x32_bf16 v[88:91], v[128:131], v[192:195], v[88:91]
	v_mfma_f32_16x16x32_bf16 v[100:103], v[136:139], v[192:195], v[100:103]
	v_mfma_f32_16x16x32_bf16 v[72:75], v[128:131], v[204:207], v[72:75]
	v_mfma_f32_16x16x32_bf16 v[76:79], v[136:139], v[204:207], v[76:79]
	v_mfma_f32_16x16x32_bf16 v[124:127], v[132:135], v[180:183], v[124:127]
	v_mfma_f32_16x16x32_bf16 v[120:123], v[140:143], v[180:183], v[120:123]
	v_mfma_f32_16x16x32_bf16 v[116:119], v[132:135], v[188:191], v[116:119]
	v_mfma_f32_16x16x32_bf16 v[108:111], v[140:143], v[188:191], v[108:111]
	v_mfma_f32_16x16x32_bf16 v[88:91], v[132:135], v[200:203], v[88:91]
	v_mfma_f32_16x16x32_bf16 v[100:103], v[140:143], v[200:203], v[100:103]
	v_mfma_f32_16x16x32_bf16 v[72:75], v[132:135], v[208:211], v[72:75]
	v_mfma_f32_16x16x32_bf16 v[76:79], v[140:143], v[208:211], v[76:79]
	s_setprio 0
	s_setprio 1
	v_mfma_f32_16x16x32_bf16 v[112:115], v[144:147], v[160:163], v[112:115]
	v_mfma_f32_16x16x32_bf16 v[104:107], v[152:155], v[160:163], v[104:107]
	v_mfma_f32_16x16x32_bf16 v[96:99], v[144:147], v[184:187], v[96:99]
	v_mfma_f32_16x16x32_bf16 v[92:95], v[152:155], v[184:187], v[92:95]
	v_mfma_f32_16x16x32_bf16 v[80:83], v[144:147], v[192:195], v[80:83]
	v_mfma_f32_16x16x32_bf16 v[84:87], v[152:155], v[192:195], v[84:87]
	v_mfma_f32_16x16x32_bf16 v[64:67], v[144:147], v[204:207], v[64:67]
	v_mfma_f32_16x16x32_bf16 v[68:71], v[152:155], v[204:207], v[68:71]
	v_mfma_f32_16x16x32_bf16 v[112:115], v[148:151], v[180:183], v[112:115]
	v_mfma_f32_16x16x32_bf16 v[104:107], v[156:159], v[180:183], v[104:107]
	v_mfma_f32_16x16x32_bf16 v[96:99], v[148:151], v[188:191], v[96:99]
	v_mfma_f32_16x16x32_bf16 v[92:95], v[156:159], v[188:191], v[92:95]
	s_setprio 2
	s_barrier
	v_mfma_f32_16x16x32_bf16 v[80:83], v[148:151], v[200:203], v[80:83]
	v_mfma_f32_16x16x32_bf16 v[84:87], v[156:159], v[200:203], v[84:87]
	v_mfma_f32_16x16x32_bf16 v[64:67], v[148:151], v[208:211], v[64:67]
	v_mfma_f32_16x16x32_bf16 v[68:71], v[156:159], v[208:211], v[68:71]
	s_setprio 0
	s_add_i32 s24, s54, s35
	s_add_i32 m0, s24, 0xffffff80
	ds_read_b128 v[160:163], v199 offset:49152
	ds_read_b128 v[180:183], v199 offset:50176
	ds_read_b128 v[184:187], v199 offset:51200
	ds_read_b128 v[188:191], v199 offset:52224
	ds_read_b128 v[192:195], v199 offset:53248
	global_load_lds_dwordx4 v[212:213], off offset:128
	s_add_i32 m0, s24, 0x1f80
	s_add_u32 s24, s26, 0xb0080
	s_addc_u32 s25, s27, 0
	s_add_i32 s26, s55, s35
	global_load_lds_dwordx4 v[214:215], off offset:128
	s_mov_b32 m0, s26
	ds_read_b128 v[200:203], v199 offset:54272
	global_load_lds_dwordx4 v166, s[24:25]
	s_add_i32 m0, s26, 0x2000
	ds_read_b128 v[204:207], v199 offset:55296
	global_load_lds_dwordx4 v170, s[24:25]
	s_add_i32 m0, s41, 0xffffff80
	ds_read_b128 v[208:211], v199 offset:56320
	global_load_lds_dwordx4 v[216:217], off offset:128
	s_mov_b32 m0, s42
	v_lshl_add_u64 v[212:213], v[218:219], 0, s[16:17]
	global_load_lds_dwordx4 v[212:213], off
	s_waitcnt vmcnt(8)
	s_waitcnt lgkmcnt(0)
	s_barrier
	s_setprio 1
	s_waitcnt lgkmcnt(0)
	v_mfma_f32_16x16x32_bf16 v[56:59], v[128:131], v[160:163], v[56:59]
	v_mfma_f32_16x16x32_bf16 v[60:63], v[136:139], v[160:163], v[60:63]
	v_mfma_f32_16x16x32_bf16 v[40:43], v[128:131], v[184:187], v[40:43]
	v_mfma_f32_16x16x32_bf16 v[44:47], v[136:139], v[184:187], v[44:47]
	v_mfma_f32_16x16x32_bf16 v[24:27], v[128:131], v[192:195], v[24:27]
	v_mfma_f32_16x16x32_bf16 v[28:31], v[136:139], v[192:195], v[28:31]
	v_mfma_f32_16x16x32_bf16 v[8:11], v[128:131], v[204:207], v[8:11]
	v_mfma_f32_16x16x32_bf16 v[12:15], v[136:139], v[204:207], v[12:15]
	v_mfma_f32_16x16x32_bf16 v[56:59], v[132:135], v[180:183], v[56:59]
	v_mfma_f32_16x16x32_bf16 v[60:63], v[140:143], v[180:183], v[60:63]
	v_mfma_f32_16x16x32_bf16 v[40:43], v[132:135], v[188:191], v[40:43]
	v_mfma_f32_16x16x32_bf16 v[44:47], v[140:143], v[188:191], v[44:47]
	v_mfma_f32_16x16x32_bf16 v[24:27], v[132:135], v[200:203], v[24:27]
	v_mfma_f32_16x16x32_bf16 v[28:31], v[140:143], v[200:203], v[28:31]
	v_mfma_f32_16x16x32_bf16 v[8:11], v[132:135], v[208:211], v[8:11]
	v_mfma_f32_16x16x32_bf16 v[12:15], v[140:143], v[208:211], v[12:15]
	s_setprio 0
	s_setprio 1
	v_mfma_f32_16x16x32_bf16 v[48:51], v[144:147], v[160:163], v[48:51]
	v_mfma_f32_16x16x32_bf16 v[52:55], v[152:155], v[160:163], v[52:55]
	v_mfma_f32_16x16x32_bf16 v[32:35], v[144:147], v[184:187], v[32:35]
	v_mfma_f32_16x16x32_bf16 v[36:39], v[152:155], v[184:187], v[36:39]
	v_mfma_f32_16x16x32_bf16 v[16:19], v[144:147], v[192:195], v[16:19]
	v_mfma_f32_16x16x32_bf16 v[20:23], v[152:155], v[192:195], v[20:23]
	v_mfma_f32_16x16x32_bf16 v[0:3], v[144:147], v[204:207], v[0:3]
	v_mfma_f32_16x16x32_bf16 v[4:7], v[152:155], v[204:207], v[4:7]
	v_mfma_f32_16x16x32_bf16 v[48:51], v[148:151], v[180:183], v[48:51]
	v_mfma_f32_16x16x32_bf16 v[52:55], v[156:159], v[180:183], v[52:55]
	v_mfma_f32_16x16x32_bf16 v[32:35], v[148:151], v[188:191], v[32:35]
	v_mfma_f32_16x16x32_bf16 v[36:39], v[156:159], v[188:191], v[36:39]
	s_setprio 2
	s_barrier
	v_mfma_f32_16x16x32_bf16 v[16:19], v[148:151], v[200:203], v[16:19]
	v_mfma_f32_16x16x32_bf16 v[20:23], v[156:159], v[200:203], v[20:23]
	v_mfma_f32_16x16x32_bf16 v[0:3], v[148:151], v[208:211], v[0:3]
	v_mfma_f32_16x16x32_bf16 v[4:7], v[156:159], v[208:211], v[4:7]
	s_setprio 0
	s_add_i32 s53, s53, 2
	s_add_u32 s51, s51, 0x100
	s_addc_u32 s52, s52, 0
	s_cmp_gt_u32 s53, 41
	s_mov_b64 s[24:25], s[4:5]
	s_cbranch_scc0 .LBB0_1310
